# GEMM loops: static s_setprio raise for the wr==1 wave half instead of per-MFMA-block toggling
# speedup vs baseline: 1.0214x; 1.0059x over previous
.LBB0_171:
	s_or_b64 exec, exec, s[0:1]
	s_add_u32 s0, s30, 0xea00000
	s_addc_u32 s1, s31, 0
	s_add_u32 s3, s30, 0xce00000
	v_writelane_b32 v239, s3, 9
	s_addc_u32 s3, s31, 0
	v_writelane_b32 v239, s3, 10
	v_mov_b32_e32 v9, v176
	v_readlane_b32 s4, v239, 2
	s_ashr_i32 s3, s4, 31
	v_readlane_b32 s5, v239, 3
	v_writelane_b32 v239, s3, 11
	s_ashr_i32 s3, s2, 31
	s_waitcnt lgkmcnt(0)
	s_barrier
	s_cmpk_gt_i32 s2, 0x3ef
	s_nop 0
	v_readfirstlane_b32 s36, v9
	s_cbranch_scc1 .LBB0_183
	v_lshlrev_b32_e32 v0, 4, v9
	v_add_u32_e32 v1, 0x2000, v0
	v_ashrrev_i32_e32 v2, 31, v1
	v_lshrrev_b32_e32 v2, 22, v2
	v_add_u32_e32 v2, v1, v2
	v_ashrrev_i32_e32 v8, 10, v2
	v_mul_i32_i24_e32 v2, 0x400, v8
	v_sub_u32_e32 v1, v1, v2
	v_lshrrev_b32_e32 v2, 4, v1
	v_bitop3_b32 v1, v2, v1, 32 bitop3:0x6c
	v_ashrrev_i32_e32 v2, 31, v1
	v_lshrrev_b32_e32 v2, 26, v2
	v_add_u32_e32 v2, v1, v2
	v_lshlrev_b32_e32 v3, 3, v8
	v_ashrrev_i32_e32 v10, 6, v2
	v_and_b32_e32 v3, -16, v3
	v_add_u32_e32 v3, v10, v3
	v_and_b32_e32 v4, 3, v10
	s_mov_b32 s4, 0xfffe0
	v_lshrrev_b32_e32 v5, 2, v3
	v_lshlrev_b32_e32 v6, 1, v3
	v_and_b32_e32 v2, 0xc0, v2
	v_and_or_b32 v4, v3, s4, v4
	v_and_b32_e32 v5, 4, v5
	v_and_b32_e32 v6, 24, v6
	v_sub_u32_e32 v1, v1, v2
	v_mov_b32_e32 v2, 1
	v_or3_b32 v4, v4, v5, v6
	v_lshlrev_b32_e32 v5, 5, v8
	v_ashrrev_i16_sdwa v1, v2, sext(v1) dst_sel:DWORD dst_unused:UNUSED_PAD src0_sel:DWORD src1_sel:BYTE_0
	v_and_b32_e32 v5, 32, v5
	v_bfe_i32 v11, v1, 0, 16
	v_add_lshl_u32 v1, v5, v11, 1
	v_lshl_add_u32 v130, v4, 12, v1
	v_lshl_add_u32 v132, v3, 12, v1
	v_bfe_i32 v1, v9, 27, 1
	v_lshrrev_b32_e32 v1, 22, v1
	v_add_u32_e32 v1, v0, v1
	v_and_b32_e32 v1, 0xfffffc00, v1
	v_sub_u32_e32 v0, v0, v1
	v_lshrrev_b32_e32 v1, 4, v0
	v_bitop3_b32 v1, v1, v0, 32 bitop3:0x6c
	v_ashrrev_i32_e32 v0, 31, v0
	v_lshrrev_b32_e32 v0, 26, v0
	v_add_u32_e32 v0, v1, v0
	v_ashrrev_i32_e32 v12, 6, v0
	v_ashrrev_i32_e32 v0, 31, v9
	v_lshrrev_b32_e32 v0, 26, v0
	v_add_u32_e32 v0, v9, v0
	v_ashrrev_i32_e32 v13, 6, v0
	v_lshlrev_b32_e32 v0, 3, v13
	v_and_b32_e32 v0, -16, v0
	v_add_u32_e32 v0, v12, v0
	v_and_b32_e32 v3, 3, v12
	v_and_or_b32 v3, v0, s4, v3
	s_lshr_b32 s4, s3, 29
	s_add_i32 s4, s2, s4
	s_ashr_i32 s6, s36, 6
	s_ashr_i32 s7, s4, 3
	s_and_b32 s4, s4, -8
	s_ashr_i32 s5, s36, 8
	s_lshl_b32 s37, s6, 10
	s_sub_i32 s4, s2, s4
	s_cmp_lt_i32 s4, 0
	s_movk_i32 s38, 0x7f
	s_cselect_b32 s12, s38, 0x7e
	s_mul_i32 s4, s4, s12
	s_add_i32 s4, s4, s7
	v_lshrrev_b32_e32 v4, 2, v0
	v_lshlrev_b32_e32 v5, 1, v0
	s_mul_hi_i32 s7, s4, 0x92492493
	v_and_b32_e32 v4, 4, v4
	v_and_b32_e32 v5, 24, v5
	s_add_i32 s7, s7, s4
	v_or3_b32 v3, v3, v4, v5
	v_mul_i32_i24_e32 v5, 64, v12
	s_lshr_b32 s12, s7, 31
	s_ashr_i32 s7, s7, 7
	v_sub_u32_e32 v1, v1, v5
	s_add_i32 s7, s7, s12
	v_lshlrev_b32_e32 v4, 5, v13
	v_ashrrev_i16_sdwa v1, v2, sext(v1) dst_sel:DWORD dst_unused:UNUSED_PAD src0_sel:DWORD src1_sel:BYTE_0
	s_lshl_b32 s14, s7, 3
	v_and_b32_e32 v4, 32, v4
	v_bfe_i32 v14, v1, 0, 16
	s_sub_i32 s12, 36, s14
	s_mulk_i32 s7, 0xe0
	v_add_lshl_u32 v1, v4, v14, 1
	s_min_u32 s15, s12, 8
	s_sub_i32 s7, s4, s7
	v_lshl_add_u32 v134, v3, 12, v1
	s_sext_i32_i16 s4, s7
	v_cvt_f32_ubyte0_e32 v3, s15
	v_cvt_f32_i32_e32 v2, s4
	v_rcp_iflag_f32_e32 v4, v3
	v_lshl_add_u32 v136, v0, 12, v1
	s_ashr_i32 s4, s4, 30
	s_or_b32 s4, s4, 1
	v_mul_f32_e32 v0, v2, v4
	v_trunc_f32_e32 v0, v0
	v_fma_f32 v1, -v0, v3, v2
	v_cvt_i32_f32_e32 v0, v0
	v_cmp_ge_f32_e64 s[12:13], |v1|, v3
	s_and_b64 s[12:13], s[12:13], exec
	s_cselect_b32 s4, s4, 0
	v_readfirstlane_b32 s12, v0
	s_add_i32 s4, s12, s4
	s_mul_i32 s12, s4, s15
	s_sub_i32 s7, s7, s12
	s_sext_i32_i16 s7, s7
	s_add_i32 s20, s14, s7
	s_ashr_i32 s21, s20, 31
	s_bfe_i64 s[14:15], s[4:5], 0x100000
	s_lshl_b64 s[12:13], s[20:21], 20
	s_lshl_b64 s[14:15], s[14:15], 20
	v_readlane_b32 s7, v239, 9
	s_add_u32 s24, s7, s14
	v_readlane_b32 s7, v239, 10
	s_addc_u32 s25, s7, s15
	s_add_i32 s21, s37, 0
	s_add_i32 m0, s21, 0x10000
	v_mov_b32_e32 v135, 0
	global_load_lds_dwordx4 v134, s[24:25]
	s_add_i32 m0, s21, 0x12000
	s_add_u32 s22, s0, s12
	global_load_lds_dwordx4 v130, s[24:25]
	s_addc_u32 s23, s1, s13
	s_mov_b32 m0, s21
	s_add_i32 s39, s21, 0x2000
	global_load_lds_dwordx4 v136, s[22:23]
	s_mov_b32 m0, s39
	s_add_u32 s12, s24, 0x80000
	global_load_lds_dwordx4 v132, s[22:23]
	s_addc_u32 s13, s25, 0
	s_add_i32 m0, s21, 0x14000
	v_mov_b32_e32 v131, v135
	global_load_lds_dwordx4 v134, s[12:13]
	s_add_i32 m0, s21, 0x16000
	v_mov_b32_e32 v137, v135
	global_load_lds_dwordx4 v130, s[12:13]
	s_add_u32 s12, s22, 0x80000
	s_addc_u32 s13, s23, 0
	s_add_i32 s40, s21, 0x4000
	s_mov_b32 m0, s40
	s_add_i32 s41, s21, 0x6000
	global_load_lds_dwordx4 v136, s[12:13]
	s_mov_b32 m0, s41
	v_mov_b32_e32 v133, v135
	global_load_lds_dwordx4 v132, s[12:13]
	s_mov_b32 s97, s43
	s_mov_b32 s42, 0
	v_lshl_add_u64 v[6:7], s[24:25], 0, v[134:135]
	v_lshl_add_u64 v[4:5], s[24:25], 0, v[130:131]
	v_lshl_add_u64 v[2:3], s[22:23], 0, v[136:137]
	s_cmp_lg_u32 s5, 1
	v_lshl_add_u64 v[0:1], s[22:23], 0, v[132:133]
	s_cbranch_scc1 .LBB0_174
	s_setprio 1
	s_barrier

.LBB0_178:
	ds_read_b128 v[146:149], v157
	ds_read_b128 v[150:153], v157 offset:1024
	ds_read_b128 v[160:163], v157 offset:2048
	ds_read_b128 v[164:167], v157 offset:3072
	s_add_u32 s24, s22, 0xfff80080
	s_addc_u32 s25, s23, -1
	s_cmp_eq_u32 s83, 28
	s_cselect_b32 s27, s15, s25
	s_cselect_b32 s26, s51, s24
	s_cselect_b32 s25, s13, s82
	s_cselect_b32 s24, s80, s81
	v_lshl_add_u64 v[202:203], s[22:23], 0, v[138:139]
	s_add_i32 m0, s21, 0xc000
	ds_read_b128 v[168:171], v158
	ds_read_b128 v[172:175], v158 offset:1024
	ds_read_b128 v[178:181], v158 offset:2048
	ds_read_b128 v[182:185], v158 offset:3072
	ds_read_b128 v[186:189], v158 offset:4096
	ds_read_b128 v[190:193], v158 offset:5120
	ds_read_b128 v[194:197], v158 offset:6144
	ds_read_b128 v[198:201], v158 offset:7168
	global_load_lds_dwordx4 v[202:203], off
	v_lshl_add_u64 v[202:203], s[22:23], 0, v[140:141]
	s_add_i32 m0, s21, 0xe000
	s_nop 0
	global_load_lds_dwordx4 v[202:203], off
	s_waitcnt lgkmcnt(8)
	s_barrier
	s_waitcnt lgkmcnt(0)
	s_waitcnt lgkmcnt(0)
	v_mfma_f32_16x16x32_bf16 v[124:127], v[146:149], v[168:171], v[124:127]
	v_mfma_f32_16x16x32_bf16 v[120:123], v[160:163], v[168:171], v[120:123]
	v_mfma_f32_16x16x32_bf16 v[108:111], v[146:149], v[178:181], v[108:111]
	v_mfma_f32_16x16x32_bf16 v[104:107], v[160:163], v[178:181], v[104:107]
	v_mfma_f32_16x16x32_bf16 v[92:95], v[146:149], v[186:189], v[92:95]
	v_mfma_f32_16x16x32_bf16 v[88:91], v[160:163], v[186:189], v[88:91]
	v_mfma_f32_16x16x32_bf16 v[84:87], v[146:149], v[194:197], v[84:87]
	v_mfma_f32_16x16x32_bf16 v[76:79], v[160:163], v[194:197], v[76:79]
	v_mfma_f32_16x16x32_bf16 v[124:127], v[150:153], v[172:175], v[124:127]
	v_mfma_f32_16x16x32_bf16 v[120:123], v[164:167], v[172:175], v[120:123]
	v_mfma_f32_16x16x32_bf16 v[108:111], v[150:153], v[182:185], v[108:111]
	v_mfma_f32_16x16x32_bf16 v[104:107], v[164:167], v[182:185], v[104:107]
	v_mfma_f32_16x16x32_bf16 v[92:95], v[150:153], v[190:193], v[92:95]
	v_mfma_f32_16x16x32_bf16 v[88:91], v[164:167], v[190:193], v[88:91]
	v_mfma_f32_16x16x32_bf16 v[84:87], v[150:153], v[198:201], v[84:87]
	v_mfma_f32_16x16x32_bf16 v[76:79], v[164:167], v[198:201], v[76:79]
	s_barrier
	s_add_i32 s34, s45, s37
	v_lshl_add_u64 v[218:219], s[24:25], 0, v[134:135]
	s_mov_b32 m0, s34
	ds_read_b128 v[202:205], v159
	ds_read_b128 v[206:209], v159 offset:1024
	ds_read_b128 v[210:213], v159 offset:2048
	ds_read_b128 v[214:217], v159 offset:3072
	global_load_lds_dwordx4 v[218:219], off
	v_lshl_add_u64 v[220:221], s[24:25], 0, v[130:131]
	s_add_i32 m0, s34, 0x2000
	s_nop 0
	global_load_lds_dwordx4 v[220:221], off
	s_barrier
	s_waitcnt lgkmcnt(0)
	s_waitcnt lgkmcnt(0)
	v_mfma_f32_16x16x32_bf16 v[116:119], v[202:205], v[168:171], v[116:119]
	v_mfma_f32_16x16x32_bf16 v[112:115], v[210:213], v[168:171], v[112:115]
	v_mfma_f32_16x16x32_bf16 v[100:103], v[202:205], v[178:181], v[100:103]
	v_mfma_f32_16x16x32_bf16 v[96:99], v[210:213], v[178:181], v[96:99]
	v_mfma_f32_16x16x32_bf16 v[80:83], v[202:205], v[186:189], v[80:83]
	v_mfma_f32_16x16x32_bf16 v[72:75], v[210:213], v[186:189], v[72:75]
	v_mfma_f32_16x16x32_bf16 v[68:71], v[202:205], v[194:197], v[68:71]
	v_mfma_f32_16x16x32_bf16 v[64:67], v[210:213], v[194:197], v[64:67]
	v_mfma_f32_16x16x32_bf16 v[116:119], v[206:209], v[172:175], v[116:119]
	v_mfma_f32_16x16x32_bf16 v[112:115], v[214:217], v[172:175], v[112:115]
	v_mfma_f32_16x16x32_bf16 v[100:103], v[206:209], v[182:185], v[100:103]
	v_mfma_f32_16x16x32_bf16 v[96:99], v[214:217], v[182:185], v[96:99]
	v_mfma_f32_16x16x32_bf16 v[80:83], v[206:209], v[190:193], v[80:83]
	v_mfma_f32_16x16x32_bf16 v[72:75], v[214:217], v[190:193], v[72:75]
	v_mfma_f32_16x16x32_bf16 v[68:71], v[206:209], v[198:201], v[68:71]
	v_mfma_f32_16x16x32_bf16 v[64:67], v[214:217], v[198:201], v[64:67]
	s_mov_b32 m0, s21
	v_lshl_add_u64 v[222:223], s[26:27], 0, v[136:137]
	s_barrier
	ds_read_b128 v[168:171], v158 offset:16384
	ds_read_b128 v[172:175], v158 offset:17408
	ds_read_b128 v[178:181], v158 offset:18432
	ds_read_b128 v[182:185], v158 offset:19456
	ds_read_b128 v[186:189], v158 offset:20480
	ds_read_b128 v[190:193], v158 offset:21504
	ds_read_b128 v[194:197], v158 offset:22528
	ds_read_b128 v[198:201], v158 offset:23552
	global_load_lds_dwordx4 v[222:223], off
	v_lshl_add_u64 v[224:225], s[26:27], 0, v[132:133]
	s_mov_b32 m0, s39
	s_nop 0
	global_load_lds_dwordx4 v[224:225], off
	s_barrier
	s_waitcnt lgkmcnt(0)
	s_waitcnt lgkmcnt(0)
	v_mfma_f32_16x16x32_bf16 v[60:63], v[146:149], v[168:171], v[60:63]
	v_mfma_f32_16x16x32_bf16 v[56:59], v[160:163], v[168:171], v[56:59]
	v_mfma_f32_16x16x32_bf16 v[48:51], v[146:149], v[178:181], v[48:51]
	v_mfma_f32_16x16x32_bf16 v[40:43], v[160:163], v[178:181], v[40:43]
	v_mfma_f32_16x16x32_bf16 v[32:35], v[146:149], v[186:189], v[32:35]
	v_mfma_f32_16x16x32_bf16 v[24:27], v[160:163], v[186:189], v[24:27]
	v_mfma_f32_16x16x32_bf16 v[12:15], v[146:149], v[194:197], v[12:15]
	v_mfma_f32_16x16x32_bf16 v[8:11], v[160:163], v[194:197], v[8:11]
	v_mfma_f32_16x16x32_bf16 v[60:63], v[150:153], v[172:175], v[60:63]
	v_mfma_f32_16x16x32_bf16 v[56:59], v[164:167], v[172:175], v[56:59]
	v_mfma_f32_16x16x32_bf16 v[48:51], v[150:153], v[182:185], v[48:51]
	v_mfma_f32_16x16x32_bf16 v[40:43], v[164:167], v[182:185], v[40:43]
	v_mfma_f32_16x16x32_bf16 v[32:35], v[150:153], v[190:193], v[32:35]
	v_mfma_f32_16x16x32_bf16 v[24:27], v[164:167], v[190:193], v[24:27]
	v_mfma_f32_16x16x32_bf16 v[12:15], v[150:153], v[198:201], v[12:15]
	v_mfma_f32_16x16x32_bf16 v[8:11], v[164:167], v[198:201], v[8:11]
	s_barrier
	s_add_u32 s34, s24, 0x80000
	s_addc_u32 s35, s25, 0
	s_add_i32 s96, s46, s37
	v_lshl_add_u64 v[146:147], s[34:35], 0, v[134:135]
	s_mov_b32 m0, s96
	s_nop 0
	global_load_lds_dwordx4 v[146:147], off
	v_lshl_add_u64 v[146:147], s[34:35], 0, v[130:131]
	s_add_i32 m0, s96, 0x2000
	s_nop 0
	global_load_lds_dwordx4 v[146:147], off
	s_waitcnt vmcnt(6)
	s_barrier
	v_mfma_f32_16x16x32_bf16 v[52:55], v[202:205], v[168:171], v[52:55]
	v_mfma_f32_16x16x32_bf16 v[44:47], v[210:213], v[168:171], v[44:47]
	v_mfma_f32_16x16x32_bf16 v[36:39], v[202:205], v[178:181], v[36:39]
	v_mfma_f32_16x16x32_bf16 v[28:31], v[210:213], v[178:181], v[28:31]
	v_mfma_f32_16x16x32_bf16 v[20:23], v[202:205], v[186:189], v[20:23]
	v_mfma_f32_16x16x32_bf16 v[16:19], v[210:213], v[186:189], v[16:19]
	v_mfma_f32_16x16x32_bf16 v[4:7], v[202:205], v[194:197], v[4:7]
	v_mfma_f32_16x16x32_bf16 v[0:3], v[210:213], v[194:197], v[0:3]
	v_mfma_f32_16x16x32_bf16 v[52:55], v[206:209], v[172:175], v[52:55]
	v_mfma_f32_16x16x32_bf16 v[44:47], v[214:217], v[172:175], v[44:47]
	v_mfma_f32_16x16x32_bf16 v[36:39], v[206:209], v[182:185], v[36:39]
	v_mfma_f32_16x16x32_bf16 v[28:31], v[214:217], v[182:185], v[28:31]
	v_mfma_f32_16x16x32_bf16 v[20:23], v[206:209], v[190:193], v[20:23]
	v_mfma_f32_16x16x32_bf16 v[16:19], v[214:217], v[190:193], v[16:19]
	v_mfma_f32_16x16x32_bf16 v[4:7], v[206:209], v[198:201], v[4:7]
	v_mfma_f32_16x16x32_bf16 v[0:3], v[214:217], v[198:201], v[0:3]
	s_add_i32 s34, 0, 0x18000
	v_add_u32_e32 v164, s34, v155
	s_barrier
	ds_read_b128 v[146:149], v164
	ds_read_b128 v[150:153], v164 offset:1024
	ds_read_b128 v[160:163], v164 offset:2048
	ds_read_b128 v[164:167], v164 offset:3072
	s_add_u32 s26, s26, 0x80000
	s_addc_u32 s27, s27, 0
	s_mov_b32 m0, s40
	v_lshl_add_u64 v[202:203], s[26:27], 0, v[136:137]
	ds_read_b128 v[168:171], v158 offset:32768
	ds_read_b128 v[172:175], v158 offset:33792
	ds_read_b128 v[178:181], v158 offset:34816
	ds_read_b128 v[182:185], v158 offset:35840
	ds_read_b128 v[186:189], v158 offset:36864
	ds_read_b128 v[190:193], v158 offset:37888
	ds_read_b128 v[194:197], v158 offset:38912
	ds_read_b128 v[198:201], v158 offset:39936
	global_load_lds_dwordx4 v[202:203], off
	v_lshl_add_u64 v[202:203], s[26:27], 0, v[132:133]
	s_mov_b32 m0, s41
	s_nop 0
	global_load_lds_dwordx4 v[202:203], off
	s_waitcnt lgkmcnt(8)
	s_barrier
	s_waitcnt lgkmcnt(0)
	s_waitcnt lgkmcnt(0)
	v_mfma_f32_16x16x32_bf16 v[124:127], v[146:149], v[168:171], v[124:127]
	v_mfma_f32_16x16x32_bf16 v[120:123], v[160:163], v[168:171], v[120:123]
	v_mfma_f32_16x16x32_bf16 v[108:111], v[146:149], v[178:181], v[108:111]
	v_mfma_f32_16x16x32_bf16 v[104:107], v[160:163], v[178:181], v[104:107]
	v_mfma_f32_16x16x32_bf16 v[92:95], v[146:149], v[186:189], v[92:95]
	v_mfma_f32_16x16x32_bf16 v[88:91], v[160:163], v[186:189], v[88:91]
	v_mfma_f32_16x16x32_bf16 v[84:87], v[146:149], v[194:197], v[84:87]
	v_mfma_f32_16x16x32_bf16 v[76:79], v[160:163], v[194:197], v[76:79]
	v_mfma_f32_16x16x32_bf16 v[124:127], v[150:153], v[172:175], v[124:127]
	v_mfma_f32_16x16x32_bf16 v[120:123], v[164:167], v[172:175], v[120:123]
	v_mfma_f32_16x16x32_bf16 v[108:111], v[150:153], v[182:185], v[108:111]
	v_mfma_f32_16x16x32_bf16 v[104:107], v[164:167], v[182:185], v[104:107]
	v_mfma_f32_16x16x32_bf16 v[92:95], v[150:153], v[190:193], v[92:95]
	v_mfma_f32_16x16x32_bf16 v[88:91], v[164:167], v[190:193], v[88:91]
	v_mfma_f32_16x16x32_bf16 v[84:87], v[150:153], v[198:201], v[84:87]
	v_mfma_f32_16x16x32_bf16 v[76:79], v[164:167], v[198:201], v[76:79]
	s_barrier
	s_add_i32 s26, 0, 0x1c000
	s_add_i32 s27, s34, s37
	v_add_u32_e32 v177, s26, v155
	v_lshl_add_u64 v[218:219], v[218:219], 0, s[6:7]
	s_mov_b32 m0, s27
	ds_read_b128 v[202:205], v177
	ds_read_b128 v[206:209], v177 offset:1024
	ds_read_b128 v[210:213], v177 offset:2048
	ds_read_b128 v[214:217], v177 offset:3072
	global_load_lds_dwordx4 v[218:219], off
	v_lshl_add_u64 v[218:219], v[220:221], 0, s[6:7]
	s_add_i32 m0, s27, 0x2000
	s_nop 0
	global_load_lds_dwordx4 v[218:219], off
	s_barrier
	s_waitcnt lgkmcnt(0)
	s_waitcnt lgkmcnt(0)
	v_mfma_f32_16x16x32_bf16 v[116:119], v[202:205], v[168:171], v[116:119]
	v_mfma_f32_16x16x32_bf16 v[112:115], v[210:213], v[168:171], v[112:115]
	v_mfma_f32_16x16x32_bf16 v[100:103], v[202:205], v[178:181], v[100:103]
	v_mfma_f32_16x16x32_bf16 v[96:99], v[210:213], v[178:181], v[96:99]
	v_mfma_f32_16x16x32_bf16 v[80:83], v[202:205], v[186:189], v[80:83]
	v_mfma_f32_16x16x32_bf16 v[72:75], v[210:213], v[186:189], v[72:75]
	v_mfma_f32_16x16x32_bf16 v[68:71], v[202:205], v[194:197], v[68:71]
	v_mfma_f32_16x16x32_bf16 v[64:67], v[210:213], v[194:197], v[64:67]
	v_mfma_f32_16x16x32_bf16 v[116:119], v[206:209], v[172:175], v[116:119]
	v_mfma_f32_16x16x32_bf16 v[112:115], v[214:217], v[172:175], v[112:115]
	v_mfma_f32_16x16x32_bf16 v[100:103], v[206:209], v[182:185], v[100:103]
	v_mfma_f32_16x16x32_bf16 v[96:99], v[214:217], v[182:185], v[96:99]
	v_mfma_f32_16x16x32_bf16 v[80:83], v[206:209], v[190:193], v[80:83]
	v_mfma_f32_16x16x32_bf16 v[72:75], v[214:217], v[190:193], v[72:75]
	v_mfma_f32_16x16x32_bf16 v[68:71], v[206:209], v[198:201], v[68:71]
	v_mfma_f32_16x16x32_bf16 v[64:67], v[214:217], v[198:201], v[64:67]
	s_mov_b32 m0, s43
	v_lshl_add_u64 v[218:219], v[222:223], 0, s[6:7]
	s_barrier
	ds_read_b128 v[168:171], v158 offset:49152
	ds_read_b128 v[172:175], v158 offset:50176
	ds_read_b128 v[178:181], v158 offset:51200
	ds_read_b128 v[182:185], v158 offset:52224
	ds_read_b128 v[186:189], v158 offset:53248
	ds_read_b128 v[190:193], v158 offset:54272
	ds_read_b128 v[194:197], v158 offset:55296
	ds_read_b128 v[198:201], v158 offset:56320
	global_load_lds_dwordx4 v[218:219], off
	v_lshl_add_u64 v[218:219], v[224:225], 0, s[6:7]
	s_mov_b32 m0, s44
	s_nop 0
	global_load_lds_dwordx4 v[218:219], off
	s_barrier
	s_waitcnt lgkmcnt(0)
	s_waitcnt lgkmcnt(0)
	v_mfma_f32_16x16x32_bf16 v[60:63], v[146:149], v[168:171], v[60:63]
	v_mfma_f32_16x16x32_bf16 v[56:59], v[160:163], v[168:171], v[56:59]
	v_mfma_f32_16x16x32_bf16 v[48:51], v[146:149], v[178:181], v[48:51]
	v_mfma_f32_16x16x32_bf16 v[40:43], v[160:163], v[178:181], v[40:43]
	v_mfma_f32_16x16x32_bf16 v[32:35], v[146:149], v[186:189], v[32:35]
	v_mfma_f32_16x16x32_bf16 v[24:27], v[160:163], v[186:189], v[24:27]
	v_mfma_f32_16x16x32_bf16 v[12:15], v[146:149], v[194:197], v[12:15]
	v_mfma_f32_16x16x32_bf16 v[8:11], v[160:163], v[194:197], v[8:11]
	v_mfma_f32_16x16x32_bf16 v[60:63], v[150:153], v[172:175], v[60:63]
	v_mfma_f32_16x16x32_bf16 v[56:59], v[164:167], v[172:175], v[56:59]
	v_mfma_f32_16x16x32_bf16 v[48:51], v[150:153], v[182:185], v[48:51]
	v_mfma_f32_16x16x32_bf16 v[40:43], v[164:167], v[182:185], v[40:43]
	v_mfma_f32_16x16x32_bf16 v[32:35], v[150:153], v[190:193], v[32:35]
	v_mfma_f32_16x16x32_bf16 v[24:27], v[164:167], v[190:193], v[24:27]
	v_mfma_f32_16x16x32_bf16 v[12:15], v[150:153], v[198:201], v[12:15]
	v_mfma_f32_16x16x32_bf16 v[8:11], v[164:167], v[198:201], v[8:11]
	s_barrier
	s_add_u32 s24, s24, 0x80080
	s_addc_u32 s25, s25, 0
	s_add_i32 s26, s26, s37
	v_lshl_add_u64 v[146:147], s[24:25], 0, v[134:135]
	s_mov_b32 m0, s26
	s_nop 0
	global_load_lds_dwordx4 v[146:147], off
	v_lshl_add_u64 v[146:147], s[24:25], 0, v[130:131]
	s_add_i32 m0, s26, 0x2000
	s_nop 0
	global_load_lds_dwordx4 v[146:147], off
	s_waitcnt vmcnt(6)
	s_barrier
	v_mfma_f32_16x16x32_bf16 v[52:55], v[202:205], v[168:171], v[52:55]
	v_mfma_f32_16x16x32_bf16 v[44:47], v[210:213], v[168:171], v[44:47]
	v_mfma_f32_16x16x32_bf16 v[36:39], v[202:205], v[178:181], v[36:39]
	v_mfma_f32_16x16x32_bf16 v[28:31], v[210:213], v[178:181], v[28:31]
	v_mfma_f32_16x16x32_bf16 v[20:23], v[202:205], v[186:189], v[20:23]
	v_mfma_f32_16x16x32_bf16 v[16:19], v[210:213], v[186:189], v[16:19]
	v_mfma_f32_16x16x32_bf16 v[4:7], v[202:205], v[194:197], v[4:7]
	v_mfma_f32_16x16x32_bf16 v[0:3], v[210:213], v[194:197], v[0:3]
	v_mfma_f32_16x16x32_bf16 v[52:55], v[206:209], v[172:175], v[52:55]
	v_mfma_f32_16x16x32_bf16 v[44:47], v[214:217], v[172:175], v[44:47]
	v_mfma_f32_16x16x32_bf16 v[36:39], v[206:209], v[182:185], v[36:39]
	v_mfma_f32_16x16x32_bf16 v[28:31], v[214:217], v[182:185], v[28:31]
	v_mfma_f32_16x16x32_bf16 v[20:23], v[206:209], v[190:193], v[20:23]
	v_mfma_f32_16x16x32_bf16 v[16:19], v[214:217], v[190:193], v[16:19]
	v_mfma_f32_16x16x32_bf16 v[4:7], v[206:209], v[198:201], v[4:7]
	v_mfma_f32_16x16x32_bf16 v[0:3], v[214:217], v[198:201], v[0:3]
	s_add_i32 s83, s83, 2
	s_add_u32 s22, s22, 0x100
	s_addc_u32 s23, s23, 0
	s_add_u32 s81, s81, 0x100
	s_addc_u32 s82, s82, 0
	s_cmp_gt_u32 s83, 29
	s_barrier
	s_cbranch_scc0 .LBB0_178
	v_lshl_add_u32 v146, s20, 8, v154
	v_ashrrev_i32_e32 v147, 31, v146
	v_lshl_add_u64 v[152:153], v[146:147], 2, s[10:11]
	global_load_dword v160, v[152:153], off
	v_lshl_or_b32 v150, s50, 8, v156
	v_mov_b64_e32 v[148:149], s[30:31]
	v_ashrrev_i32_e32 v151, 31, v150
	v_mad_i64_i32 v[162:163], s[22:23], v146, s47, v[148:149]
	v_or_b32_e32 v164, 16, v146
	v_lshlrev_b64 v[150:151], 1, v[150:151]
	v_ashrrev_i32_e32 v165, 31, v164
	v_lshl_add_u64 v[162:163], v[162:163], 0, v[150:151]
	v_lshl_add_u64 v[166:167], v[164:165], 2, s[10:11]
	s_and_b64 vcc, exec, s[4:5]
	s_mov_b32 s50, s12
	s_mov_b32 s20, s14
	s_mov_b64 s[24:25], s[18:19]
	s_waitcnt vmcnt(0)
	v_pk_mul_f32 v[126:127], v[126:127], v[160:161] op_sel_hi:[1,0]
	v_pk_mul_f32 v[124:125], v[124:125], v[160:161] op_sel_hi:[1,0]
	v_pk_mul_f32 v[122:123], v[122:123], v[160:161] op_sel_hi:[1,0]
	v_pk_mul_f32 v[120:121], v[120:121], v[160:161] op_sel_hi:[1,0]
	v_pk_mul_f32 v[118:119], v[118:119], v[160:161] op_sel_hi:[1,0]
	v_pk_mul_f32 v[116:117], v[116:117], v[160:161] op_sel_hi:[1,0]
	v_pk_mul_f32 v[168:169], v[114:115], v[160:161] op_sel_hi:[1,0]
	v_pk_mul_f32 v[160:161], v[112:113], v[160:161] op_sel_hi:[1,0]
	v_cvt_pk_bf16_f32 v112, v124, v125
	v_cvt_pk_bf16_f32 v113, v126, v127
	v_cvt_pk_bf16_f32 v114, v120, v121
	v_cvt_pk_bf16_f32 v115, v122, v123
	v_cvt_pk_bf16_f32 v116, v116, v117
	v_cvt_pk_bf16_f32 v117, v118, v119
	v_cvt_pk_bf16_f32 v118, v160, v161
	v_cvt_pk_bf16_f32 v119, v168, v169
	global_store_dwordx4 v[162:163], v[112:115], off
	global_store_dwordx4 v[162:163], v[116:119], off offset:256
	global_load_dword v112, v[166:167], off
	v_or_b32_e32 v114, 32, v146
	v_mad_i64_i32 v[116:117], s[22:23], v164, s47, v[148:149]
	v_ashrrev_i32_e32 v115, 31, v114
	v_lshl_add_u64 v[116:117], v[116:117], 0, v[150:151]
	v_lshl_add_u64 v[118:119], v[114:115], 2, s[10:11]
	s_waitcnt vmcnt(0)
	v_pk_mul_f32 v[110:111], v[110:111], v[112:113] op_sel_hi:[1,0]
	v_pk_mul_f32 v[108:109], v[108:109], v[112:113] op_sel_hi:[1,0]
	v_pk_mul_f32 v[106:107], v[106:107], v[112:113] op_sel_hi:[1,0]
	v_pk_mul_f32 v[104:105], v[104:105], v[112:113] op_sel_hi:[1,0]
	v_pk_mul_f32 v[102:103], v[102:103], v[112:113] op_sel_hi:[1,0]
	v_pk_mul_f32 v[100:101], v[100:101], v[112:113] op_sel_hi:[1,0]
	v_pk_mul_f32 v[120:121], v[98:99], v[112:113] op_sel_hi:[1,0]
	v_pk_mul_f32 v[112:113], v[96:97], v[112:113] op_sel_hi:[1,0]
	v_cvt_pk_bf16_f32 v96, v108, v109
	v_cvt_pk_bf16_f32 v97, v110, v111
	v_cvt_pk_bf16_f32 v98, v104, v105
	v_cvt_pk_bf16_f32 v99, v106, v107
	v_cvt_pk_bf16_f32 v100, v100, v101
	v_cvt_pk_bf16_f32 v101, v102, v103
	v_cvt_pk_bf16_f32 v102, v112, v113
	v_cvt_pk_bf16_f32 v103, v120, v121
	global_store_dwordx4 v[116:117], v[96:99], off
	global_store_dwordx4 v[116:117], v[100:103], off offset:256
	global_load_dword v96, v[118:119], off
	v_or_b32_e32 v98, 48, v146
	v_mad_i64_i32 v[100:101], s[22:23], v114, s47, v[148:149]
	v_ashrrev_i32_e32 v99, 31, v98
	v_lshl_add_u64 v[100:101], v[100:101], 0, v[150:151]
	v_lshl_add_u64 v[102:103], v[98:99], 2, s[10:11]
	s_waitcnt vmcnt(0)
	v_pk_mul_f32 v[94:95], v[94:95], v[96:97] op_sel_hi:[1,0]
	v_pk_mul_f32 v[92:93], v[92:93], v[96:97] op_sel_hi:[1,0]
	v_pk_mul_f32 v[90:91], v[90:91], v[96:97] op_sel_hi:[1,0]
	v_pk_mul_f32 v[88:89], v[88:89], v[96:97] op_sel_hi:[1,0]
	v_pk_mul_f32 v[82:83], v[82:83], v[96:97] op_sel_hi:[1,0]
	v_pk_mul_f32 v[80:81], v[80:81], v[96:97] op_sel_hi:[1,0]
	v_pk_mul_f32 v[104:105], v[74:75], v[96:97] op_sel_hi:[1,0]
	v_pk_mul_f32 v[96:97], v[72:73], v[96:97] op_sel_hi:[1,0]
	v_cvt_pk_bf16_f32 v72, v92, v93
	v_cvt_pk_bf16_f32 v73, v94, v95
	v_cvt_pk_bf16_f32 v74, v88, v89
	v_cvt_pk_bf16_f32 v75, v90, v91
	v_cvt_pk_bf16_f32 v80, v80, v81
	v_cvt_pk_bf16_f32 v81, v82, v83
	v_cvt_pk_bf16_f32 v82, v96, v97
	v_cvt_pk_bf16_f32 v83, v104, v105
	global_store_dwordx4 v[100:101], v[72:75], off
	global_store_dwordx4 v[100:101], v[80:83], off offset:256
	global_load_dword v72, v[102:103], off
	v_mad_i64_i32 v[74:75], s[22:23], v98, s47, v[148:149]
	v_lshl_add_u64 v[74:75], v[74:75], 0, v[150:151]
	s_waitcnt vmcnt(0)
	v_pk_mul_f32 v[80:81], v[86:87], v[72:73] op_sel_hi:[1,0]
	v_pk_mul_f32 v[82:83], v[84:85], v[72:73] op_sel_hi:[1,0]
	v_pk_mul_f32 v[78:79], v[78:79], v[72:73] op_sel_hi:[1,0]
	v_pk_mul_f32 v[76:77], v[76:77], v[72:73] op_sel_hi:[1,0]
	v_pk_mul_f32 v[70:71], v[70:71], v[72:73] op_sel_hi:[1,0]
	v_pk_mul_f32 v[68:69], v[68:69], v[72:73] op_sel_hi:[1,0]
	v_pk_mul_f32 v[84:85], v[66:67], v[72:73] op_sel_hi:[1,0]
	v_pk_mul_f32 v[72:73], v[64:65], v[72:73] op_sel_hi:[1,0]
	v_cvt_pk_bf16_f32 v64, v82, v83
	v_cvt_pk_bf16_f32 v65, v80, v81
	v_cvt_pk_bf16_f32 v66, v76, v77
	v_cvt_pk_bf16_f32 v67, v78, v79
	v_cvt_pk_bf16_f32 v68, v68, v69
	v_cvt_pk_bf16_f32 v69, v70, v71
	v_cvt_pk_bf16_f32 v70, v72, v73
	v_cvt_pk_bf16_f32 v71, v84, v85
	global_store_dwordx4 v[74:75], v[64:67], off
	global_store_dwordx4 v[74:75], v[68:71], off offset:256
	global_load_dword v64, v[152:153], off offset:512
	v_add_u32_e32 v65, 0x80, v146
	v_mad_i64_i32 v[66:67], s[22:23], v65, s47, v[148:149]
	v_lshl_add_u64 v[66:67], v[66:67], 0, v[150:151]
	s_waitcnt vmcnt(0)
	v_pk_mul_f32 v[62:63], v[62:63], v[64:65] op_sel_hi:[1,0]
	v_pk_mul_f32 v[60:61], v[60:61], v[64:65] op_sel_hi:[1,0]
	v_pk_mul_f32 v[58:59], v[58:59], v[64:65] op_sel_hi:[1,0]
	v_pk_mul_f32 v[56:57], v[56:57], v[64:65] op_sel_hi:[1,0]
	v_pk_mul_f32 v[54:55], v[54:55], v[64:65] op_sel_hi:[1,0]
	v_pk_mul_f32 v[52:53], v[52:53], v[64:65] op_sel_hi:[1,0]
	v_pk_mul_f32 v[68:69], v[46:47], v[64:65] op_sel_hi:[1,0]
	v_pk_mul_f32 v[64:65], v[44:45], v[64:65] op_sel_hi:[1,0]
	v_cvt_pk_bf16_f32 v44, v60, v61
	v_cvt_pk_bf16_f32 v45, v62, v63
	v_cvt_pk_bf16_f32 v46, v56, v57
	v_cvt_pk_bf16_f32 v47, v58, v59
	v_cvt_pk_bf16_f32 v52, v52, v53
	v_cvt_pk_bf16_f32 v53, v54, v55
	v_cvt_pk_bf16_f32 v54, v64, v65
	v_cvt_pk_bf16_f32 v55, v68, v69
	global_store_dwordx4 v[66:67], v[44:47], off
	global_store_dwordx4 v[66:67], v[52:55], off offset:256
	global_load_dword v44, v[152:153], off offset:576
	v_add_u32_e32 v45, 0x90, v146
	v_mad_i64_i32 v[46:47], s[22:23], v45, s47, v[148:149]
	v_lshl_add_u64 v[46:47], v[46:47], 0, v[150:151]
	s_waitcnt vmcnt(0)
	v_pk_mul_f32 v[50:51], v[50:51], v[44:45] op_sel_hi:[1,0]
	v_pk_mul_f32 v[48:49], v[48:49], v[44:45] op_sel_hi:[1,0]
	v_pk_mul_f32 v[42:43], v[42:43], v[44:45] op_sel_hi:[1,0]
	v_pk_mul_f32 v[40:41], v[40:41], v[44:45] op_sel_hi:[1,0]
	v_pk_mul_f32 v[38:39], v[38:39], v[44:45] op_sel_hi:[1,0]
	v_pk_mul_f32 v[36:37], v[36:37], v[44:45] op_sel_hi:[1,0]
	v_pk_mul_f32 v[52:53], v[30:31], v[44:45] op_sel_hi:[1,0]
	v_pk_mul_f32 v[44:45], v[28:29], v[44:45] op_sel_hi:[1,0]
	v_cvt_pk_bf16_f32 v28, v48, v49
	v_cvt_pk_bf16_f32 v29, v50, v51
	v_cvt_pk_bf16_f32 v30, v40, v41
	v_cvt_pk_bf16_f32 v31, v42, v43
	v_cvt_pk_bf16_f32 v36, v36, v37
	v_cvt_pk_bf16_f32 v37, v38, v39
	v_cvt_pk_bf16_f32 v38, v44, v45
	v_cvt_pk_bf16_f32 v39, v52, v53
	global_store_dwordx4 v[46:47], v[28:31], off
	global_store_dwordx4 v[46:47], v[36:39], off offset:256
	global_load_dword v28, v[152:153], off offset:640
	v_add_u32_e32 v29, 0xa0, v146
	v_mad_i64_i32 v[30:31], s[22:23], v29, s47, v[148:149]
	v_lshl_add_u64 v[30:31], v[30:31], 0, v[150:151]
	s_mov_b64 s[22:23], s[16:17]
	s_waitcnt vmcnt(0)
	v_pk_mul_f32 v[34:35], v[34:35], v[28:29] op_sel_hi:[1,0]
	v_pk_mul_f32 v[32:33], v[32:33], v[28:29] op_sel_hi:[1,0]
	v_pk_mul_f32 v[26:27], v[26:27], v[28:29] op_sel_hi:[1,0]
	v_pk_mul_f32 v[24:25], v[24:25], v[28:29] op_sel_hi:[1,0]
	v_pk_mul_f32 v[22:23], v[22:23], v[28:29] op_sel_hi:[1,0]
	v_pk_mul_f32 v[20:21], v[20:21], v[28:29] op_sel_hi:[1,0]
	v_pk_mul_f32 v[36:37], v[18:19], v[28:29] op_sel_hi:[1,0]
	v_pk_mul_f32 v[28:29], v[16:17], v[28:29] op_sel_hi:[1,0]
	v_cvt_pk_bf16_f32 v16, v32, v33
	v_cvt_pk_bf16_f32 v17, v34, v35
	v_cvt_pk_bf16_f32 v18, v24, v25
	v_cvt_pk_bf16_f32 v19, v26, v27
	v_cvt_pk_bf16_f32 v20, v20, v21
	v_cvt_pk_bf16_f32 v21, v22, v23
	v_cvt_pk_bf16_f32 v22, v28, v29
	v_cvt_pk_bf16_f32 v23, v36, v37
	global_store_dwordx4 v[30:31], v[16:19], off
	global_store_dwordx4 v[30:31], v[20:23], off offset:256
	global_load_dword v16, v[152:153], off offset:704
	v_add_u32_e32 v17, 0xb0, v146
	v_mad_i64_i32 v[18:19], s[4:5], v17, s47, v[148:149]
	v_lshl_add_u64 v[18:19], v[18:19], 0, v[150:151]
	s_waitcnt vmcnt(0)
	v_pk_mul_f32 v[14:15], v[14:15], v[16:17] op_sel_hi:[1,0]
	v_pk_mul_f32 v[12:13], v[12:13], v[16:17] op_sel_hi:[1,0]
	v_pk_mul_f32 v[10:11], v[10:11], v[16:17] op_sel_hi:[1,0]
	v_pk_mul_f32 v[8:9], v[8:9], v[16:17] op_sel_hi:[1,0]
	v_pk_mul_f32 v[6:7], v[6:7], v[16:17] op_sel_hi:[1,0]
	v_pk_mul_f32 v[4:5], v[4:5], v[16:17] op_sel_hi:[1,0]
	v_pk_mul_f32 v[20:21], v[2:3], v[16:17] op_sel_hi:[1,0]
	v_pk_mul_f32 v[16:17], v[0:1], v[16:17] op_sel_hi:[1,0]
	v_cvt_pk_bf16_f32 v0, v12, v13
	v_cvt_pk_bf16_f32 v1, v14, v15
	v_cvt_pk_bf16_f32 v2, v8, v9
	v_cvt_pk_bf16_f32 v3, v10, v11
	v_cvt_pk_bf16_f32 v4, v4, v5
	v_cvt_pk_bf16_f32 v5, v6, v7
	v_cvt_pk_bf16_f32 v6, v16, v17
	v_cvt_pk_bf16_f32 v7, v20, v21
	global_store_dwordx4 v[18:19], v[0:3], off
	global_store_dwordx4 v[18:19], v[4:7], off offset:256
	s_cbranch_vccz .LBB0_175
	s_waitcnt vmcnt(0)
	s_setprio 0
	s_cmpk_gt_u32 s36, 0xff
	s_mov_b32 s43, s97
	s_cbranch_scc1 .LBB0_182
	s_barrier

.LBB0_678:
	s_or_b64 exec, exec, s[4:5]
	v_mov_b32_e32 v13, v176
	s_barrier
	s_mov_b32 s5, 0xfffe0
	v_ashrrev_i32_e32 v1, 31, v13
	v_lshrrev_b32_e32 v1, 26, v1
	v_add_u32_e32 v1, v13, v1
	v_ashrrev_i32_e32 v8, 6, v1
	v_bfe_i32 v1, v13, 27, 1
	v_lshlrev_b32_e32 v0, 4, v13
	v_lshrrev_b32_e32 v1, 22, v1
	v_add_u32_e32 v1, v0, v1
	v_and_b32_e32 v1, 0xfffffc00, v1
	v_sub_u32_e32 v1, v0, v1
	v_lshrrev_b32_e32 v2, 4, v1
	v_bitop3_b32 v2, v2, v1, 32 bitop3:0x6c
	v_ashrrev_i32_e32 v1, 31, v1
	v_lshrrev_b32_e32 v1, 26, v1
	v_add_u32_e32 v1, v2, v1
	v_ashrrev_i32_e32 v9, 6, v1
	v_lshlrev_b32_e32 v3, 3, v8
	v_mul_i32_i24_e32 v4, 64, v9
	v_and_b32_e32 v3, -16, v3
	v_sub_u32_e32 v2, v2, v4
	v_mov_b32_e32 v4, 1
	v_add_u32_e32 v1, v9, v3
	v_lshlrev_b32_e32 v3, 5, v8
	v_ashrrev_i16_sdwa v2, v4, sext(v2) dst_sel:DWORD dst_unused:UNUSED_PAD src0_sel:DWORD src1_sel:BYTE_0
	v_and_b32_e32 v3, 32, v3
	v_bfe_i32 v10, v2, 0, 16
	v_and_b32_e32 v6, 3, v9
	v_add_lshl_u32 v3, v3, v10, 1
	v_add_u32_e32 v0, 0x2000, v0
	v_lshlrev_b32_e32 v2, 1, v1
	v_lshrrev_b32_e32 v5, 2, v1
	v_and_or_b32 v6, v1, s5, v6
	v_lshl_add_u32 v128, v1, 12, v3
	v_ashrrev_i32_e32 v1, 31, v0
	v_lshrrev_b32_e32 v1, 22, v1
	v_add_u32_e32 v1, v0, v1
	v_ashrrev_i32_e32 v11, 10, v1
	v_mul_i32_i24_e32 v1, 0x400, v11
	v_sub_u32_e32 v0, v0, v1
	v_and_b32_e32 v2, 24, v2
	v_and_b32_e32 v5, 4, v5
	v_lshrrev_b32_e32 v1, 4, v0
	v_or3_b32 v2, v6, v5, v2
	v_bitop3_b32 v0, v1, v0, 32 bitop3:0x6c
	v_lshl_add_u32 v130, v2, 12, v3
	v_ashrrev_i32_e32 v2, 31, v0
	v_lshrrev_b32_e32 v2, 26, v2
	v_add_u32_e32 v2, v0, v2
	v_lshlrev_b32_e32 v1, 3, v11
	v_ashrrev_i32_e32 v12, 6, v2
	v_and_b32_e32 v2, 0xc0, v2
	s_sub_i32 s4, s68, s8
	v_and_b32_e32 v1, -16, v1
	v_sub_u32_e32 v0, v0, v2
	s_ashr_i32 s4, s4, 3
	v_readfirstlane_b32 s20, v13
	v_add_u32_e32 v1, v12, v1
	v_ashrrev_i16_sdwa v0, v4, sext(v0) dst_sel:DWORD dst_unused:UNUSED_PAD src0_sel:DWORD src1_sel:BYTE_0
	v_and_b32_e32 v4, 3, v12
	s_add_i32 s4, s4, 32
	s_and_b32 s22, s2, 7
	s_ashr_i32 s10, s20, 6
	v_and_or_b32 v4, v1, s5, v4
	s_mov_b32 s5, 0
	s_ashr_i32 s11, s20, 8
	s_lshl_b32 s16, s10, 10
	s_lshl_b64 s[12:13], s[4:5], 20
	s_lshl_b32 s14, s22, 20
	s_add_u32 s15, s30, s14
	s_addc_u32 s17, s31, 0
	s_add_u32 s6, s15, 0x13200000
	s_addc_u32 s7, s17, 0
	s_add_i32 s5, s16, 0
	s_add_i32 m0, s5, 0x10000
	v_lshlrev_b32_e32 v3, 5, v11
	v_bfe_i32 v14, v0, 0, 16
	v_lshlrev_b32_e32 v0, 1, v1
	v_lshrrev_b32_e32 v2, 2, v1
	global_load_lds_dwordx4 v130, s[6:7]
	s_add_i32 m0, s5, 0x12000
	v_and_b32_e32 v3, 32, v3
	v_and_b32_e32 v0, 24, v0
	v_and_b32_e32 v2, 4, v2
	s_add_u32 s21, s30, s12
	v_or3_b32 v0, v4, v2, v0
	v_add_lshl_u32 v2, v3, v14, 1
	s_addc_u32 s24, s31, s13
	v_lshl_add_u32 v134, v0, 12, v2
	s_add_u32 s8, s21, 0x10e00000
	global_load_lds_dwordx4 v134, s[6:7]
	s_addc_u32 s9, s24, 0
	s_mov_b32 m0, s5
	s_add_i32 s23, s5, 0x2000
	v_lshl_add_u32 v132, v1, 12, v2
	global_load_lds_dwordx4 v128, s[8:9]
	s_mov_b32 m0, s23
	s_add_u32 s18, s15, 0x13280000
	global_load_lds_dwordx4 v132, s[8:9]
	s_addc_u32 s19, s17, 0
	s_add_i32 m0, s5, 0x14000
	v_mov_b32_e32 v131, 0
	global_load_lds_dwordx4 v130, s[18:19]
	s_add_i32 m0, s5, 0x16000
	v_mov_b32_e32 v135, v131
	global_load_lds_dwordx4 v134, s[18:19]
	s_add_u32 s18, s21, 0x10e80000
	s_addc_u32 s19, s24, 0
	s_add_i32 s24, s5, 0x4000
	s_mov_b32 m0, s24
	s_add_i32 s25, s5, 0x6000
	global_load_lds_dwordx4 v128, s[18:19]
	s_mov_b32 m0, s25
	v_mov_b32_e32 v129, v131
	global_load_lds_dwordx4 v132, s[18:19]
	v_mov_b32_e32 v133, v131
	v_lshl_add_u64 v[6:7], s[6:7], 0, v[130:131]
	v_lshl_add_u64 v[4:5], s[6:7], 0, v[134:135]
	v_lshl_add_u64 v[2:3], s[8:9], 0, v[128:129]
	s_cmp_lg_u32 s11, 1
	v_lshl_add_u64 v[0:1], s[8:9], 0, v[132:133]
	s_cbranch_scc1 .LBB0_680
	s_setprio 1
	s_barrier

.LBB0_681:
	s_add_u32 s16, s12, s14
	ds_read_b128 v[146:149], v141
	ds_read_b128 v[150:153], v141 offset:1024
	ds_read_b128 v[154:157], v141 offset:2048
	ds_read_b128 v[158:161], v141 offset:3072
	s_addc_u32 s17, s13, s15
	s_add_u32 s16, s16, 0x10e00100
	s_addc_u32 s17, s17, 0
	s_add_u32 s34, s33, s14
	s_addc_u32 s47, s35, s15
	s_cmpk_eq_i32 s14, 0xf00
	s_cselect_b32 s19, s9, s17
	s_cselect_b32 s18, s8, s16
	s_cselect_b32 s17, s7, s47
	s_cselect_b32 s16, s6, s34
	s_mov_b32 m0, s37
	v_lshl_add_u64 v[174:175], v[136:137], 0, s[14:15]
	ds_read_b128 v[162:165], v142
	ds_read_b128 v[166:169], v142 offset:1024
	ds_read_b128 v[170:173], v142 offset:2048
	ds_read_b128 v[182:185], v142 offset:3072
	ds_read_b128 v[186:189], v142 offset:4096
	ds_read_b128 v[190:193], v142 offset:5120
	ds_read_b128 v[194:197], v142 offset:6144
	ds_read_b128 v[198:201], v142 offset:7168
	global_load_lds_dwordx4 v[174:175], off
	v_lshl_add_u64 v[174:175], v[138:139], 0, s[14:15]
	s_mov_b32 m0, s38
	s_nop 0
	global_load_lds_dwordx4 v[174:175], off
	s_waitcnt lgkmcnt(8)
	s_barrier
	s_waitcnt lgkmcnt(0)
	s_waitcnt lgkmcnt(0)
	v_mfma_f32_16x16x32_bf16 v[124:127], v[146:149], v[162:165], v[124:127]
	v_mfma_f32_16x16x32_bf16 v[120:123], v[154:157], v[162:165], v[120:123]
	v_mfma_f32_16x16x32_bf16 v[108:111], v[146:149], v[170:173], v[108:111]
	v_mfma_f32_16x16x32_bf16 v[104:107], v[154:157], v[170:173], v[104:107]
	v_mfma_f32_16x16x32_bf16 v[92:95], v[146:149], v[186:189], v[92:95]
	v_mfma_f32_16x16x32_bf16 v[88:91], v[154:157], v[186:189], v[88:91]
	v_mfma_f32_16x16x32_bf16 v[76:79], v[146:149], v[194:197], v[76:79]
	v_mfma_f32_16x16x32_bf16 v[72:75], v[154:157], v[194:197], v[72:75]
	v_mfma_f32_16x16x32_bf16 v[124:127], v[150:153], v[166:169], v[124:127]
	v_mfma_f32_16x16x32_bf16 v[120:123], v[158:161], v[166:169], v[120:123]
	v_mfma_f32_16x16x32_bf16 v[108:111], v[150:153], v[182:185], v[108:111]
	v_mfma_f32_16x16x32_bf16 v[104:107], v[158:161], v[182:185], v[104:107]
	v_mfma_f32_16x16x32_bf16 v[92:95], v[150:153], v[190:193], v[92:95]
	v_mfma_f32_16x16x32_bf16 v[88:91], v[158:161], v[190:193], v[88:91]
	v_mfma_f32_16x16x32_bf16 v[76:79], v[150:153], v[198:201], v[76:79]
	v_mfma_f32_16x16x32_bf16 v[72:75], v[158:161], v[198:201], v[72:75]
	s_barrier
	s_mov_b32 m0, s39
	v_lshl_add_u64 v[174:175], s[16:17], 0, v[130:131]
	ds_read_b128 v[202:205], v143
	ds_read_b128 v[206:209], v143 offset:1024
	ds_read_b128 v[210:213], v143 offset:2048
	ds_read_b128 v[214:217], v143 offset:3072
	global_load_lds_dwordx4 v[174:175], off
	v_lshl_add_u64 v[218:219], s[16:17], 0, v[134:135]
	s_mov_b32 m0, s40
	s_nop 0
	global_load_lds_dwordx4 v[218:219], off
	s_barrier
	s_waitcnt lgkmcnt(0)
	s_waitcnt lgkmcnt(0)
	v_mfma_f32_16x16x32_bf16 v[116:119], v[202:205], v[162:165], v[116:119]
	v_mfma_f32_16x16x32_bf16 v[112:115], v[210:213], v[162:165], v[112:115]
	v_mfma_f32_16x16x32_bf16 v[100:103], v[202:205], v[170:173], v[100:103]
	v_mfma_f32_16x16x32_bf16 v[96:99], v[210:213], v[170:173], v[96:99]
	v_mfma_f32_16x16x32_bf16 v[84:87], v[202:205], v[186:189], v[84:87]
	v_mfma_f32_16x16x32_bf16 v[80:83], v[210:213], v[186:189], v[80:83]
	v_mfma_f32_16x16x32_bf16 v[68:71], v[202:205], v[194:197], v[68:71]
	v_mfma_f32_16x16x32_bf16 v[64:67], v[210:213], v[194:197], v[64:67]
	v_mfma_f32_16x16x32_bf16 v[116:119], v[206:209], v[166:169], v[116:119]
	v_mfma_f32_16x16x32_bf16 v[112:115], v[214:217], v[166:169], v[112:115]
	v_mfma_f32_16x16x32_bf16 v[100:103], v[206:209], v[182:185], v[100:103]
	v_mfma_f32_16x16x32_bf16 v[96:99], v[214:217], v[182:185], v[96:99]
	v_mfma_f32_16x16x32_bf16 v[84:87], v[206:209], v[190:193], v[84:87]
	v_mfma_f32_16x16x32_bf16 v[80:83], v[214:217], v[190:193], v[80:83]
	v_mfma_f32_16x16x32_bf16 v[68:71], v[206:209], v[198:201], v[68:71]
	v_mfma_f32_16x16x32_bf16 v[64:67], v[214:217], v[198:201], v[64:67]
	s_mov_b32 m0, s5
	v_lshl_add_u64 v[220:221], s[18:19], 0, v[128:129]
	s_barrier
	ds_read_b128 v[162:165], v142 offset:16384
	ds_read_b128 v[166:169], v142 offset:17408
	ds_read_b128 v[170:173], v142 offset:18432
	ds_read_b128 v[182:185], v142 offset:19456
	ds_read_b128 v[186:189], v142 offset:20480
	ds_read_b128 v[190:193], v142 offset:21504
	ds_read_b128 v[194:197], v142 offset:22528
	ds_read_b128 v[198:201], v142 offset:23552
	global_load_lds_dwordx4 v[220:221], off
	v_lshl_add_u64 v[222:223], s[18:19], 0, v[132:133]
	s_mov_b32 m0, s23
	s_nop 0
	global_load_lds_dwordx4 v[222:223], off
	s_barrier
	s_waitcnt lgkmcnt(0)
	s_waitcnt lgkmcnt(0)
	v_mfma_f32_16x16x32_bf16 v[60:63], v[146:149], v[162:165], v[60:63]
	v_mfma_f32_16x16x32_bf16 v[56:59], v[154:157], v[162:165], v[56:59]
	v_mfma_f32_16x16x32_bf16 v[44:47], v[146:149], v[170:173], v[44:47]
	v_mfma_f32_16x16x32_bf16 v[40:43], v[154:157], v[170:173], v[40:43]
	v_mfma_f32_16x16x32_bf16 v[28:31], v[146:149], v[186:189], v[28:31]
	v_mfma_f32_16x16x32_bf16 v[24:27], v[154:157], v[186:189], v[24:27]
	v_mfma_f32_16x16x32_bf16 v[12:15], v[146:149], v[194:197], v[12:15]
	v_mfma_f32_16x16x32_bf16 v[8:11], v[154:157], v[194:197], v[8:11]
	v_mfma_f32_16x16x32_bf16 v[60:63], v[150:153], v[166:169], v[60:63]
	v_mfma_f32_16x16x32_bf16 v[56:59], v[158:161], v[166:169], v[56:59]
	v_mfma_f32_16x16x32_bf16 v[44:47], v[150:153], v[182:185], v[44:47]
	v_mfma_f32_16x16x32_bf16 v[40:43], v[158:161], v[182:185], v[40:43]
	v_mfma_f32_16x16x32_bf16 v[28:31], v[150:153], v[190:193], v[28:31]
	v_mfma_f32_16x16x32_bf16 v[24:27], v[158:161], v[190:193], v[24:27]
	v_mfma_f32_16x16x32_bf16 v[12:15], v[150:153], v[198:201], v[12:15]
	v_mfma_f32_16x16x32_bf16 v[8:11], v[158:161], v[198:201], v[8:11]
	s_barrier
	s_add_u32 s48, s16, 0x80000
	s_addc_u32 s49, s17, 0
	s_mov_b32 m0, s41
	v_lshl_add_u64 v[146:147], s[48:49], 0, v[130:131]
	global_load_lds_dwordx4 v[146:147], off
	v_lshl_add_u64 v[146:147], s[48:49], 0, v[134:135]
	s_mov_b32 m0, s42
	s_nop 0
	global_load_lds_dwordx4 v[146:147], off
	s_waitcnt vmcnt(6)
	s_barrier
	v_mfma_f32_16x16x32_bf16 v[52:55], v[202:205], v[162:165], v[52:55]
	v_mfma_f32_16x16x32_bf16 v[48:51], v[210:213], v[162:165], v[48:51]
	v_mfma_f32_16x16x32_bf16 v[36:39], v[202:205], v[170:173], v[36:39]
	v_mfma_f32_16x16x32_bf16 v[32:35], v[210:213], v[170:173], v[32:35]
	v_mfma_f32_16x16x32_bf16 v[20:23], v[202:205], v[186:189], v[20:23]
	v_mfma_f32_16x16x32_bf16 v[16:19], v[210:213], v[186:189], v[16:19]
	v_mfma_f32_16x16x32_bf16 v[4:7], v[202:205], v[194:197], v[4:7]
	v_mfma_f32_16x16x32_bf16 v[0:3], v[210:213], v[194:197], v[0:3]
	v_mfma_f32_16x16x32_bf16 v[52:55], v[206:209], v[166:169], v[52:55]
	v_mfma_f32_16x16x32_bf16 v[48:51], v[214:217], v[166:169], v[48:51]
	v_mfma_f32_16x16x32_bf16 v[36:39], v[206:209], v[182:185], v[36:39]
	v_mfma_f32_16x16x32_bf16 v[32:35], v[214:217], v[182:185], v[32:35]
	v_mfma_f32_16x16x32_bf16 v[20:23], v[206:209], v[190:193], v[20:23]
	v_mfma_f32_16x16x32_bf16 v[16:19], v[214:217], v[190:193], v[16:19]
	v_mfma_f32_16x16x32_bf16 v[4:7], v[206:209], v[198:201], v[4:7]
	v_mfma_f32_16x16x32_bf16 v[0:3], v[214:217], v[198:201], v[0:3]
	s_barrier
	ds_read_b128 v[146:149], v144
	ds_read_b128 v[150:153], v144 offset:1024
	ds_read_b128 v[154:157], v144 offset:2048
	ds_read_b128 v[158:161], v144 offset:3072
	s_add_u32 s18, s18, 0x80000
	s_addc_u32 s19, s19, 0
	s_mov_b32 m0, s24
	v_lshl_add_u64 v[202:203], s[18:19], 0, v[128:129]
	ds_read_b128 v[162:165], v142 offset:32768
	ds_read_b128 v[166:169], v142 offset:33792
	ds_read_b128 v[170:173], v142 offset:34816
	ds_read_b128 v[182:185], v142 offset:35840
	ds_read_b128 v[186:189], v142 offset:36864
	ds_read_b128 v[190:193], v142 offset:37888
	ds_read_b128 v[194:197], v142 offset:38912
	ds_read_b128 v[198:201], v142 offset:39936
	global_load_lds_dwordx4 v[202:203], off
	v_lshl_add_u64 v[202:203], s[18:19], 0, v[132:133]
	s_mov_b32 m0, s25
	s_nop 0
	global_load_lds_dwordx4 v[202:203], off
	s_waitcnt lgkmcnt(8)
	s_barrier
	s_waitcnt lgkmcnt(0)
	s_waitcnt lgkmcnt(0)
	v_mfma_f32_16x16x32_bf16 v[124:127], v[146:149], v[162:165], v[124:127]
	v_mfma_f32_16x16x32_bf16 v[120:123], v[154:157], v[162:165], v[120:123]
	v_mfma_f32_16x16x32_bf16 v[108:111], v[146:149], v[170:173], v[108:111]
	v_mfma_f32_16x16x32_bf16 v[104:107], v[154:157], v[170:173], v[104:107]
	v_mfma_f32_16x16x32_bf16 v[92:95], v[146:149], v[186:189], v[92:95]
	v_mfma_f32_16x16x32_bf16 v[88:91], v[154:157], v[186:189], v[88:91]
	v_mfma_f32_16x16x32_bf16 v[76:79], v[146:149], v[194:197], v[76:79]
	v_mfma_f32_16x16x32_bf16 v[72:75], v[154:157], v[194:197], v[72:75]
	v_mfma_f32_16x16x32_bf16 v[124:127], v[150:153], v[166:169], v[124:127]
	v_mfma_f32_16x16x32_bf16 v[120:123], v[158:161], v[166:169], v[120:123]
	v_mfma_f32_16x16x32_bf16 v[108:111], v[150:153], v[182:185], v[108:111]
	v_mfma_f32_16x16x32_bf16 v[104:107], v[158:161], v[182:185], v[104:107]
	v_mfma_f32_16x16x32_bf16 v[92:95], v[150:153], v[190:193], v[92:95]
	v_mfma_f32_16x16x32_bf16 v[88:91], v[158:161], v[190:193], v[88:91]
	v_mfma_f32_16x16x32_bf16 v[76:79], v[150:153], v[198:201], v[76:79]
	v_mfma_f32_16x16x32_bf16 v[72:75], v[158:161], v[198:201], v[72:75]
	s_barrier
	s_mov_b32 m0, s43
	v_lshl_add_u64 v[174:175], v[174:175], 0, s[10:11]
	ds_read_b128 v[202:205], v145
	ds_read_b128 v[206:209], v145 offset:1024
	ds_read_b128 v[210:213], v145 offset:2048
	ds_read_b128 v[214:217], v145 offset:3072
	global_load_lds_dwordx4 v[174:175], off
	v_lshl_add_u64 v[174:175], v[218:219], 0, s[10:11]
	s_mov_b32 m0, s44
	s_nop 0
	global_load_lds_dwordx4 v[174:175], off
	s_barrier
	s_waitcnt lgkmcnt(0)
	s_waitcnt lgkmcnt(0)
	v_mfma_f32_16x16x32_bf16 v[116:119], v[202:205], v[162:165], v[116:119]
	v_mfma_f32_16x16x32_bf16 v[112:115], v[210:213], v[162:165], v[112:115]
	v_mfma_f32_16x16x32_bf16 v[100:103], v[202:205], v[170:173], v[100:103]
	v_mfma_f32_16x16x32_bf16 v[96:99], v[210:213], v[170:173], v[96:99]
	v_mfma_f32_16x16x32_bf16 v[84:87], v[202:205], v[186:189], v[84:87]
	v_mfma_f32_16x16x32_bf16 v[80:83], v[210:213], v[186:189], v[80:83]
	v_mfma_f32_16x16x32_bf16 v[68:71], v[202:205], v[194:197], v[68:71]
	v_mfma_f32_16x16x32_bf16 v[64:67], v[210:213], v[194:197], v[64:67]
	v_mfma_f32_16x16x32_bf16 v[116:119], v[206:209], v[166:169], v[116:119]
	v_mfma_f32_16x16x32_bf16 v[112:115], v[214:217], v[166:169], v[112:115]
	v_mfma_f32_16x16x32_bf16 v[100:103], v[206:209], v[182:185], v[100:103]
	v_mfma_f32_16x16x32_bf16 v[96:99], v[214:217], v[182:185], v[96:99]
	v_mfma_f32_16x16x32_bf16 v[84:87], v[206:209], v[190:193], v[84:87]
	v_mfma_f32_16x16x32_bf16 v[80:83], v[214:217], v[190:193], v[80:83]
	v_mfma_f32_16x16x32_bf16 v[68:71], v[206:209], v[198:201], v[68:71]
	v_mfma_f32_16x16x32_bf16 v[64:67], v[214:217], v[198:201], v[64:67]
	s_mov_b32 m0, s26
	v_lshl_add_u64 v[174:175], v[220:221], 0, s[10:11]
	s_barrier
	ds_read_b128 v[162:165], v142 offset:49152
	ds_read_b128 v[166:169], v142 offset:50176
	ds_read_b128 v[170:173], v142 offset:51200
	ds_read_b128 v[182:185], v142 offset:52224
	ds_read_b128 v[186:189], v142 offset:53248
	ds_read_b128 v[190:193], v142 offset:54272
	ds_read_b128 v[194:197], v142 offset:55296
	ds_read_b128 v[198:201], v142 offset:56320
	global_load_lds_dwordx4 v[174:175], off
	v_lshl_add_u64 v[174:175], v[222:223], 0, s[10:11]
	s_mov_b32 m0, s27
	s_nop 0
	global_load_lds_dwordx4 v[174:175], off
	s_barrier
	s_waitcnt lgkmcnt(0)
	s_waitcnt lgkmcnt(0)
	v_mfma_f32_16x16x32_bf16 v[60:63], v[146:149], v[162:165], v[60:63]
	v_mfma_f32_16x16x32_bf16 v[56:59], v[154:157], v[162:165], v[56:59]
	v_mfma_f32_16x16x32_bf16 v[44:47], v[146:149], v[170:173], v[44:47]
	v_mfma_f32_16x16x32_bf16 v[40:43], v[154:157], v[170:173], v[40:43]
	v_mfma_f32_16x16x32_bf16 v[28:31], v[146:149], v[186:189], v[28:31]
	v_mfma_f32_16x16x32_bf16 v[24:27], v[154:157], v[186:189], v[24:27]
	v_mfma_f32_16x16x32_bf16 v[12:15], v[146:149], v[194:197], v[12:15]
	v_mfma_f32_16x16x32_bf16 v[8:11], v[154:157], v[194:197], v[8:11]
	v_mfma_f32_16x16x32_bf16 v[60:63], v[150:153], v[166:169], v[60:63]
	v_mfma_f32_16x16x32_bf16 v[56:59], v[158:161], v[166:169], v[56:59]
	v_mfma_f32_16x16x32_bf16 v[44:47], v[150:153], v[182:185], v[44:47]
	v_mfma_f32_16x16x32_bf16 v[40:43], v[158:161], v[182:185], v[40:43]
	v_mfma_f32_16x16x32_bf16 v[28:31], v[150:153], v[190:193], v[28:31]
	v_mfma_f32_16x16x32_bf16 v[24:27], v[158:161], v[190:193], v[24:27]
	v_mfma_f32_16x16x32_bf16 v[12:15], v[150:153], v[198:201], v[12:15]
	v_mfma_f32_16x16x32_bf16 v[8:11], v[158:161], v[198:201], v[8:11]
	s_barrier
	s_add_u32 s16, s16, 0x80080
	s_addc_u32 s17, s17, 0
	s_mov_b32 m0, s45
	v_lshl_add_u64 v[146:147], s[16:17], 0, v[130:131]
	global_load_lds_dwordx4 v[146:147], off
	v_lshl_add_u64 v[146:147], s[16:17], 0, v[134:135]
	s_mov_b32 m0, s46
	s_nop 0
	global_load_lds_dwordx4 v[146:147], off
	s_waitcnt vmcnt(6)
	s_barrier
	v_mfma_f32_16x16x32_bf16 v[52:55], v[202:205], v[162:165], v[52:55]
	v_mfma_f32_16x16x32_bf16 v[48:51], v[210:213], v[162:165], v[48:51]
	v_mfma_f32_16x16x32_bf16 v[36:39], v[202:205], v[170:173], v[36:39]
	v_mfma_f32_16x16x32_bf16 v[32:35], v[210:213], v[170:173], v[32:35]
	v_mfma_f32_16x16x32_bf16 v[20:23], v[202:205], v[186:189], v[20:23]
	v_mfma_f32_16x16x32_bf16 v[16:19], v[210:213], v[186:189], v[16:19]
	v_mfma_f32_16x16x32_bf16 v[4:7], v[202:205], v[194:197], v[4:7]
	v_mfma_f32_16x16x32_bf16 v[0:3], v[210:213], v[194:197], v[0:3]
	v_mfma_f32_16x16x32_bf16 v[52:55], v[206:209], v[166:169], v[52:55]
	v_mfma_f32_16x16x32_bf16 v[48:51], v[214:217], v[166:169], v[48:51]
	v_mfma_f32_16x16x32_bf16 v[36:39], v[206:209], v[182:185], v[36:39]
	v_mfma_f32_16x16x32_bf16 v[32:35], v[214:217], v[182:185], v[32:35]
	v_mfma_f32_16x16x32_bf16 v[20:23], v[206:209], v[190:193], v[20:23]
	v_mfma_f32_16x16x32_bf16 v[16:19], v[214:217], v[190:193], v[16:19]
	v_mfma_f32_16x16x32_bf16 v[4:7], v[206:209], v[198:201], v[4:7]
	v_mfma_f32_16x16x32_bf16 v[0:3], v[214:217], v[198:201], v[0:3]
	s_add_i32 s36, s36, 2
	s_add_u32 s14, s14, 0x100
	s_addc_u32 s15, s15, 0
	s_cmp_gt_u32 s36, 29
	s_barrier
	s_cbranch_scc0 .LBB0_681
	v_lshlrev_b32_e32 v128, 3, v177
	v_lshl_or_b32 v128, s21, 5, v128
	v_lshl_add_u32 v184, s4, 8, v140
	s_movk_i32 s8, 0x2000
	v_lshl_or_b32 v210, s22, 8, v128
	v_add_u32_e32 v128, 0xffffe000, v184
	v_ashrrev_i32_e32 v185, 31, v184
	v_cmp_gt_i32_e32 vcc, s8, v184
	v_mov_b32_e32 v138, s67
	v_mov_b32_e32 v139, s65
	v_cndmask_b32_e32 v129, 0, v185, vcc
	v_cndmask_b32_e32 v128, v128, v184, vcc
	v_mov_b32_e32 v140, s66
	v_mov_b32_e32 v141, s64
	v_or_b32_e32 v190, 16, v184
	v_lshlrev_b64 v[128:129], 13, v[128:129]
	v_cndmask_b32_e32 v137, v138, v139, vcc
	v_cndmask_b32_e32 v136, v140, v141, vcc
	v_mov_b32_e32 v183, 0
	v_ashrrev_i32_e32 v191, 31, v190
	v_add_u32_e32 v130, 0xffffe010, v184
	v_cmp_gt_i32_e64 s[4:5], s8, v190
	v_lshl_add_u64 v[128:129], v[136:137], 0, v[128:129]
	v_lshlrev_b32_e32 v182, 2, v210
	v_cndmask_b32_e64 v131, 0, v191, s[4:5]
	v_cndmask_b32_e64 v130, v130, v190, s[4:5]
	v_lshl_add_u64 v[128:129], v[128:129], 0, v[182:183]
	v_or_b32_e32 v188, 32, v184
	v_lshlrev_b64 v[130:131], 13, v[130:131]
	global_load_dwordx4 v[192:195], v[128:129], off offset:16
	global_load_dwordx4 v[196:199], v[128:129], off
	global_load_dwordx4 v[200:203], v[128:129], off offset:528
	global_load_dwordx4 v[204:207], v[128:129], off offset:512
	v_cndmask_b32_e64 v129, v138, v139, s[4:5]
	v_cndmask_b32_e64 v128, v140, v141, s[4:5]
	v_ashrrev_i32_e32 v189, 31, v188
	v_add_u32_e32 v132, 0xffffe020, v184
	v_cmp_gt_i32_e64 s[6:7], s8, v188
	v_lshl_add_u64 v[128:129], v[128:129], 0, v[130:131]
	v_lshl_add_u64 v[128:129], v[128:129], 0, v[182:183]
	v_cndmask_b32_e64 v133, 0, v189, s[6:7]
	v_cndmask_b32_e64 v132, v132, v188, s[6:7]
	v_or_b32_e32 v186, 48, v184
	v_lshlrev_b64 v[132:133], 13, v[132:133]
	global_load_dwordx4 v[168:171], v[128:129], off offset:16
	global_load_dwordx4 v[172:175], v[128:129], off
	global_load_dwordx4 v[160:163], v[128:129], off offset:528
	global_load_dwordx4 v[164:167], v[128:129], off offset:512
	v_cndmask_b32_e64 v129, v138, v139, s[6:7]
	v_cndmask_b32_e64 v128, v140, v141, s[6:7]
	v_ashrrev_i32_e32 v187, 31, v186
	v_add_u32_e32 v134, 0xffffe030, v184
	v_cmp_gt_i32_e64 s[8:9], s8, v186
	v_lshl_add_u64 v[128:129], v[128:129], 0, v[132:133]
	v_lshl_add_u64 v[128:129], v[128:129], 0, v[182:183]
	v_cndmask_b32_e64 v135, 0, v187, s[8:9]
	v_cndmask_b32_e64 v134, v134, v186, s[8:9]
	v_lshlrev_b64 v[134:135], 13, v[134:135]
	global_load_dwordx4 v[152:155], v[128:129], off offset:16
	global_load_dwordx4 v[156:159], v[128:129], off
	global_load_dwordx4 v[144:147], v[128:129], off offset:528
	global_load_dwordx4 v[148:151], v[128:129], off offset:512
	v_cndmask_b32_e64 v129, v138, v139, s[8:9]
	v_cndmask_b32_e64 v128, v140, v141, s[8:9]
	v_lshl_add_u64 v[128:129], v[128:129], 0, v[134:135]
	v_lshl_add_u64 v[132:133], v[128:129], 0, v[182:183]
	global_load_dwordx4 v[136:139], v[132:133], off offset:16
	global_load_dwordx4 v[140:143], v[132:133], off
	global_load_dwordx4 v[128:131], v[132:133], off offset:528
	s_nop 0
	global_load_dwordx4 v[132:135], v[132:133], off offset:512
	s_lshl_b32 s14, s22, 2
	s_add_u32 s12, s30, 0x17d29000
	s_mov_b32 s7, 0
	v_cmp_eq_u32_e32 vcc, 0, v177
	s_addc_u32 s13, s31, 0
	v_lshlrev_b64 v[208:209], 13, v[184:185]
	s_waitcnt vmcnt(0)
	v_pk_add_f32 v[192:193], v[120:121], v[192:193]
	v_lshlrev_b64 v[120:121], 12, v[184:185]
	v_lshl_add_u64 v[208:209], s[28:29], 0, v[208:209]
	v_pk_add_f32 v[124:125], v[124:125], v[196:197]
	v_pk_add_f32 v[194:195], v[122:123], v[194:195]
	v_lshl_add_u64 v[122:123], s[0:1], 0, v[120:121]
	v_lshlrev_b32_e32 v120, 1, v210
	v_mov_b32_e32 v121, v183
	v_lshl_add_u64 v[208:209], v[208:209], 0, v[182:183]
	v_pk_add_f32 v[126:127], v[126:127], v[198:199]
	v_lshl_add_u64 v[210:211], v[122:123], 0, v[120:121]
	v_mul_f32_e32 v122, v125, v125
	v_pk_add_f32 v[116:117], v[116:117], v[204:205]
	global_store_dwordx4 v[208:209], v[124:127], off
	global_store_dwordx4 v[208:209], v[192:195], off offset:16
	v_cvt_pk_bf16_f32 v196, v124, v125
	v_fmac_f32_e32 v122, v124, v124
	v_pk_add_f32 v[124:125], v[112:113], v[200:201]
	v_mul_f32_e32 v112, v117, v117
	v_pk_add_f32 v[118:119], v[118:119], v[206:207]
	v_fmac_f32_e32 v112, v116, v116
	v_fmac_f32_e32 v122, v126, v126
	v_fmac_f32_e32 v112, v118, v118
	v_mbcnt_lo_u32_b32 v113, -1, 0
	v_fmac_f32_e32 v122, v127, v127
	v_fmac_f32_e32 v112, v119, v119
	v_mbcnt_hi_u32_b32 v113, -1, v113
	v_cvt_pk_bf16_f32 v197, v126, v127
	v_fmac_f32_e32 v122, v192, v192
	v_pk_add_f32 v[126:127], v[114:115], v[202:203]
	v_fmac_f32_e32 v112, v124, v124
	v_and_b32_e32 v115, 64, v113
	v_fmac_f32_e32 v122, v193, v193
	v_fmac_f32_e32 v112, v125, v125
	v_xor_b32_e32 v114, 16, v113
	v_add_u32_e32 v115, 64, v115
	v_fmac_f32_e32 v122, v194, v194
	v_fmac_f32_e32 v112, v126, v126
	v_cmp_lt_i32_e64 s[4:5], v114, v115
	v_fmac_f32_e32 v122, v195, v195
	v_fmac_f32_e32 v112, v127, v127
	v_cndmask_b32_e64 v114, v113, v114, s[4:5]
	v_add_f32_e32 v112, v122, v112
	v_lshlrev_b32_e32 v122, 2, v114
	ds_bpermute_b32 v123, v122, v112
	v_cvt_pk_bf16_f32 v198, v192, v193
	v_cvt_pk_bf16_f32 v199, v194, v195
	global_store_dwordx4 v[210:211], v[196:199], off
	global_store_dwordx4 v[208:209], v[116:119], off offset:512
	global_store_dwordx4 v[208:209], v[124:127], off offset:528
	v_cvt_pk_bf16_f32 v114, v116, v117
	v_xor_b32_e32 v116, 32, v113
	v_cmp_lt_i32_e64 s[4:5], v116, v115
	s_waitcnt lgkmcnt(0)
	v_add_f32_e32 v112, v112, v123
	v_cvt_pk_bf16_f32 v115, v118, v119
	v_cndmask_b32_e64 v113, v113, v116, s[4:5]
	v_lshlrev_b32_e32 v123, 2, v113
	ds_bpermute_b32 v113, v123, v112
	v_cvt_pk_bf16_f32 v116, v124, v125
	v_cvt_pk_bf16_f32 v117, v126, v127
	global_store_dwordx4 v[210:211], v[114:117], off offset:256
	s_and_saveexec_b64 s[4:5], vcc
	s_cbranch_execz .LBB0_684
	v_lshlrev_b64 v[114:115], 7, v[184:185]
	v_lshl_add_u64 v[114:115], s[12:13], 0, v[114:115]
	s_lshl_b32 s6, s14, 2
	v_lshl_add_u64 v[114:115], v[114:115], 0, s[6:7]
	s_lshl_b32 s6, s21, 2
	v_lshl_add_u64 v[114:115], v[114:115], 0, s[6:7]
	s_waitcnt lgkmcnt(0)
	v_add_f32_e32 v112, v112, v113
	global_store_dword v[114:115], v112, off

.LBB0_698:
	s_or_b64 exec, exec, s[4:5]
	s_waitcnt vmcnt(0)
	s_setprio 0
	s_cmpk_gt_u32 s20, 0xff
	s_cbranch_scc1 .LBB0_700
	s_barrier

.LBB0_856:
	s_add_u32 s8, s30, 0x17d29000
	s_addc_u32 s9, s31, 0
	s_andn2_b64 vcc, exec, s[4:5]
	s_cbranch_vccnz .LBB0_888
	v_ashrrev_i32_e32 v1, 31, v9
	v_lshrrev_b32_e32 v1, 26, v1
	v_add_u32_e32 v1, v9, v1
	v_ashrrev_i32_e32 v8, 6, v1
	v_bfe_i32 v1, v9, 27, 1
	v_lshlrev_b32_e32 v0, 4, v9
	v_lshrrev_b32_e32 v1, 22, v1
	v_add_u32_e32 v1, v0, v1
	v_and_b32_e32 v1, 0xfffffc00, v1
	v_sub_u32_e32 v1, v0, v1
	v_lshrrev_b32_e32 v2, 4, v1
	v_bitop3_b32 v2, v2, v1, 32 bitop3:0x6c
	v_ashrrev_i32_e32 v1, 31, v1
	v_lshrrev_b32_e32 v1, 26, v1
	v_add_u32_e32 v1, v2, v1
	v_ashrrev_i32_e32 v10, 6, v1
	v_lshlrev_b32_e32 v3, 3, v8
	v_mul_i32_i24_e32 v4, 64, v10
	v_and_b32_e32 v3, -16, v3
	v_sub_u32_e32 v2, v2, v4
	v_mov_b32_e32 v4, 1
	v_add_u32_e32 v1, v10, v3
	v_lshlrev_b32_e32 v3, 5, v8
	v_ashrrev_i16_sdwa v2, v4, sext(v2) dst_sel:DWORD dst_unused:UNUSED_PAD src0_sel:DWORD src1_sel:BYTE_0
	v_and_b32_e32 v3, 32, v3
	v_bfe_i32 v11, v2, 0, 16
	v_and_b32_e32 v6, 3, v10
	s_mov_b32 s5, 0xfffe0
	v_add_lshl_u32 v3, v3, v11, 1
	v_add_u32_e32 v0, 0x2000, v0
	v_lshlrev_b32_e32 v2, 1, v1
	v_lshrrev_b32_e32 v5, 2, v1
	v_and_or_b32 v6, v1, s5, v6
	v_lshl_add_u32 v182, v1, 12, v3
	v_ashrrev_i32_e32 v1, 31, v0
	v_lshrrev_b32_e32 v1, 22, v1
	v_add_u32_e32 v1, v0, v1
	v_ashrrev_i32_e32 v12, 10, v1
	v_mul_i32_i24_e32 v1, 0x400, v12
	v_sub_u32_e32 v0, v0, v1
	v_and_b32_e32 v2, 24, v2
	v_and_b32_e32 v5, 4, v5
	v_lshrrev_b32_e32 v1, 4, v0
	v_or3_b32 v2, v6, v5, v2
	v_bitop3_b32 v0, v1, v0, 32 bitop3:0x6c
	v_lshl_add_u32 v184, v2, 12, v3
	v_ashrrev_i32_e32 v2, 31, v0
	v_lshrrev_b32_e32 v2, 26, v2
	s_add_u32 s35, s30, 0x10e00000
	v_add_u32_e32 v2, v0, v2
	s_addc_u32 s38, s31, 0
	v_lshlrev_b32_e32 v1, 3, v12
	v_ashrrev_i32_e32 v13, 6, v2
	v_and_b32_e32 v2, 0xc0, v2
	s_add_u32 s39, s30, 0x13200000
	v_and_b32_e32 v1, -16, v1
	v_sub_u32_e32 v0, v0, v2
	s_addc_u32 s40, s31, 0
	s_ashr_i32 s4, s33, 6
	v_add_u32_e32 v1, v13, v1
	v_ashrrev_i16_sdwa v0, v4, sext(v0) dst_sel:DWORD dst_unused:UNUSED_PAD src0_sel:DWORD src1_sel:BYTE_0
	v_and_b32_e32 v4, 3, v13
	s_ashr_i32 s13, s12, 31
	s_ashr_i32 s11, s10, 31
	v_and_or_b32 v4, v1, s5, v4
	s_ashr_i32 s5, s33, 8
	s_lshl_b32 s41, s4, 10
	s_lshl_b64 s[6:7], s[12:13], 20
	s_lshl_b64 s[14:15], s[10:11], 20
	s_add_u32 s26, s39, s14
	v_lshlrev_b32_e32 v3, 5, v12
	v_bfe_i32 v14, v0, 0, 16
	v_lshlrev_b32_e32 v0, 1, v1
	v_lshrrev_b32_e32 v2, 2, v1
	s_addc_u32 s27, s40, s15
	s_add_i32 s11, s41, 0
	v_and_b32_e32 v3, 32, v3
	v_and_b32_e32 v0, 24, v0
	v_and_b32_e32 v2, 4, v2
	s_add_i32 m0, s11, 0x10000
	v_or3_b32 v0, v4, v2, v0
	v_add_lshl_u32 v2, v3, v14, 1
	global_load_lds_dwordx4 v184, s[26:27]
	s_add_i32 m0, s11, 0x12000
	v_lshl_add_u32 v188, v0, 12, v2
	s_add_u32 s24, s35, s6
	global_load_lds_dwordx4 v188, s[26:27]
	s_addc_u32 s25, s38, s7
	s_mov_b32 m0, s11
	s_add_i32 s42, s11, 0x2000
	v_lshl_add_u32 v186, v1, 12, v2
	global_load_lds_dwordx4 v182, s[24:25]
	s_mov_b32 m0, s42
	s_add_u32 s6, s26, 0x80000
	global_load_lds_dwordx4 v186, s[24:25]
	s_addc_u32 s7, s27, 0
	s_add_i32 m0, s11, 0x14000
	v_mov_b32_e32 v185, 0
	global_load_lds_dwordx4 v184, s[6:7]
	s_add_i32 m0, s11, 0x16000
	v_mov_b32_e32 v189, v185
	global_load_lds_dwordx4 v188, s[6:7]
	s_add_u32 s6, s24, 0x80000
	s_addc_u32 s7, s25, 0
	s_add_i32 s43, s11, 0x4000
	s_mov_b32 m0, s43
	s_add_i32 s44, s11, 0x6000
	global_load_lds_dwordx4 v182, s[6:7]
	s_mov_b32 m0, s44
	v_mov_b32_e32 v183, v185
	global_load_lds_dwordx4 v186, s[6:7]
	v_mov_b32_e32 v187, v185
	s_movk_i32 s45, 0x2000
	s_mov_b32 s13, 0
	v_lshl_add_u64 v[6:7], s[26:27], 0, v[184:185]
	v_lshl_add_u64 v[4:5], s[26:27], 0, v[188:189]
	v_lshl_add_u64 v[2:3], s[24:25], 0, v[182:183]
	s_cmp_lg_u32 s5, 1
	v_lshl_add_u64 v[0:1], s[24:25], 0, v[186:187]
	s_cbranch_scc1 .LBB0_859
	s_setprio 1
	s_barrier

.LBB0_868:
	ds_read_b128 v[128:131], v212
	ds_read_b128 v[132:135], v212 offset:1024
	ds_read_b128 v[136:139], v212 offset:2048
	ds_read_b128 v[140:143], v212 offset:3072
	s_add_u32 s26, s24, 0xfff80080
	s_addc_u32 s27, s25, -1
	s_cmp_eq_u32 s54, 28
	s_cselect_b32 s37, s19, s27
	s_cselect_b32 s36, s52, s26
	s_cselect_b32 s27, s23, s53
	s_cselect_b32 s26, s22, s17
	v_lshl_add_u64 v[198:199], s[24:25], 0, v[190:191]
	s_add_i32 m0, s11, 0xc000
	ds_read_b128 v[144:147], v213
	ds_read_b128 v[148:151], v213 offset:1024
	ds_read_b128 v[152:155], v213 offset:2048
	ds_read_b128 v[156:159], v213 offset:3072
	ds_read_b128 v[160:163], v213 offset:4096
	ds_read_b128 v[164:167], v213 offset:5120
	ds_read_b128 v[168:171], v213 offset:6144
	ds_read_b128 v[172:175], v213 offset:7168
	global_load_lds_dwordx4 v[198:199], off
	v_lshl_add_u64 v[198:199], s[24:25], 0, v[192:193]
	s_add_i32 m0, s11, 0xe000
	s_nop 0
	global_load_lds_dwordx4 v[198:199], off
	s_waitcnt lgkmcnt(8)
	s_barrier
	s_waitcnt lgkmcnt(0)
	s_waitcnt lgkmcnt(0)
	v_mfma_f32_16x16x32_bf16 v[124:127], v[128:131], v[144:147], v[124:127]
	v_mfma_f32_16x16x32_bf16 v[120:123], v[136:139], v[144:147], v[120:123]
	v_mfma_f32_16x16x32_bf16 v[108:111], v[128:131], v[152:155], v[108:111]
	v_mfma_f32_16x16x32_bf16 v[104:107], v[136:139], v[152:155], v[104:107]
	v_mfma_f32_16x16x32_bf16 v[92:95], v[128:131], v[160:163], v[92:95]
	v_mfma_f32_16x16x32_bf16 v[88:91], v[136:139], v[160:163], v[88:91]
	v_mfma_f32_16x16x32_bf16 v[76:79], v[128:131], v[168:171], v[76:79]
	v_mfma_f32_16x16x32_bf16 v[72:75], v[136:139], v[168:171], v[72:75]
	v_mfma_f32_16x16x32_bf16 v[124:127], v[132:135], v[148:151], v[124:127]
	v_mfma_f32_16x16x32_bf16 v[120:123], v[140:143], v[148:151], v[120:123]
	v_mfma_f32_16x16x32_bf16 v[108:111], v[132:135], v[156:159], v[108:111]
	v_mfma_f32_16x16x32_bf16 v[104:107], v[140:143], v[156:159], v[104:107]
	v_mfma_f32_16x16x32_bf16 v[92:95], v[132:135], v[164:167], v[92:95]
	v_mfma_f32_16x16x32_bf16 v[88:91], v[140:143], v[164:167], v[88:91]
	v_mfma_f32_16x16x32_bf16 v[76:79], v[132:135], v[172:175], v[76:79]
	v_mfma_f32_16x16x32_bf16 v[72:75], v[140:143], v[172:175], v[72:75]
	s_barrier
	s_add_i32 s34, s49, s41
	v_lshl_add_u64 v[220:221], s[26:27], 0, v[184:185]
	s_mov_b32 m0, s34
	ds_read_b128 v[198:201], v214
	ds_read_b128 v[202:205], v214 offset:1024
	ds_read_b128 v[206:209], v214 offset:2048
	ds_read_b128 v[216:219], v214 offset:3072
	global_load_lds_dwordx4 v[220:221], off
	v_lshl_add_u64 v[222:223], s[26:27], 0, v[188:189]
	s_add_i32 m0, s34, 0x2000
	s_nop 0
	global_load_lds_dwordx4 v[222:223], off
	s_barrier
	s_waitcnt lgkmcnt(0)
	s_waitcnt lgkmcnt(0)
	v_mfma_f32_16x16x32_bf16 v[116:119], v[198:201], v[144:147], v[116:119]
	v_mfma_f32_16x16x32_bf16 v[112:115], v[206:209], v[144:147], v[112:115]
	v_mfma_f32_16x16x32_bf16 v[100:103], v[198:201], v[152:155], v[100:103]
	v_mfma_f32_16x16x32_bf16 v[96:99], v[206:209], v[152:155], v[96:99]
	v_mfma_f32_16x16x32_bf16 v[84:87], v[198:201], v[160:163], v[84:87]
	v_mfma_f32_16x16x32_bf16 v[80:83], v[206:209], v[160:163], v[80:83]
	v_mfma_f32_16x16x32_bf16 v[68:71], v[198:201], v[168:171], v[68:71]
	v_mfma_f32_16x16x32_bf16 v[64:67], v[206:209], v[168:171], v[64:67]
	v_mfma_f32_16x16x32_bf16 v[116:119], v[202:205], v[148:151], v[116:119]
	v_mfma_f32_16x16x32_bf16 v[112:115], v[216:219], v[148:151], v[112:115]
	v_mfma_f32_16x16x32_bf16 v[100:103], v[202:205], v[156:159], v[100:103]
	v_mfma_f32_16x16x32_bf16 v[96:99], v[216:219], v[156:159], v[96:99]
	v_mfma_f32_16x16x32_bf16 v[84:87], v[202:205], v[164:167], v[84:87]
	v_mfma_f32_16x16x32_bf16 v[80:83], v[216:219], v[164:167], v[80:83]
	v_mfma_f32_16x16x32_bf16 v[68:71], v[202:205], v[172:175], v[68:71]
	v_mfma_f32_16x16x32_bf16 v[64:67], v[216:219], v[172:175], v[64:67]
	s_mov_b32 m0, s11
	v_lshl_add_u64 v[224:225], s[36:37], 0, v[182:183]
	s_barrier
	ds_read_b128 v[144:147], v213 offset:16384
	ds_read_b128 v[148:151], v213 offset:17408
	ds_read_b128 v[152:155], v213 offset:18432
	ds_read_b128 v[156:159], v213 offset:19456
	ds_read_b128 v[160:163], v213 offset:20480
	ds_read_b128 v[164:167], v213 offset:21504
	ds_read_b128 v[168:171], v213 offset:22528
	ds_read_b128 v[172:175], v213 offset:23552
	global_load_lds_dwordx4 v[224:225], off
	v_lshl_add_u64 v[226:227], s[36:37], 0, v[186:187]
	s_mov_b32 m0, s42
	s_nop 0
	global_load_lds_dwordx4 v[226:227], off
	s_barrier
	s_waitcnt lgkmcnt(0)
	s_waitcnt lgkmcnt(0)
	v_mfma_f32_16x16x32_bf16 v[60:63], v[128:131], v[144:147], v[60:63]
	v_mfma_f32_16x16x32_bf16 v[56:59], v[136:139], v[144:147], v[56:59]
	v_mfma_f32_16x16x32_bf16 v[44:47], v[128:131], v[152:155], v[44:47]
	v_mfma_f32_16x16x32_bf16 v[40:43], v[136:139], v[152:155], v[40:43]
	v_mfma_f32_16x16x32_bf16 v[28:31], v[128:131], v[160:163], v[28:31]
	v_mfma_f32_16x16x32_bf16 v[24:27], v[136:139], v[160:163], v[24:27]
	v_mfma_f32_16x16x32_bf16 v[12:15], v[128:131], v[168:171], v[12:15]
	v_mfma_f32_16x16x32_bf16 v[8:11], v[136:139], v[168:171], v[8:11]
	v_mfma_f32_16x16x32_bf16 v[60:63], v[132:135], v[148:151], v[60:63]
	v_mfma_f32_16x16x32_bf16 v[56:59], v[140:143], v[148:151], v[56:59]
	v_mfma_f32_16x16x32_bf16 v[44:47], v[132:135], v[156:159], v[44:47]
	v_mfma_f32_16x16x32_bf16 v[40:43], v[140:143], v[156:159], v[40:43]
	v_mfma_f32_16x16x32_bf16 v[28:31], v[132:135], v[164:167], v[28:31]
	v_mfma_f32_16x16x32_bf16 v[24:27], v[140:143], v[164:167], v[24:27]
	v_mfma_f32_16x16x32_bf16 v[12:15], v[132:135], v[172:175], v[12:15]
	v_mfma_f32_16x16x32_bf16 v[8:11], v[140:143], v[172:175], v[8:11]
	s_barrier
	s_add_u32 s60, s26, 0x80000
	s_addc_u32 s61, s27, 0
	s_add_i32 s34, s50, s41
	v_lshl_add_u64 v[128:129], s[60:61], 0, v[184:185]
	s_mov_b32 m0, s34
	s_nop 0
	global_load_lds_dwordx4 v[128:129], off
	v_lshl_add_u64 v[128:129], s[60:61], 0, v[188:189]
	s_add_i32 m0, s34, 0x2000
	s_nop 0
	global_load_lds_dwordx4 v[128:129], off
	s_waitcnt vmcnt(6)
	s_barrier
	v_mfma_f32_16x16x32_bf16 v[52:55], v[198:201], v[144:147], v[52:55]
	v_mfma_f32_16x16x32_bf16 v[48:51], v[206:209], v[144:147], v[48:51]
	v_mfma_f32_16x16x32_bf16 v[36:39], v[198:201], v[152:155], v[36:39]
	v_mfma_f32_16x16x32_bf16 v[32:35], v[206:209], v[152:155], v[32:35]
	v_mfma_f32_16x16x32_bf16 v[20:23], v[198:201], v[160:163], v[20:23]
	v_mfma_f32_16x16x32_bf16 v[16:19], v[206:209], v[160:163], v[16:19]
	v_mfma_f32_16x16x32_bf16 v[4:7], v[198:201], v[168:171], v[4:7]
	v_mfma_f32_16x16x32_bf16 v[0:3], v[206:209], v[168:171], v[0:3]
	v_mfma_f32_16x16x32_bf16 v[52:55], v[202:205], v[148:151], v[52:55]
	v_mfma_f32_16x16x32_bf16 v[48:51], v[216:219], v[148:151], v[48:51]
	v_mfma_f32_16x16x32_bf16 v[36:39], v[202:205], v[156:159], v[36:39]
	v_mfma_f32_16x16x32_bf16 v[32:35], v[216:219], v[156:159], v[32:35]
	v_mfma_f32_16x16x32_bf16 v[20:23], v[202:205], v[164:167], v[20:23]
	v_mfma_f32_16x16x32_bf16 v[16:19], v[216:219], v[164:167], v[16:19]
	v_mfma_f32_16x16x32_bf16 v[4:7], v[202:205], v[172:175], v[4:7]
	v_mfma_f32_16x16x32_bf16 v[0:3], v[216:219], v[172:175], v[0:3]
	s_add_i32 s34, 0, 0x18000
	v_add_u32_e32 v140, s34, v210
	s_barrier
	ds_read_b128 v[128:131], v140
	ds_read_b128 v[132:135], v140 offset:1024
	ds_read_b128 v[136:139], v140 offset:2048
	ds_read_b128 v[140:143], v140 offset:3072
	s_add_u32 s36, s36, 0x80000
	s_addc_u32 s37, s37, 0
	s_mov_b32 m0, s43
	v_lshl_add_u64 v[198:199], s[36:37], 0, v[182:183]
	ds_read_b128 v[144:147], v213 offset:32768
	ds_read_b128 v[148:151], v213 offset:33792
	ds_read_b128 v[152:155], v213 offset:34816
	ds_read_b128 v[156:159], v213 offset:35840
	ds_read_b128 v[160:163], v213 offset:36864
	ds_read_b128 v[164:167], v213 offset:37888
	ds_read_b128 v[168:171], v213 offset:38912
	ds_read_b128 v[172:175], v213 offset:39936
	global_load_lds_dwordx4 v[198:199], off
	v_lshl_add_u64 v[198:199], s[36:37], 0, v[186:187]
	s_mov_b32 m0, s44
	s_nop 0
	global_load_lds_dwordx4 v[198:199], off
	s_waitcnt lgkmcnt(8)
	s_barrier
	s_waitcnt lgkmcnt(0)
	s_waitcnt lgkmcnt(0)
	v_mfma_f32_16x16x32_bf16 v[124:127], v[128:131], v[144:147], v[124:127]
	v_mfma_f32_16x16x32_bf16 v[120:123], v[136:139], v[144:147], v[120:123]
	v_mfma_f32_16x16x32_bf16 v[108:111], v[128:131], v[152:155], v[108:111]
	v_mfma_f32_16x16x32_bf16 v[104:107], v[136:139], v[152:155], v[104:107]
	v_mfma_f32_16x16x32_bf16 v[92:95], v[128:131], v[160:163], v[92:95]
	v_mfma_f32_16x16x32_bf16 v[88:91], v[136:139], v[160:163], v[88:91]
	v_mfma_f32_16x16x32_bf16 v[76:79], v[128:131], v[168:171], v[76:79]
	v_mfma_f32_16x16x32_bf16 v[72:75], v[136:139], v[168:171], v[72:75]
	v_mfma_f32_16x16x32_bf16 v[124:127], v[132:135], v[148:151], v[124:127]
	v_mfma_f32_16x16x32_bf16 v[120:123], v[140:143], v[148:151], v[120:123]
	v_mfma_f32_16x16x32_bf16 v[108:111], v[132:135], v[156:159], v[108:111]
	v_mfma_f32_16x16x32_bf16 v[104:107], v[140:143], v[156:159], v[104:107]
	v_mfma_f32_16x16x32_bf16 v[92:95], v[132:135], v[164:167], v[92:95]
	v_mfma_f32_16x16x32_bf16 v[88:91], v[140:143], v[164:167], v[88:91]
	v_mfma_f32_16x16x32_bf16 v[76:79], v[132:135], v[172:175], v[76:79]
	v_mfma_f32_16x16x32_bf16 v[72:75], v[140:143], v[172:175], v[72:75]
	s_barrier
	s_add_i32 s36, 0, 0x1c000
	s_add_i32 s34, s34, s41
	v_add_u32_e32 v216, s36, v210
	v_lshl_add_u64 v[220:221], v[220:221], 0, s[14:15]
	s_mov_b32 m0, s34
	ds_read_b128 v[198:201], v216
	ds_read_b128 v[202:205], v216 offset:1024
	ds_read_b128 v[206:209], v216 offset:2048
	ds_read_b128 v[216:219], v216 offset:3072
	global_load_lds_dwordx4 v[220:221], off
	v_lshl_add_u64 v[220:221], v[222:223], 0, s[14:15]
	s_add_i32 m0, s34, 0x2000
	s_nop 0
	global_load_lds_dwordx4 v[220:221], off
	s_barrier
	s_waitcnt lgkmcnt(0)
	s_waitcnt lgkmcnt(0)
	v_mfma_f32_16x16x32_bf16 v[116:119], v[198:201], v[144:147], v[116:119]
	v_mfma_f32_16x16x32_bf16 v[112:115], v[206:209], v[144:147], v[112:115]
	v_mfma_f32_16x16x32_bf16 v[100:103], v[198:201], v[152:155], v[100:103]
	v_mfma_f32_16x16x32_bf16 v[96:99], v[206:209], v[152:155], v[96:99]
	v_mfma_f32_16x16x32_bf16 v[84:87], v[198:201], v[160:163], v[84:87]
	v_mfma_f32_16x16x32_bf16 v[80:83], v[206:209], v[160:163], v[80:83]
	v_mfma_f32_16x16x32_bf16 v[68:71], v[198:201], v[168:171], v[68:71]
	v_mfma_f32_16x16x32_bf16 v[64:67], v[206:209], v[168:171], v[64:67]
	v_mfma_f32_16x16x32_bf16 v[116:119], v[202:205], v[148:151], v[116:119]
	v_mfma_f32_16x16x32_bf16 v[112:115], v[216:219], v[148:151], v[112:115]
	v_mfma_f32_16x16x32_bf16 v[100:103], v[202:205], v[156:159], v[100:103]
	v_mfma_f32_16x16x32_bf16 v[96:99], v[216:219], v[156:159], v[96:99]
	v_mfma_f32_16x16x32_bf16 v[84:87], v[202:205], v[164:167], v[84:87]
	v_mfma_f32_16x16x32_bf16 v[80:83], v[216:219], v[164:167], v[80:83]
	v_mfma_f32_16x16x32_bf16 v[68:71], v[202:205], v[172:175], v[68:71]
	v_mfma_f32_16x16x32_bf16 v[64:67], v[216:219], v[172:175], v[64:67]
	s_mov_b32 m0, s47
	v_lshl_add_u64 v[220:221], v[224:225], 0, s[14:15]
	s_barrier
	ds_read_b128 v[144:147], v213 offset:49152
	ds_read_b128 v[148:151], v213 offset:50176
	ds_read_b128 v[152:155], v213 offset:51200
	ds_read_b128 v[156:159], v213 offset:52224
	ds_read_b128 v[160:163], v213 offset:53248
	ds_read_b128 v[164:167], v213 offset:54272
	ds_read_b128 v[168:171], v213 offset:55296
	ds_read_b128 v[172:175], v213 offset:56320
	global_load_lds_dwordx4 v[220:221], off
	v_lshl_add_u64 v[220:221], v[226:227], 0, s[14:15]
	s_mov_b32 m0, s48
	s_nop 0
	global_load_lds_dwordx4 v[220:221], off
	s_barrier
	s_waitcnt lgkmcnt(0)
	s_waitcnt lgkmcnt(0)
	v_mfma_f32_16x16x32_bf16 v[60:63], v[128:131], v[144:147], v[60:63]
	v_mfma_f32_16x16x32_bf16 v[56:59], v[136:139], v[144:147], v[56:59]
	v_mfma_f32_16x16x32_bf16 v[44:47], v[128:131], v[152:155], v[44:47]
	v_mfma_f32_16x16x32_bf16 v[40:43], v[136:139], v[152:155], v[40:43]
	v_mfma_f32_16x16x32_bf16 v[28:31], v[128:131], v[160:163], v[28:31]
	v_mfma_f32_16x16x32_bf16 v[24:27], v[136:139], v[160:163], v[24:27]
	v_mfma_f32_16x16x32_bf16 v[12:15], v[128:131], v[168:171], v[12:15]
	v_mfma_f32_16x16x32_bf16 v[8:11], v[136:139], v[168:171], v[8:11]
	v_mfma_f32_16x16x32_bf16 v[60:63], v[132:135], v[148:151], v[60:63]
	v_mfma_f32_16x16x32_bf16 v[56:59], v[140:143], v[148:151], v[56:59]
	v_mfma_f32_16x16x32_bf16 v[44:47], v[132:135], v[156:159], v[44:47]
	v_mfma_f32_16x16x32_bf16 v[40:43], v[140:143], v[156:159], v[40:43]
	v_mfma_f32_16x16x32_bf16 v[28:31], v[132:135], v[164:167], v[28:31]
	v_mfma_f32_16x16x32_bf16 v[24:27], v[140:143], v[164:167], v[24:27]
	v_mfma_f32_16x16x32_bf16 v[12:15], v[132:135], v[172:175], v[12:15]
	v_mfma_f32_16x16x32_bf16 v[8:11], v[140:143], v[172:175], v[8:11]
	s_barrier
	s_add_u32 s26, s26, 0x80080
	s_addc_u32 s27, s27, 0
	s_add_i32 s34, s36, s41
	v_lshl_add_u64 v[128:129], s[26:27], 0, v[184:185]
	s_mov_b32 m0, s34
	s_nop 0
	global_load_lds_dwordx4 v[128:129], off
	v_lshl_add_u64 v[128:129], s[26:27], 0, v[188:189]
	s_add_i32 m0, s34, 0x2000
	s_nop 0
	global_load_lds_dwordx4 v[128:129], off
	s_waitcnt vmcnt(6)
	s_barrier
	v_mfma_f32_16x16x32_bf16 v[52:55], v[198:201], v[144:147], v[52:55]
	v_mfma_f32_16x16x32_bf16 v[48:51], v[206:209], v[144:147], v[48:51]
	v_mfma_f32_16x16x32_bf16 v[36:39], v[198:201], v[152:155], v[36:39]
	v_mfma_f32_16x16x32_bf16 v[32:35], v[206:209], v[152:155], v[32:35]
	v_mfma_f32_16x16x32_bf16 v[20:23], v[198:201], v[160:163], v[20:23]
	v_mfma_f32_16x16x32_bf16 v[16:19], v[206:209], v[160:163], v[16:19]
	v_mfma_f32_16x16x32_bf16 v[4:7], v[198:201], v[168:171], v[4:7]
	v_mfma_f32_16x16x32_bf16 v[0:3], v[206:209], v[168:171], v[0:3]
	v_mfma_f32_16x16x32_bf16 v[52:55], v[202:205], v[148:151], v[52:55]
	v_mfma_f32_16x16x32_bf16 v[48:51], v[216:219], v[148:151], v[48:51]
	v_mfma_f32_16x16x32_bf16 v[36:39], v[202:205], v[156:159], v[36:39]
	v_mfma_f32_16x16x32_bf16 v[32:35], v[216:219], v[156:159], v[32:35]
	v_mfma_f32_16x16x32_bf16 v[20:23], v[202:205], v[164:167], v[20:23]
	v_mfma_f32_16x16x32_bf16 v[16:19], v[216:219], v[164:167], v[16:19]
	v_mfma_f32_16x16x32_bf16 v[4:7], v[202:205], v[172:175], v[4:7]
	v_mfma_f32_16x16x32_bf16 v[0:3], v[216:219], v[172:175], v[0:3]
	s_add_i32 s54, s54, 2
	s_add_u32 s24, s24, 0x100
	s_addc_u32 s25, s25, 0
	s_add_u32 s17, s17, 0x100
	s_addc_u32 s53, s53, 0
	s_cmp_gt_u32 s54, 29
	s_barrier
	s_cbranch_scc0 .LBB0_868
	v_lshl_add_u32 v200, s12, 8, v177
	v_add_u32_e32 v128, 0xffffe000, v200
	v_ashrrev_i32_e32 v201, 31, v200
	v_cmp_gt_i32_e32 vcc, s45, v200
	v_lshl_or_b32 v198, s10, 8, v211
	v_mov_b32_e32 v132, s67
	v_cndmask_b32_e32 v129, 0, v201, vcc
	v_cndmask_b32_e32 v128, v128, v200, vcc
	v_mov_b32_e32 v133, s65
	v_mov_b32_e32 v134, s66
	v_mov_b32_e32 v135, s64
	v_ashrrev_i32_e32 v199, 31, v198
	v_cndmask_b32_e32 v131, v132, v133, vcc
	v_cndmask_b32_e32 v130, v134, v135, vcc
	v_lshlrev_b64 v[128:129], 13, v[128:129]
	v_lshl_add_u64 v[128:129], v[130:131], 0, v[128:129]
	v_lshlrev_b64 v[202:203], 2, v[198:199]
	v_lshl_add_u64 v[128:129], v[128:129], 0, v[202:203]
	v_or_b32_e32 v208, 16, v200
	global_load_dwordx4 v[216:219], v[128:129], off offset:16
	global_load_dwordx4 v[220:223], v[128:129], off
	global_load_dwordx4 v[224:227], v[128:129], off offset:528
	global_load_dwordx4 v[228:231], v[128:129], off offset:512
	v_ashrrev_i32_e32 v209, 31, v208
	v_add_u32_e32 v128, 0xffffe010, v200
	v_cmp_gt_i32_e32 vcc, s45, v208
	v_or_b32_e32 v206, 32, v200
	v_ashrrev_i32_e32 v207, 31, v206
	v_cndmask_b32_e32 v129, 0, v209, vcc
	v_cndmask_b32_e32 v128, v128, v208, vcc
	v_cndmask_b32_e32 v131, v132, v133, vcc
	v_cndmask_b32_e32 v130, v134, v135, vcc
	v_lshlrev_b64 v[128:129], 13, v[128:129]
	v_lshl_add_u64 v[128:129], v[130:131], 0, v[128:129]
	v_lshl_add_u64 v[128:129], v[128:129], 0, v[202:203]
	global_load_dwordx4 v[168:171], v[128:129], off offset:16
	global_load_dwordx4 v[172:175], v[128:129], off
	global_load_dwordx4 v[160:163], v[128:129], off offset:528
	global_load_dwordx4 v[164:167], v[128:129], off offset:512
	v_add_u32_e32 v128, 0xffffe020, v200
	v_cmp_gt_i32_e32 vcc, s45, v206
	v_or_b32_e32 v204, 48, v200
	v_ashrrev_i32_e32 v205, 31, v204
	v_cndmask_b32_e32 v129, 0, v207, vcc
	v_cndmask_b32_e32 v128, v128, v206, vcc
	v_cndmask_b32_e32 v131, v132, v133, vcc
	v_cndmask_b32_e32 v130, v134, v135, vcc
	v_lshlrev_b64 v[128:129], 13, v[128:129]
	v_lshl_add_u64 v[128:129], v[130:131], 0, v[128:129]
	v_lshl_add_u64 v[128:129], v[128:129], 0, v[202:203]
	global_load_dwordx4 v[152:155], v[128:129], off offset:16
	global_load_dwordx4 v[156:159], v[128:129], off
	global_load_dwordx4 v[144:147], v[128:129], off offset:528
	global_load_dwordx4 v[148:151], v[128:129], off offset:512
	v_add_u32_e32 v128, 0xffffe030, v200
	v_cmp_gt_i32_e32 vcc, s45, v204
	s_nop 1
	v_cndmask_b32_e32 v129, 0, v205, vcc
	v_cndmask_b32_e32 v128, v128, v204, vcc
	v_cndmask_b32_e32 v131, v132, v133, vcc
	v_cndmask_b32_e32 v130, v134, v135, vcc
	v_lshlrev_b64 v[128:129], 13, v[128:129]
	v_lshl_add_u64 v[128:129], v[130:131], 0, v[128:129]
	v_lshl_add_u64 v[132:133], v[128:129], 0, v[202:203]
	global_load_dwordx4 v[136:139], v[132:133], off offset:16
	global_load_dwordx4 v[140:143], v[132:133], off
	global_load_dwordx4 v[128:131], v[132:133], off offset:528
	s_nop 0
	global_load_dwordx4 v[132:135], v[132:133], off offset:512
	s_waitcnt vmcnt(0)
	v_pk_add_f32 v[124:125], v[124:125], v[220:221]
	v_pk_add_f32 v[126:127], v[126:127], v[222:223]
	v_mul_f32_e32 v222, v125, v125
	v_fmac_f32_e32 v222, v124, v124
	v_fmac_f32_e32 v222, v126, v126
	v_pk_add_f32 v[120:121], v[120:121], v[216:217]
	v_fmac_f32_e32 v222, v127, v127
	v_lshlrev_b64 v[232:233], 13, v[200:201]
	v_fmac_f32_e32 v222, v120, v120
	v_lshl_add_u64 v[232:233], s[28:29], 0, v[232:233]
	v_pk_add_f32 v[122:123], v[122:123], v[218:219]
	v_fmac_f32_e32 v222, v121, v121
	v_lshl_add_u64 v[232:233], v[232:233], 0, v[202:203]
	v_fmac_f32_e32 v222, v122, v122
	v_pk_add_f32 v[116:117], v[116:117], v[228:229]
	global_store_dwordx4 v[232:233], v[124:127], off
	global_store_dwordx4 v[232:233], v[120:123], off offset:16
	v_cvt_pk_bf16_f32 v219, v122, v123
	v_fmac_f32_e32 v222, v123, v123
	v_pk_add_f32 v[122:123], v[112:113], v[224:225]
	v_mul_f32_e32 v112, v117, v117
	v_pk_add_f32 v[118:119], v[118:119], v[230:231]
	v_fmac_f32_e32 v112, v116, v116
	v_fmac_f32_e32 v112, v118, v118
	v_fmac_f32_e32 v112, v119, v119
	v_cvt_pk_bf16_f32 v216, v124, v125
	v_pk_add_f32 v[124:125], v[114:115], v[226:227]
	v_fmac_f32_e32 v112, v122, v122
	v_and_b32_e32 v114, 64, v215
	v_fmac_f32_e32 v112, v123, v123
	v_xor_b32_e32 v113, 16, v215
	v_add_u32_e32 v115, 64, v114
	v_fmac_f32_e32 v112, v124, v124
	v_cmp_lt_i32_e32 vcc, v113, v115
	v_fmac_f32_e32 v112, v125, v125
	v_cvt_pk_bf16_f32 v218, v120, v121
	v_cndmask_b32_e32 v113, v215, v113, vcc
	v_add_f32_e32 v112, v222, v112
	v_lshlrev_b32_e32 v120, 2, v113
	ds_bpermute_b32 v113, v120, v112
	v_lshlrev_b64 v[220:221], 12, v[200:201]
	v_lshl_add_u64 v[220:221], s[0:1], 0, v[220:221]
	v_cvt_pk_bf16_f32 v217, v126, v127
	v_lshl_add_u64 v[220:221], v[198:199], 1, v[220:221]
	s_waitcnt lgkmcnt(0)
	v_add_f32_e32 v112, v112, v113
	v_xor_b32_e32 v113, 32, v215
	v_cmp_lt_i32_e32 vcc, v113, v115
	global_store_dwordx4 v[220:221], v[216:219], off
	global_store_dwordx4 v[232:233], v[116:119], off offset:512
	global_store_dwordx4 v[232:233], v[122:125], off offset:528
	v_cndmask_b32_e32 v113, v215, v113, vcc
	v_lshlrev_b32_e32 v121, 2, v113
	ds_bpermute_b32 v113, v121, v112
	v_cvt_pk_bf16_f32 v114, v116, v117
	v_cvt_pk_bf16_f32 v115, v118, v119
	v_cvt_pk_bf16_f32 v116, v122, v123
	v_cvt_pk_bf16_f32 v117, v124, v125
	global_store_dwordx4 v[220:221], v[114:117], off offset:256
	s_and_saveexec_b64 s[24:25], s[4:5]
	s_cbranch_execz .LBB0_871
	s_waitcnt lgkmcnt(0)
	v_add_f32_e32 v114, v112, v113
	s_lshl_b32 s26, s10, 2
	v_lshlrev_b64 v[112:113], 7, v[200:201]
	s_ashr_i32 s27, s26, 31
	v_lshl_add_u64 v[112:113], s[8:9], 0, v[112:113]
	v_lshl_add_u64 v[112:113], s[26:27], 2, v[112:113]
	s_lshl_b32 s12, s46, 2
	v_lshl_add_u64 v[112:113], v[112:113], 0, s[12:13]
	global_store_dword v[112:113], v114, off

.LBB0_885:
	s_waitcnt vmcnt(0)
	v_readlane_b32 s50, v238, 17
	v_readlane_b32 s48, v239, 26
	s_setprio 0
	s_cmpk_gt_u32 s33, 0xff
	v_readlane_b32 s51, v238, 18
	v_readlane_b32 s49, v239, 27
	s_cbranch_scc1 .LBB0_887
	s_barrier

.Lt5_sel:
	s_ashr_i32 s17, s16, 31
	s_bfe_i64 s[12:13], s[4:5], 0x100000
	s_lshl_b64 s[10:11], s[16:17], 20
	s_lshl_b64 s[12:13], s[12:13], 20
	v_readlane_b32 s14, v239, 7
	v_readlane_b32 s15, v239, 8
	s_add_u32 s20, s14, s12
	s_addc_u32 s21, s15, s13
	s_add_i32 s17, s25, 0
	s_add_i32 m0, s17, 0x10000
	v_mov_b32_e32 v133, 0
	global_load_lds_dwordx4 v132, s[20:21]
	s_add_i32 m0, s17, 0x12000
	s_add_u32 s18, s0, s10
	global_load_lds_dwordx4 v128, s[20:21]
	s_addc_u32 s19, s1, s11
	s_mov_b32 m0, s17
	s_add_i32 s27, s17, 0x2000
	global_load_lds_dwordx4 v134, s[18:19]
	s_mov_b32 m0, s27
	s_add_u32 s10, s20, 0x80000
	global_load_lds_dwordx4 v130, s[18:19]
	s_addc_u32 s11, s21, 0
	s_add_i32 m0, s17, 0x14000
	v_mov_b32_e32 v129, v133
	global_load_lds_dwordx4 v132, s[10:11]
	s_add_i32 m0, s17, 0x16000
	v_mov_b32_e32 v135, v133
	global_load_lds_dwordx4 v128, s[10:11]
	s_add_u32 s10, s18, 0x80000
	s_addc_u32 s11, s19, 0
	s_add_i32 s33, s17, 0x4000
	s_mov_b32 m0, s33
	s_add_i32 s35, s17, 0x6000
	global_load_lds_dwordx4 v134, s[10:11]
	s_mov_b32 m0, s35
	v_mov_b32_e32 v131, v133
	global_load_lds_dwordx4 v130, s[10:11]
	s_lshl_b32 s36, s97, 8
	v_lshl_add_u64 v[6:7], s[20:21], 0, v[132:133]
	v_lshl_add_u64 v[4:5], s[20:21], 0, v[128:129]
	v_lshl_add_u64 v[2:3], s[18:19], 0, v[134:135]
	s_cmp_lg_u32 s6, 1
	v_lshl_add_u64 v[0:1], s[18:19], 0, v[130:131]
	s_cbranch_scc1 .LBB0_939
	s_setprio 1
	s_barrier

.LBB0_943:
	ds_read_b128 v[146:149], v155
	ds_read_b128 v[160:163], v155 offset:1024
	ds_read_b128 v[164:167], v155 offset:2048
	ds_read_b128 v[168:171], v155 offset:3072
	s_add_u32 s20, s18, 0xfff80080
	s_addc_u32 s21, s19, -1
	s_cmp_eq_u32 s48, 28
	s_cselect_b32 s23, s11, s21
	s_cselect_b32 s22, s44, s20
	s_cselect_b32 s21, s9, s47
	s_cselect_b32 s20, s45, s46
	v_lshl_add_u64 v[150:151], s[18:19], 0, v[138:139]
	s_add_i32 m0, s17, 0xc000
	ds_read_b128 v[172:175], v156
	ds_read_b128 v[182:185], v156 offset:1024
	ds_read_b128 v[186:189], v156 offset:2048
	ds_read_b128 v[190:193], v156 offset:3072
	ds_read_b128 v[194:197], v156 offset:4096
	ds_read_b128 v[198:201], v156 offset:5120
	ds_read_b128 v[202:205], v156 offset:6144
	ds_read_b128 v[206:209], v156 offset:7168
	global_load_lds_dwordx4 v[150:151], off
	v_lshl_add_u64 v[150:151], s[18:19], 0, v[140:141]
	s_add_i32 m0, s17, 0xe000
	s_nop 0
	global_load_lds_dwordx4 v[150:151], off
	s_waitcnt lgkmcnt(8)
	s_barrier
	s_waitcnt lgkmcnt(0)
	s_waitcnt lgkmcnt(0)
	v_mfma_f32_16x16x32_bf16 v[124:127], v[146:149], v[172:175], v[124:127]
	v_mfma_f32_16x16x32_bf16 v[120:123], v[164:167], v[172:175], v[120:123]
	v_mfma_f32_16x16x32_bf16 v[108:111], v[146:149], v[186:189], v[108:111]
	v_mfma_f32_16x16x32_bf16 v[104:107], v[164:167], v[186:189], v[104:107]
	v_mfma_f32_16x16x32_bf16 v[92:95], v[146:149], v[194:197], v[92:95]
	v_mfma_f32_16x16x32_bf16 v[88:91], v[164:167], v[194:197], v[88:91]
	v_mfma_f32_16x16x32_bf16 v[76:79], v[146:149], v[202:205], v[76:79]
	v_mfma_f32_16x16x32_bf16 v[72:75], v[164:167], v[202:205], v[72:75]
	v_mfma_f32_16x16x32_bf16 v[124:127], v[160:163], v[182:185], v[124:127]
	v_mfma_f32_16x16x32_bf16 v[120:123], v[168:171], v[182:185], v[120:123]
	v_mfma_f32_16x16x32_bf16 v[108:111], v[160:163], v[190:193], v[108:111]
	v_mfma_f32_16x16x32_bf16 v[104:107], v[168:171], v[190:193], v[104:107]
	v_mfma_f32_16x16x32_bf16 v[92:95], v[160:163], v[198:201], v[92:95]
	v_mfma_f32_16x16x32_bf16 v[88:91], v[168:171], v[198:201], v[88:91]
	v_mfma_f32_16x16x32_bf16 v[76:79], v[160:163], v[206:209], v[76:79]
	v_mfma_f32_16x16x32_bf16 v[72:75], v[168:171], v[206:209], v[72:75]
	s_barrier
	s_add_i32 s34, s39, s25
	v_lshl_add_u64 v[150:151], s[20:21], 0, v[132:133]
	s_mov_b32 m0, s34
	ds_read_b128 v[210:213], v157
	ds_read_b128 v[214:217], v157 offset:1024
	ds_read_b128 v[218:221], v157 offset:2048
	ds_read_b128 v[222:225], v157 offset:3072
	global_load_lds_dwordx4 v[150:151], off
	v_lshl_add_u64 v[226:227], s[20:21], 0, v[128:129]
	s_add_i32 m0, s34, 0x2000
	s_nop 0
	global_load_lds_dwordx4 v[226:227], off
	s_barrier
	s_waitcnt lgkmcnt(0)
	s_waitcnt lgkmcnt(0)
	v_mfma_f32_16x16x32_bf16 v[116:119], v[210:213], v[172:175], v[116:119]
	v_mfma_f32_16x16x32_bf16 v[112:115], v[218:221], v[172:175], v[112:115]
	v_mfma_f32_16x16x32_bf16 v[100:103], v[210:213], v[186:189], v[100:103]
	v_mfma_f32_16x16x32_bf16 v[96:99], v[218:221], v[186:189], v[96:99]
	v_mfma_f32_16x16x32_bf16 v[84:87], v[210:213], v[194:197], v[84:87]
	v_mfma_f32_16x16x32_bf16 v[80:83], v[218:221], v[194:197], v[80:83]
	v_mfma_f32_16x16x32_bf16 v[68:71], v[210:213], v[202:205], v[68:71]
	v_mfma_f32_16x16x32_bf16 v[64:67], v[218:221], v[202:205], v[64:67]
	v_mfma_f32_16x16x32_bf16 v[116:119], v[214:217], v[182:185], v[116:119]
	v_mfma_f32_16x16x32_bf16 v[112:115], v[222:225], v[182:185], v[112:115]
	v_mfma_f32_16x16x32_bf16 v[100:103], v[214:217], v[190:193], v[100:103]
	v_mfma_f32_16x16x32_bf16 v[96:99], v[222:225], v[190:193], v[96:99]
	v_mfma_f32_16x16x32_bf16 v[84:87], v[214:217], v[198:201], v[84:87]
	v_mfma_f32_16x16x32_bf16 v[80:83], v[222:225], v[198:201], v[80:83]
	v_mfma_f32_16x16x32_bf16 v[68:71], v[214:217], v[206:209], v[68:71]
	v_mfma_f32_16x16x32_bf16 v[64:67], v[222:225], v[206:209], v[64:67]
	s_mov_b32 m0, s17
	v_lshl_add_u64 v[228:229], s[22:23], 0, v[134:135]
	s_barrier
	ds_read_b128 v[172:175], v156 offset:16384
	ds_read_b128 v[182:185], v156 offset:17408
	ds_read_b128 v[186:189], v156 offset:18432
	ds_read_b128 v[190:193], v156 offset:19456
	ds_read_b128 v[194:197], v156 offset:20480
	ds_read_b128 v[198:201], v156 offset:21504
	ds_read_b128 v[202:205], v156 offset:22528
	ds_read_b128 v[206:209], v156 offset:23552
	global_load_lds_dwordx4 v[228:229], off
	v_lshl_add_u64 v[230:231], s[22:23], 0, v[130:131]
	s_mov_b32 m0, s27
	s_nop 0
	global_load_lds_dwordx4 v[230:231], off
	s_barrier
	s_waitcnt lgkmcnt(0)
	s_waitcnt lgkmcnt(0)
	v_mfma_f32_16x16x32_bf16 v[60:63], v[146:149], v[172:175], v[60:63]
	v_mfma_f32_16x16x32_bf16 v[56:59], v[164:167], v[172:175], v[56:59]
	v_mfma_f32_16x16x32_bf16 v[44:47], v[146:149], v[186:189], v[44:47]
	v_mfma_f32_16x16x32_bf16 v[40:43], v[164:167], v[186:189], v[40:43]
	v_mfma_f32_16x16x32_bf16 v[28:31], v[146:149], v[194:197], v[28:31]
	v_mfma_f32_16x16x32_bf16 v[24:27], v[164:167], v[194:197], v[24:27]
	v_mfma_f32_16x16x32_bf16 v[12:15], v[146:149], v[202:205], v[12:15]
	v_mfma_f32_16x16x32_bf16 v[8:11], v[164:167], v[202:205], v[8:11]
	v_mfma_f32_16x16x32_bf16 v[60:63], v[160:163], v[182:185], v[60:63]
	v_mfma_f32_16x16x32_bf16 v[56:59], v[168:171], v[182:185], v[56:59]
	v_mfma_f32_16x16x32_bf16 v[44:47], v[160:163], v[190:193], v[44:47]
	v_mfma_f32_16x16x32_bf16 v[40:43], v[168:171], v[190:193], v[40:43]
	v_mfma_f32_16x16x32_bf16 v[28:31], v[160:163], v[198:201], v[28:31]
	v_mfma_f32_16x16x32_bf16 v[24:27], v[168:171], v[198:201], v[24:27]
	v_mfma_f32_16x16x32_bf16 v[12:15], v[160:163], v[206:209], v[12:15]
	v_mfma_f32_16x16x32_bf16 v[8:11], v[168:171], v[206:209], v[8:11]
	s_barrier
	s_add_u32 s50, s20, 0x80000
	s_addc_u32 s51, s21, 0
	s_add_i32 s34, s40, s25
	v_lshl_add_u64 v[146:147], s[50:51], 0, v[132:133]
	s_mov_b32 m0, s34
	s_nop 0
	global_load_lds_dwordx4 v[146:147], off
	v_lshl_add_u64 v[146:147], s[50:51], 0, v[128:129]
	s_add_i32 m0, s34, 0x2000
	s_nop 0
	global_load_lds_dwordx4 v[146:147], off
	s_waitcnt vmcnt(6)
	s_barrier
	v_mfma_f32_16x16x32_bf16 v[52:55], v[210:213], v[172:175], v[52:55]
	v_mfma_f32_16x16x32_bf16 v[48:51], v[218:221], v[172:175], v[48:51]
	v_mfma_f32_16x16x32_bf16 v[36:39], v[210:213], v[186:189], v[36:39]
	v_mfma_f32_16x16x32_bf16 v[32:35], v[218:221], v[186:189], v[32:35]
	v_mfma_f32_16x16x32_bf16 v[20:23], v[210:213], v[194:197], v[20:23]
	v_mfma_f32_16x16x32_bf16 v[16:19], v[218:221], v[194:197], v[16:19]
	v_mfma_f32_16x16x32_bf16 v[4:7], v[210:213], v[202:205], v[4:7]
	v_mfma_f32_16x16x32_bf16 v[0:3], v[218:221], v[202:205], v[0:3]
	v_mfma_f32_16x16x32_bf16 v[52:55], v[214:217], v[182:185], v[52:55]
	v_mfma_f32_16x16x32_bf16 v[48:51], v[222:225], v[182:185], v[48:51]
	v_mfma_f32_16x16x32_bf16 v[36:39], v[214:217], v[190:193], v[36:39]
	v_mfma_f32_16x16x32_bf16 v[32:35], v[222:225], v[190:193], v[32:35]
	v_mfma_f32_16x16x32_bf16 v[20:23], v[214:217], v[198:201], v[20:23]
	v_mfma_f32_16x16x32_bf16 v[16:19], v[222:225], v[198:201], v[16:19]
	v_mfma_f32_16x16x32_bf16 v[4:7], v[214:217], v[206:209], v[4:7]
	v_mfma_f32_16x16x32_bf16 v[0:3], v[222:225], v[206:209], v[0:3]
	s_add_i32 s34, 0, 0x18000
	v_add_u32_e32 v168, s34, v153
	s_barrier
	ds_read_b128 v[146:149], v168
	ds_read_b128 v[160:163], v168 offset:1024
	ds_read_b128 v[164:167], v168 offset:2048
	ds_read_b128 v[168:171], v168 offset:3072
	s_add_u32 s22, s22, 0x80000
	s_addc_u32 s23, s23, 0
	s_mov_b32 m0, s33
	v_lshl_add_u64 v[210:211], s[22:23], 0, v[134:135]
	ds_read_b128 v[172:175], v156 offset:32768
	ds_read_b128 v[182:185], v156 offset:33792
	ds_read_b128 v[186:189], v156 offset:34816
	ds_read_b128 v[190:193], v156 offset:35840
	ds_read_b128 v[194:197], v156 offset:36864
	ds_read_b128 v[198:201], v156 offset:37888
	ds_read_b128 v[202:205], v156 offset:38912
	ds_read_b128 v[206:209], v156 offset:39936
	global_load_lds_dwordx4 v[210:211], off
	v_lshl_add_u64 v[210:211], s[22:23], 0, v[130:131]
	s_mov_b32 m0, s35
	s_nop 0
	global_load_lds_dwordx4 v[210:211], off
	s_waitcnt lgkmcnt(8)
	s_barrier
	s_waitcnt lgkmcnt(0)
	s_waitcnt lgkmcnt(0)
	v_mfma_f32_16x16x32_bf16 v[124:127], v[146:149], v[172:175], v[124:127]
	v_mfma_f32_16x16x32_bf16 v[120:123], v[164:167], v[172:175], v[120:123]
	v_mfma_f32_16x16x32_bf16 v[108:111], v[146:149], v[186:189], v[108:111]
	v_mfma_f32_16x16x32_bf16 v[104:107], v[164:167], v[186:189], v[104:107]
	v_mfma_f32_16x16x32_bf16 v[92:95], v[146:149], v[194:197], v[92:95]
	v_mfma_f32_16x16x32_bf16 v[88:91], v[164:167], v[194:197], v[88:91]
	v_mfma_f32_16x16x32_bf16 v[76:79], v[146:149], v[202:205], v[76:79]
	v_mfma_f32_16x16x32_bf16 v[72:75], v[164:167], v[202:205], v[72:75]
	v_mfma_f32_16x16x32_bf16 v[124:127], v[160:163], v[182:185], v[124:127]
	v_mfma_f32_16x16x32_bf16 v[120:123], v[168:171], v[182:185], v[120:123]
	v_mfma_f32_16x16x32_bf16 v[108:111], v[160:163], v[190:193], v[108:111]
	v_mfma_f32_16x16x32_bf16 v[104:107], v[168:171], v[190:193], v[104:107]
	v_mfma_f32_16x16x32_bf16 v[92:95], v[160:163], v[198:201], v[92:95]
	v_mfma_f32_16x16x32_bf16 v[88:91], v[168:171], v[198:201], v[88:91]
	v_mfma_f32_16x16x32_bf16 v[76:79], v[160:163], v[206:209], v[76:79]
	v_mfma_f32_16x16x32_bf16 v[72:75], v[168:171], v[206:209], v[72:75]
	s_barrier
	s_add_i32 s22, 0, 0x1c000
	s_add_i32 s23, s34, s25
	v_add_u32_e32 v177, s22, v153
	v_lshl_add_u64 v[150:151], v[150:151], 0, s[6:7]
	s_mov_b32 m0, s23
	ds_read_b128 v[210:213], v177
	ds_read_b128 v[214:217], v177 offset:1024
	ds_read_b128 v[218:221], v177 offset:2048
	ds_read_b128 v[222:225], v177 offset:3072
	global_load_lds_dwordx4 v[150:151], off
	v_lshl_add_u64 v[150:151], v[226:227], 0, s[6:7]
	s_add_i32 m0, s23, 0x2000
	s_nop 0
	global_load_lds_dwordx4 v[150:151], off
	s_barrier
	s_waitcnt lgkmcnt(0)
	s_waitcnt lgkmcnt(0)
	v_mfma_f32_16x16x32_bf16 v[116:119], v[210:213], v[172:175], v[116:119]
	v_mfma_f32_16x16x32_bf16 v[112:115], v[218:221], v[172:175], v[112:115]
	v_mfma_f32_16x16x32_bf16 v[100:103], v[210:213], v[186:189], v[100:103]
	v_mfma_f32_16x16x32_bf16 v[96:99], v[218:221], v[186:189], v[96:99]
	v_mfma_f32_16x16x32_bf16 v[84:87], v[210:213], v[194:197], v[84:87]
	v_mfma_f32_16x16x32_bf16 v[80:83], v[218:221], v[194:197], v[80:83]
	v_mfma_f32_16x16x32_bf16 v[68:71], v[210:213], v[202:205], v[68:71]
	v_mfma_f32_16x16x32_bf16 v[64:67], v[218:221], v[202:205], v[64:67]
	v_mfma_f32_16x16x32_bf16 v[116:119], v[214:217], v[182:185], v[116:119]
	v_mfma_f32_16x16x32_bf16 v[112:115], v[222:225], v[182:185], v[112:115]
	v_mfma_f32_16x16x32_bf16 v[100:103], v[214:217], v[190:193], v[100:103]
	v_mfma_f32_16x16x32_bf16 v[96:99], v[222:225], v[190:193], v[96:99]
	v_mfma_f32_16x16x32_bf16 v[84:87], v[214:217], v[198:201], v[84:87]
	v_mfma_f32_16x16x32_bf16 v[80:83], v[222:225], v[198:201], v[80:83]
	v_mfma_f32_16x16x32_bf16 v[68:71], v[214:217], v[206:209], v[68:71]
	v_mfma_f32_16x16x32_bf16 v[64:67], v[222:225], v[206:209], v[64:67]
	s_mov_b32 m0, s37
	v_lshl_add_u64 v[150:151], v[228:229], 0, s[6:7]
	s_barrier
	ds_read_b128 v[172:175], v156 offset:49152
	ds_read_b128 v[182:185], v156 offset:50176
	ds_read_b128 v[186:189], v156 offset:51200
	ds_read_b128 v[190:193], v156 offset:52224
	ds_read_b128 v[194:197], v156 offset:53248
	ds_read_b128 v[198:201], v156 offset:54272
	ds_read_b128 v[202:205], v156 offset:55296
	ds_read_b128 v[206:209], v156 offset:56320
	global_load_lds_dwordx4 v[150:151], off
	v_lshl_add_u64 v[150:151], v[230:231], 0, s[6:7]
	s_mov_b32 m0, s38
	s_nop 0
	global_load_lds_dwordx4 v[150:151], off
	s_barrier
	s_waitcnt lgkmcnt(0)
	s_waitcnt lgkmcnt(0)
	v_mfma_f32_16x16x32_bf16 v[60:63], v[146:149], v[172:175], v[60:63]
	v_mfma_f32_16x16x32_bf16 v[56:59], v[164:167], v[172:175], v[56:59]
	v_mfma_f32_16x16x32_bf16 v[44:47], v[146:149], v[186:189], v[44:47]
	v_mfma_f32_16x16x32_bf16 v[40:43], v[164:167], v[186:189], v[40:43]
	v_mfma_f32_16x16x32_bf16 v[28:31], v[146:149], v[194:197], v[28:31]
	v_mfma_f32_16x16x32_bf16 v[24:27], v[164:167], v[194:197], v[24:27]
	v_mfma_f32_16x16x32_bf16 v[12:15], v[146:149], v[202:205], v[12:15]
	v_mfma_f32_16x16x32_bf16 v[8:11], v[164:167], v[202:205], v[8:11]
	v_mfma_f32_16x16x32_bf16 v[60:63], v[160:163], v[182:185], v[60:63]
	v_mfma_f32_16x16x32_bf16 v[56:59], v[168:171], v[182:185], v[56:59]
	v_mfma_f32_16x16x32_bf16 v[44:47], v[160:163], v[190:193], v[44:47]
	v_mfma_f32_16x16x32_bf16 v[40:43], v[168:171], v[190:193], v[40:43]
	v_mfma_f32_16x16x32_bf16 v[28:31], v[160:163], v[198:201], v[28:31]
	v_mfma_f32_16x16x32_bf16 v[24:27], v[168:171], v[198:201], v[24:27]
	v_mfma_f32_16x16x32_bf16 v[12:15], v[160:163], v[206:209], v[12:15]
	v_mfma_f32_16x16x32_bf16 v[8:11], v[168:171], v[206:209], v[8:11]
	s_barrier
	s_add_u32 s20, s20, 0x80080
	s_addc_u32 s21, s21, 0
	s_add_i32 s22, s22, s25
	v_lshl_add_u64 v[146:147], s[20:21], 0, v[132:133]
	s_mov_b32 m0, s22
	s_nop 0
	global_load_lds_dwordx4 v[146:147], off
	v_lshl_add_u64 v[146:147], s[20:21], 0, v[128:129]
	s_add_i32 m0, s22, 0x2000
	s_nop 0
	global_load_lds_dwordx4 v[146:147], off
	s_waitcnt vmcnt(6)
	s_barrier
	v_mfma_f32_16x16x32_bf16 v[52:55], v[210:213], v[172:175], v[52:55]
	v_mfma_f32_16x16x32_bf16 v[48:51], v[218:221], v[172:175], v[48:51]
	v_mfma_f32_16x16x32_bf16 v[36:39], v[210:213], v[186:189], v[36:39]
	v_mfma_f32_16x16x32_bf16 v[32:35], v[218:221], v[186:189], v[32:35]
	v_mfma_f32_16x16x32_bf16 v[20:23], v[210:213], v[194:197], v[20:23]
	v_mfma_f32_16x16x32_bf16 v[16:19], v[218:221], v[194:197], v[16:19]
	v_mfma_f32_16x16x32_bf16 v[4:7], v[210:213], v[202:205], v[4:7]
	v_mfma_f32_16x16x32_bf16 v[0:3], v[218:221], v[202:205], v[0:3]
	v_mfma_f32_16x16x32_bf16 v[52:55], v[214:217], v[182:185], v[52:55]
	v_mfma_f32_16x16x32_bf16 v[48:51], v[222:225], v[182:185], v[48:51]
	v_mfma_f32_16x16x32_bf16 v[36:39], v[214:217], v[190:193], v[36:39]
	v_mfma_f32_16x16x32_bf16 v[32:35], v[222:225], v[190:193], v[32:35]
	v_mfma_f32_16x16x32_bf16 v[20:23], v[214:217], v[198:201], v[20:23]
	v_mfma_f32_16x16x32_bf16 v[16:19], v[222:225], v[198:201], v[16:19]
	v_mfma_f32_16x16x32_bf16 v[4:7], v[214:217], v[206:209], v[4:7]
	v_mfma_f32_16x16x32_bf16 v[0:3], v[222:225], v[206:209], v[0:3]
	s_add_i32 s48, s48, 2
	s_add_u32 s18, s18, 0x100
	s_addc_u32 s19, s19, 0
	s_add_u32 s46, s46, 0x100
	s_addc_u32 s47, s47, 0
	s_cmp_gt_u32 s48, 29
	s_barrier
	s_cbranch_scc0 .LBB0_943
	v_and_b32_e32 v148, 64, v158
	v_xor_b32_e32 v147, 16, v158
	v_add_u32_e32 v148, 64, v148
	v_cmp_lt_i32_e32 vcc, v147, v148
	v_lshl_add_u32 v146, s16, 8, v152
	v_lshl_or_b32 v166, s43, 8, v154
	v_cndmask_b32_e32 v147, v158, v147, vcc
	v_lshlrev_b32_e32 v160, 2, v147
	v_xor_b32_e32 v147, 32, v158
	v_cmp_lt_i32_e32 vcc, v147, v148
	v_ashrrev_i32_e32 v167, 31, v166
	s_mov_b32 s43, s8
	v_cndmask_b32_e32 v147, v158, v147, vcc
	v_lshlrev_b32_e32 v161, 2, v147
	v_ashrrev_i32_e32 v147, 31, v146
	v_lshlrev_b64 v[148:149], 7, v[146:147]
	v_lshl_add_u64 v[162:163], v[136:137], 0, v[148:149]
	global_load_dwordx4 v[148:151], v[162:163], off
	s_nop 0
	global_load_dwordx4 v[162:165], v[162:163], off offset:16
	s_mov_b32 s16, s10
	s_mov_b64 s[20:21], s[14:15]
	s_waitcnt vmcnt(0)
	v_pk_add_f32 v[148:149], v[148:149], v[162:163]
	v_pk_add_f32 v[150:151], v[150:151], v[164:165]
	v_add_f32_e32 v147, v148, v149
	v_add_f32_e32 v147, v150, v147
	v_add_f32_e32 v147, v151, v147
	ds_bpermute_b32 v148, v160, v147
	v_lshlrev_b64 v[150:151], 1, v[166:167]
	s_waitcnt lgkmcnt(0)
	v_add_f32_e32 v147, v147, v148
	ds_bpermute_b32 v148, v161, v147
	s_waitcnt lgkmcnt(0)
	v_add_f32_e32 v147, v147, v148
	v_fmamk_f32 v147, v147, 0x3a000000, v159
	v_cmp_gt_f32_e32 vcc, s41, v147
	v_mul_f32_e32 v148, 0x4b800000, v147
	s_nop 0
	v_cndmask_b32_e32 v147, v147, v148, vcc
	v_rsq_f32_e32 v147, v147
	s_nop 0
	v_mul_f32_e32 v148, 0x45800000, v147
	v_cndmask_b32_e32 v162, v147, v148, vcc
	v_mov_b64_e32 v[148:149], s[30:31]
	v_mad_i64_i32 v[164:165], s[18:19], v146, s42, v[148:149]
	v_pk_mul_f32 v[126:127], v[126:127], v[162:163] op_sel_hi:[1,0]
	v_pk_mul_f32 v[124:125], v[124:125], v[162:163] op_sel_hi:[1,0]
	v_pk_mul_f32 v[166:167], v[122:123], v[162:163] op_sel_hi:[1,0]
	v_pk_mul_f32 v[122:123], v[120:121], v[162:163] op_sel_hi:[1,0]
	v_lshl_add_u64 v[164:165], v[164:165], 0, v[150:151]
	v_cvt_pk_bf16_f32 v120, v124, v125
	v_cvt_pk_bf16_f32 v121, v126, v127
	v_cvt_pk_bf16_f32 v122, v122, v123
	v_cvt_pk_bf16_f32 v123, v166, v167
	global_store_dwordx4 v[164:165], v[120:123], off
	v_pk_mul_f32 v[118:119], v[118:119], v[162:163] op_sel_hi:[1,0]
	v_pk_mul_f32 v[116:117], v[116:117], v[162:163] op_sel_hi:[1,0]
	v_pk_mul_f32 v[120:121], v[114:115], v[162:163] op_sel_hi:[1,0]
	v_pk_mul_f32 v[114:115], v[112:113], v[162:163] op_sel_hi:[1,0]
	v_cvt_pk_bf16_f32 v112, v116, v117
	v_cvt_pk_bf16_f32 v114, v114, v115
	v_cvt_pk_bf16_f32 v115, v120, v121
	v_or_b32_e32 v120, 16, v146
	v_cvt_pk_bf16_f32 v113, v118, v119
	v_ashrrev_i32_e32 v121, 31, v120
	global_store_dwordx4 v[164:165], v[112:115], off offset:256
	s_nop 1
	v_lshlrev_b64 v[112:113], 7, v[120:121]
	v_lshl_add_u64 v[116:117], v[136:137], 0, v[112:113]
	global_load_dwordx4 v[112:115], v[116:117], off
	s_nop 0
	global_load_dwordx4 v[116:119], v[116:117], off offset:16
	s_waitcnt vmcnt(0)
	v_pk_add_f32 v[112:113], v[112:113], v[116:117]
	v_pk_add_f32 v[114:115], v[114:115], v[118:119]
	v_add_f32_e32 v112, v112, v113
	v_add_f32_e32 v112, v114, v112
	v_add_f32_e32 v112, v115, v112
	ds_bpermute_b32 v113, v160, v112
	v_mad_i64_i32 v[114:115], s[18:19], v120, s42, v[148:149]
	v_lshl_add_u64 v[114:115], v[114:115], 0, v[150:151]
	s_waitcnt lgkmcnt(0)
	v_add_f32_e32 v112, v112, v113
	ds_bpermute_b32 v113, v161, v112
	s_waitcnt lgkmcnt(0)
	v_add_f32_e32 v112, v112, v113
	v_fmamk_f32 v112, v112, 0x3a000000, v159
	v_cmp_gt_f32_e32 vcc, s41, v112
	v_mul_f32_e32 v113, 0x4b800000, v112
	s_nop 0
	v_cndmask_b32_e32 v112, v112, v113, vcc
	v_rsq_f32_e32 v112, v112
	s_nop 0
	v_mul_f32_e32 v113, 0x45800000, v112
	v_cndmask_b32_e32 v112, v112, v113, vcc
	v_pk_mul_f32 v[110:111], v[110:111], v[112:113] op_sel_hi:[1,0]
	v_pk_mul_f32 v[108:109], v[108:109], v[112:113] op_sel_hi:[1,0]
	v_pk_mul_f32 v[116:117], v[106:107], v[112:113] op_sel_hi:[1,0]
	v_pk_mul_f32 v[106:107], v[104:105], v[112:113] op_sel_hi:[1,0]
	v_cvt_pk_bf16_f32 v104, v108, v109
	v_cvt_pk_bf16_f32 v105, v110, v111
	v_cvt_pk_bf16_f32 v106, v106, v107
	v_cvt_pk_bf16_f32 v107, v116, v117
	global_store_dwordx4 v[114:115], v[104:107], off
	v_pk_mul_f32 v[102:103], v[102:103], v[112:113] op_sel_hi:[1,0]
	v_pk_mul_f32 v[100:101], v[100:101], v[112:113] op_sel_hi:[1,0]
	v_pk_mul_f32 v[104:105], v[98:99], v[112:113] op_sel_hi:[1,0]
	v_pk_mul_f32 v[98:99], v[96:97], v[112:113] op_sel_hi:[1,0]
	v_cvt_pk_bf16_f32 v96, v100, v101
	v_cvt_pk_bf16_f32 v98, v98, v99
	v_cvt_pk_bf16_f32 v99, v104, v105
	v_or_b32_e32 v104, 32, v146
	v_cvt_pk_bf16_f32 v97, v102, v103
	v_ashrrev_i32_e32 v105, 31, v104
	global_store_dwordx4 v[114:115], v[96:99], off offset:256
	s_nop 1
	v_lshlrev_b64 v[96:97], 7, v[104:105]
	v_lshl_add_u64 v[100:101], v[136:137], 0, v[96:97]
	global_load_dwordx4 v[96:99], v[100:101], off
	s_nop 0
	global_load_dwordx4 v[100:103], v[100:101], off offset:16
	s_waitcnt vmcnt(0)
	v_pk_add_f32 v[96:97], v[96:97], v[100:101]
	v_pk_add_f32 v[98:99], v[98:99], v[102:103]
	v_add_f32_e32 v96, v96, v97
	v_add_f32_e32 v96, v98, v96
	v_add_f32_e32 v96, v99, v96
	ds_bpermute_b32 v97, v160, v96
	v_mad_i64_i32 v[98:99], s[18:19], v104, s42, v[148:149]
	v_lshl_add_u64 v[98:99], v[98:99], 0, v[150:151]
	s_waitcnt lgkmcnt(0)
	v_add_f32_e32 v96, v96, v97
	ds_bpermute_b32 v97, v161, v96
	s_waitcnt lgkmcnt(0)
	v_add_f32_e32 v96, v96, v97
	v_fmamk_f32 v96, v96, 0x3a000000, v159
	v_cmp_gt_f32_e32 vcc, s41, v96
	v_mul_f32_e32 v97, 0x4b800000, v96
	s_nop 0
	v_cndmask_b32_e32 v96, v96, v97, vcc
	v_rsq_f32_e32 v96, v96
	s_nop 0
	v_mul_f32_e32 v97, 0x45800000, v96
	v_cndmask_b32_e32 v96, v96, v97, vcc
	v_pk_mul_f32 v[94:95], v[94:95], v[96:97] op_sel_hi:[1,0]
	v_pk_mul_f32 v[92:93], v[92:93], v[96:97] op_sel_hi:[1,0]
	v_pk_mul_f32 v[100:101], v[90:91], v[96:97] op_sel_hi:[1,0]
	v_pk_mul_f32 v[90:91], v[88:89], v[96:97] op_sel_hi:[1,0]
	v_cvt_pk_bf16_f32 v88, v92, v93
	v_cvt_pk_bf16_f32 v89, v94, v95
	v_cvt_pk_bf16_f32 v90, v90, v91
	v_cvt_pk_bf16_f32 v91, v100, v101
	global_store_dwordx4 v[98:99], v[88:91], off
	v_pk_mul_f32 v[86:87], v[86:87], v[96:97] op_sel_hi:[1,0]
	v_pk_mul_f32 v[84:85], v[84:85], v[96:97] op_sel_hi:[1,0]
	v_pk_mul_f32 v[88:89], v[82:83], v[96:97] op_sel_hi:[1,0]
	v_pk_mul_f32 v[82:83], v[80:81], v[96:97] op_sel_hi:[1,0]
	v_cvt_pk_bf16_f32 v80, v84, v85
	v_cvt_pk_bf16_f32 v82, v82, v83
	v_cvt_pk_bf16_f32 v83, v88, v89
	v_or_b32_e32 v88, 48, v146
	v_cvt_pk_bf16_f32 v81, v86, v87
	v_ashrrev_i32_e32 v89, 31, v88
	global_store_dwordx4 v[98:99], v[80:83], off offset:256
	s_nop 1
	v_lshlrev_b64 v[80:81], 7, v[88:89]
	v_lshl_add_u64 v[84:85], v[136:137], 0, v[80:81]
	global_load_dwordx4 v[80:83], v[84:85], off
	s_nop 0
	global_load_dwordx4 v[84:87], v[84:85], off offset:16
	s_waitcnt vmcnt(0)
	v_pk_add_f32 v[80:81], v[80:81], v[84:85]
	v_pk_add_f32 v[82:83], v[82:83], v[86:87]
	v_add_f32_e32 v80, v80, v81
	v_add_f32_e32 v80, v82, v80
	v_add_f32_e32 v80, v83, v80
	ds_bpermute_b32 v81, v160, v80
	v_mad_i64_i32 v[82:83], s[18:19], v88, s42, v[148:149]
	v_lshl_add_u64 v[82:83], v[82:83], 0, v[150:151]
	s_waitcnt lgkmcnt(0)
	v_add_f32_e32 v80, v80, v81
	ds_bpermute_b32 v81, v161, v80
	s_waitcnt lgkmcnt(0)
	v_add_f32_e32 v80, v80, v81
	v_fmamk_f32 v80, v80, 0x3a000000, v159
	v_cmp_gt_f32_e32 vcc, s41, v80
	v_mul_f32_e32 v81, 0x4b800000, v80
	s_nop 0
	v_cndmask_b32_e32 v80, v80, v81, vcc
	v_rsq_f32_e32 v80, v80
	s_nop 0
	v_mul_f32_e32 v81, 0x45800000, v80
	v_cndmask_b32_e32 v80, v80, v81, vcc
	v_pk_mul_f32 v[78:79], v[78:79], v[80:81] op_sel_hi:[1,0]
	v_pk_mul_f32 v[76:77], v[76:77], v[80:81] op_sel_hi:[1,0]
	v_pk_mul_f32 v[84:85], v[74:75], v[80:81] op_sel_hi:[1,0]
	v_pk_mul_f32 v[74:75], v[72:73], v[80:81] op_sel_hi:[1,0]
	v_cvt_pk_bf16_f32 v72, v76, v77
	v_cvt_pk_bf16_f32 v73, v78, v79
	v_cvt_pk_bf16_f32 v74, v74, v75
	v_cvt_pk_bf16_f32 v75, v84, v85
	global_store_dwordx4 v[82:83], v[72:75], off
	v_pk_mul_f32 v[70:71], v[70:71], v[80:81] op_sel_hi:[1,0]
	v_pk_mul_f32 v[68:69], v[68:69], v[80:81] op_sel_hi:[1,0]
	v_pk_mul_f32 v[72:73], v[66:67], v[80:81] op_sel_hi:[1,0]
	v_pk_mul_f32 v[66:67], v[64:65], v[80:81] op_sel_hi:[1,0]
	v_cvt_pk_bf16_f32 v64, v68, v69
	v_cvt_pk_bf16_f32 v66, v66, v67
	v_cvt_pk_bf16_f32 v67, v72, v73
	v_add_u32_e32 v72, 0x80, v146
	v_cvt_pk_bf16_f32 v65, v70, v71
	v_ashrrev_i32_e32 v73, 31, v72
	global_store_dwordx4 v[82:83], v[64:67], off offset:256
	s_nop 1
	v_lshlrev_b64 v[64:65], 7, v[72:73]
	v_lshl_add_u64 v[68:69], v[136:137], 0, v[64:65]
	global_load_dwordx4 v[64:67], v[68:69], off
	s_nop 0
	global_load_dwordx4 v[68:71], v[68:69], off offset:16
	s_waitcnt vmcnt(0)
	v_pk_add_f32 v[64:65], v[64:65], v[68:69]
	v_pk_add_f32 v[66:67], v[66:67], v[70:71]
	v_add_f32_e32 v64, v64, v65
	v_add_f32_e32 v64, v66, v64
	v_add_f32_e32 v64, v67, v64
	ds_bpermute_b32 v65, v160, v64
	v_mad_i64_i32 v[66:67], s[18:19], v72, s42, v[148:149]
	v_lshl_add_u64 v[66:67], v[66:67], 0, v[150:151]
	s_waitcnt lgkmcnt(0)
	v_add_f32_e32 v64, v64, v65
	ds_bpermute_b32 v65, v161, v64
	s_waitcnt lgkmcnt(0)
	v_add_f32_e32 v64, v64, v65
	v_fmamk_f32 v64, v64, 0x3a000000, v159
	v_cmp_gt_f32_e32 vcc, s41, v64
	v_mul_f32_e32 v65, 0x4b800000, v64
	s_nop 0
	v_cndmask_b32_e32 v64, v64, v65, vcc
	v_rsq_f32_e32 v64, v64
	s_nop 0
	v_mul_f32_e32 v65, 0x45800000, v64
	v_cndmask_b32_e32 v64, v64, v65, vcc
	v_pk_mul_f32 v[62:63], v[62:63], v[64:65] op_sel_hi:[1,0]
	v_pk_mul_f32 v[60:61], v[60:61], v[64:65] op_sel_hi:[1,0]
	v_pk_mul_f32 v[68:69], v[58:59], v[64:65] op_sel_hi:[1,0]
	v_pk_mul_f32 v[58:59], v[56:57], v[64:65] op_sel_hi:[1,0]
	v_cvt_pk_bf16_f32 v56, v60, v61
	v_cvt_pk_bf16_f32 v57, v62, v63
	v_cvt_pk_bf16_f32 v58, v58, v59
	v_cvt_pk_bf16_f32 v59, v68, v69
	global_store_dwordx4 v[66:67], v[56:59], off
	v_pk_mul_f32 v[54:55], v[54:55], v[64:65] op_sel_hi:[1,0]
	v_pk_mul_f32 v[52:53], v[52:53], v[64:65] op_sel_hi:[1,0]
	v_pk_mul_f32 v[56:57], v[50:51], v[64:65] op_sel_hi:[1,0]
	v_pk_mul_f32 v[50:51], v[48:49], v[64:65] op_sel_hi:[1,0]
	v_cvt_pk_bf16_f32 v48, v52, v53
	v_cvt_pk_bf16_f32 v50, v50, v51
	v_cvt_pk_bf16_f32 v51, v56, v57
	v_add_u32_e32 v56, 0x90, v146
	v_cvt_pk_bf16_f32 v49, v54, v55
	v_ashrrev_i32_e32 v57, 31, v56
	global_store_dwordx4 v[66:67], v[48:51], off offset:256
	s_nop 1
	v_lshlrev_b64 v[48:49], 7, v[56:57]
	v_lshl_add_u64 v[52:53], v[136:137], 0, v[48:49]
	global_load_dwordx4 v[48:51], v[52:53], off
	s_nop 0
	global_load_dwordx4 v[52:55], v[52:53], off offset:16
	s_waitcnt vmcnt(0)
	v_pk_add_f32 v[48:49], v[48:49], v[52:53]
	v_pk_add_f32 v[50:51], v[50:51], v[54:55]
	v_add_f32_e32 v48, v48, v49
	v_add_f32_e32 v48, v50, v48
	v_add_f32_e32 v48, v51, v48
	ds_bpermute_b32 v49, v160, v48
	v_mad_i64_i32 v[50:51], s[18:19], v56, s42, v[148:149]
	v_lshl_add_u64 v[50:51], v[50:51], 0, v[150:151]
	s_waitcnt lgkmcnt(0)
	v_add_f32_e32 v48, v48, v49
	ds_bpermute_b32 v49, v161, v48
	s_waitcnt lgkmcnt(0)
	v_add_f32_e32 v48, v48, v49
	v_fmamk_f32 v48, v48, 0x3a000000, v159
	v_cmp_gt_f32_e32 vcc, s41, v48
	v_mul_f32_e32 v49, 0x4b800000, v48
	s_nop 0
	v_cndmask_b32_e32 v48, v48, v49, vcc
	v_rsq_f32_e32 v48, v48
	s_nop 0
	v_mul_f32_e32 v49, 0x45800000, v48
	v_cndmask_b32_e32 v48, v48, v49, vcc
	v_pk_mul_f32 v[46:47], v[46:47], v[48:49] op_sel_hi:[1,0]
	v_pk_mul_f32 v[44:45], v[44:45], v[48:49] op_sel_hi:[1,0]
	v_pk_mul_f32 v[52:53], v[42:43], v[48:49] op_sel_hi:[1,0]
	v_pk_mul_f32 v[42:43], v[40:41], v[48:49] op_sel_hi:[1,0]
	v_cvt_pk_bf16_f32 v40, v44, v45
	v_cvt_pk_bf16_f32 v41, v46, v47
	v_cvt_pk_bf16_f32 v42, v42, v43
	v_cvt_pk_bf16_f32 v43, v52, v53
	global_store_dwordx4 v[50:51], v[40:43], off
	v_pk_mul_f32 v[38:39], v[38:39], v[48:49] op_sel_hi:[1,0]
	v_pk_mul_f32 v[36:37], v[36:37], v[48:49] op_sel_hi:[1,0]
	v_pk_mul_f32 v[40:41], v[34:35], v[48:49] op_sel_hi:[1,0]
	v_pk_mul_f32 v[34:35], v[32:33], v[48:49] op_sel_hi:[1,0]
	v_cvt_pk_bf16_f32 v32, v36, v37
	v_cvt_pk_bf16_f32 v34, v34, v35
	v_cvt_pk_bf16_f32 v35, v40, v41
	v_add_u32_e32 v40, 0xa0, v146
	v_cvt_pk_bf16_f32 v33, v38, v39
	v_ashrrev_i32_e32 v41, 31, v40
	global_store_dwordx4 v[50:51], v[32:35], off offset:256
	s_nop 1
	v_lshlrev_b64 v[32:33], 7, v[40:41]
	v_lshl_add_u64 v[36:37], v[136:137], 0, v[32:33]
	global_load_dwordx4 v[32:35], v[36:37], off
	s_nop 0
	global_load_dwordx4 v[36:39], v[36:37], off offset:16
	s_waitcnt vmcnt(0)
	v_pk_add_f32 v[32:33], v[32:33], v[36:37]
	v_pk_add_f32 v[34:35], v[34:35], v[38:39]
	v_add_f32_e32 v32, v32, v33
	v_add_f32_e32 v32, v34, v32
	v_add_f32_e32 v32, v35, v32
	ds_bpermute_b32 v33, v160, v32
	v_mad_i64_i32 v[34:35], s[18:19], v40, s42, v[148:149]
	v_lshl_add_u64 v[34:35], v[34:35], 0, v[150:151]
	s_waitcnt lgkmcnt(0)
	v_add_f32_e32 v32, v32, v33
	ds_bpermute_b32 v33, v161, v32
	s_waitcnt lgkmcnt(0)
	v_add_f32_e32 v32, v32, v33
	v_fmamk_f32 v32, v32, 0x3a000000, v159
	v_cmp_gt_f32_e32 vcc, s41, v32
	v_mul_f32_e32 v33, 0x4b800000, v32
	s_nop 0
	v_cndmask_b32_e32 v32, v32, v33, vcc
	v_rsq_f32_e32 v32, v32
	s_nop 0
	v_mul_f32_e32 v33, 0x45800000, v32
	v_cndmask_b32_e32 v32, v32, v33, vcc
	v_pk_mul_f32 v[30:31], v[30:31], v[32:33] op_sel_hi:[1,0]
	v_pk_mul_f32 v[28:29], v[28:29], v[32:33] op_sel_hi:[1,0]
	v_pk_mul_f32 v[36:37], v[26:27], v[32:33] op_sel_hi:[1,0]
	v_pk_mul_f32 v[26:27], v[24:25], v[32:33] op_sel_hi:[1,0]
	v_cvt_pk_bf16_f32 v24, v28, v29
	v_cvt_pk_bf16_f32 v25, v30, v31
	v_cvt_pk_bf16_f32 v26, v26, v27
	v_cvt_pk_bf16_f32 v27, v36, v37
	global_store_dwordx4 v[34:35], v[24:27], off
	v_pk_mul_f32 v[22:23], v[22:23], v[32:33] op_sel_hi:[1,0]
	v_pk_mul_f32 v[20:21], v[20:21], v[32:33] op_sel_hi:[1,0]
	v_pk_mul_f32 v[24:25], v[18:19], v[32:33] op_sel_hi:[1,0]
	v_pk_mul_f32 v[18:19], v[16:17], v[32:33] op_sel_hi:[1,0]
	v_cvt_pk_bf16_f32 v16, v20, v21
	v_cvt_pk_bf16_f32 v18, v18, v19
	v_cvt_pk_bf16_f32 v19, v24, v25
	v_add_u32_e32 v24, 0xb0, v146
	v_cvt_pk_bf16_f32 v17, v22, v23
	v_ashrrev_i32_e32 v25, 31, v24
	global_store_dwordx4 v[34:35], v[16:19], off offset:256
	s_nop 1
	v_lshlrev_b64 v[16:17], 7, v[24:25]
	v_lshl_add_u64 v[20:21], v[136:137], 0, v[16:17]
	global_load_dwordx4 v[16:19], v[20:21], off
	s_nop 0
	global_load_dwordx4 v[20:23], v[20:21], off offset:16
	s_waitcnt vmcnt(0)
	v_pk_add_f32 v[16:17], v[16:17], v[20:21]
	v_pk_add_f32 v[18:19], v[18:19], v[22:23]
	v_add_f32_e32 v16, v16, v17
	v_add_f32_e32 v16, v18, v16
	v_add_f32_e32 v16, v19, v16
	ds_bpermute_b32 v17, v160, v16
	v_mad_i64_i32 v[18:19], s[18:19], v24, s42, v[148:149]
	v_lshl_add_u64 v[18:19], v[18:19], 0, v[150:151]
	s_mov_b64 s[18:19], s[12:13]
	s_waitcnt lgkmcnt(0)
	v_add_f32_e32 v16, v16, v17
	ds_bpermute_b32 v17, v161, v16
	s_waitcnt lgkmcnt(0)
	v_add_f32_e32 v16, v16, v17
	v_fmamk_f32 v16, v16, 0x3a000000, v159
	v_cmp_gt_f32_e32 vcc, s41, v16
	v_mul_f32_e32 v17, 0x4b800000, v16
	s_nop 0
	v_cndmask_b32_e32 v16, v16, v17, vcc
	v_rsq_f32_e32 v16, v16
	s_nop 0
	v_mul_f32_e32 v17, 0x45800000, v16
	v_cndmask_b32_e32 v16, v16, v17, vcc
	v_pk_mul_f32 v[14:15], v[14:15], v[16:17] op_sel_hi:[1,0]
	v_pk_mul_f32 v[12:13], v[12:13], v[16:17] op_sel_hi:[1,0]
	v_pk_mul_f32 v[20:21], v[10:11], v[16:17] op_sel_hi:[1,0]
	v_pk_mul_f32 v[10:11], v[8:9], v[16:17] op_sel_hi:[1,0]
	v_cvt_pk_bf16_f32 v8, v12, v13
	v_cvt_pk_bf16_f32 v9, v14, v15
	v_cvt_pk_bf16_f32 v10, v10, v11
	v_cvt_pk_bf16_f32 v11, v20, v21
	global_store_dwordx4 v[18:19], v[8:11], off
	v_pk_mul_f32 v[6:7], v[6:7], v[16:17] op_sel_hi:[1,0]
	v_pk_mul_f32 v[4:5], v[4:5], v[16:17] op_sel_hi:[1,0]
	v_pk_mul_f32 v[8:9], v[2:3], v[16:17] op_sel_hi:[1,0]
	v_pk_mul_f32 v[2:3], v[0:1], v[16:17] op_sel_hi:[1,0]
	v_cvt_pk_bf16_f32 v0, v4, v5
	v_cvt_pk_bf16_f32 v1, v6, v7
	v_cvt_pk_bf16_f32 v2, v2, v3
	v_cvt_pk_bf16_f32 v3, v8, v9
	s_and_b64 vcc, exec, s[4:5]
	global_store_dwordx4 v[18:19], v[0:3], off offset:256
	s_cbranch_vccz .LBB0_940
	s_waitcnt vmcnt(0)
	s_setprio 0
	s_cmpk_gt_u32 s24, 0xff
	s_cbranch_scc1 .LBB0_947
	s_barrier

.LBB0_1069:
	s_or_b64 exec, exec, s[0:1]
	v_mov_b32_e32 v16, v176
	s_waitcnt lgkmcnt(0)
	s_barrier
	s_cmpk_lt_i32 s2, 0x240
	v_readfirstlane_b32 s18, v16
	s_cbranch_scc0 .LBB0_1089
	v_lshlrev_b32_e32 v0, 4, v16
	v_add_u32_e32 v1, 0x2000, v0
	v_ashrrev_i32_e32 v2, 31, v1
	v_lshrrev_b32_e32 v2, 22, v2
	v_add_u32_e32 v2, v1, v2
	v_ashrrev_i32_e32 v8, 10, v2
	v_mul_i32_i24_e32 v2, 0x400, v8
	v_sub_u32_e32 v1, v1, v2
	v_lshrrev_b32_e32 v2, 4, v1
	v_bitop3_b32 v1, v2, v1, 32 bitop3:0x6c
	v_ashrrev_i32_e32 v2, 31, v1
	v_lshrrev_b32_e32 v2, 26, v2
	v_add_u32_e32 v2, v1, v2
	v_lshlrev_b32_e32 v3, 3, v8
	v_ashrrev_i32_e32 v9, 6, v2
	v_and_b32_e32 v3, -16, v3
	v_add_u32_e32 v3, v9, v3
	v_and_b32_e32 v4, 3, v9
	s_mov_b32 s5, 0x7fffe0
	v_lshrrev_b32_e32 v5, 2, v3
	v_lshlrev_b32_e32 v6, 1, v3
	v_and_b32_e32 v2, 0xc0, v2
	v_and_or_b32 v4, v3, s5, v4
	v_and_b32_e32 v5, 4, v5
	v_and_b32_e32 v6, 24, v6
	v_sub_u32_e32 v1, v1, v2
	v_mov_b32_e32 v2, 1
	v_or3_b32 v4, v4, v5, v6
	v_lshlrev_b32_e32 v5, 5, v8
	v_ashrrev_i16_sdwa v1, v2, sext(v1) dst_sel:DWORD dst_unused:UNUSED_PAD src0_sel:DWORD src1_sel:BYTE_0
	s_movk_i32 s4, 0x1600
	v_and_b32_e32 v10, 32, v5
	v_bfe_i32 v11, v1, 0, 16
	v_mul_u32_u24_e32 v4, 0x1600, v4
	v_add_u32_e32 v1, v10, v11
	v_mul_lo_u32 v3, v3, s4
	v_add_lshl_u32 v128, v4, v1, 1
	v_add_lshl_u32 v130, v1, v3, 1
	v_bfe_i32 v1, v16, 27, 1
	v_lshrrev_b32_e32 v1, 22, v1
	v_add_u32_e32 v1, v0, v1
	v_and_b32_e32 v1, 0xfffffc00, v1
	v_sub_u32_e32 v0, v0, v1
	v_lshrrev_b32_e32 v1, 4, v0
	v_bitop3_b32 v1, v1, v0, 32 bitop3:0x6c
	v_ashrrev_i32_e32 v0, 31, v0
	v_lshrrev_b32_e32 v0, 26, v0
	v_add_u32_e32 v0, v1, v0
	v_ashrrev_i32_e32 v12, 6, v0
	v_ashrrev_i32_e32 v0, 31, v16
	v_lshrrev_b32_e32 v0, 26, v0
	v_add_u32_e32 v0, v16, v0
	v_ashrrev_i32_e32 v13, 6, v0
	v_lshlrev_b32_e32 v0, 3, v13
	v_and_b32_e32 v0, -16, v0
	v_add_u32_e32 v0, v12, v0
	v_and_b32_e32 v3, 3, v12
	v_and_or_b32 v3, v0, s5, v3
	s_ashr_i32 s1, s18, 6
	s_ashr_i32 s0, s18, 8
	s_lshl_b32 s19, s1, 10
	v_lshrrev_b32_e32 v4, 2, v0
	v_lshlrev_b32_e32 v5, 1, v0
	v_and_b32_e32 v4, 4, v4
	v_and_b32_e32 v5, 24, v5
	s_and_b32 s5, s2, 7
	s_mul_i32 s100, s5, 50
	s_add_i32 s101, s100, 48
	s_add_i32 s100, s100, -2
	s_max_i32 s100, s100, 0
	s_min_i32 s101, s101, 0x18c

	s_mul_i32 s6, s100, 0x5d2
	s_lshr_b32 s6, s6, 16
	s_mul_i32 s7, s6, 44
	s_sub_i32 s8, s100, s7
	s_add_i32 s7, s7, 44
	s_min_i32 s7, s7, s101
	s_sub_i32 s7, s7, s100
	s_cmp_eq_u32 s7, 44
	s_cselect_b32 s7, 42, s7
	s_add_i32 s100, s100, s7

	s_lshl_b32 s98, s7, 1
	s_add_i32 s98, s98, -4
	s_cmp_lg_u32 s8, 0
	s_cselect_b32 s43, 1, 0
	s_lshr_b32 s9, s2, 6
	s_lshl_b32 s6, s6, 2
	s_add_i32 s42, s6, s9
	s_bfe_u32 s44, s2, 0x30003
	s_lshl_b32 s7, s8, 8
	s_mov_b32 s8, 0
	v_or3_b32 v3, v3, v4, v5
	v_lshlrev_b32_e32 v4, 5, v13
	s_mul_i32 s9, s44, 0x2c0000
	v_and_b32_e32 v14, 32, v4
	v_mul_i32_i24_e32 v4, 64, v12
	s_ashr_i32 s10, s9, 31
	v_readlane_b32 s12, v238, 23
	v_sub_u32_e32 v1, v1, v4
	v_readlane_b32 s13, v238, 24
	s_add_u32 s9, s12, s9
	v_ashrrev_i16_sdwa v1, v2, sext(v1) dst_sel:DWORD dst_unused:UNUSED_PAD src0_sel:DWORD src1_sel:BYTE_0
	s_addc_u32 s10, s13, s10
	v_bfe_i32 v15, v1, 0, 16
	s_add_u32 s12, s9, s7
	v_mul_u32_u24_e32 v3, 0x1600, v3
	v_add_u32_e32 v1, v14, v15
	s_addc_u32 s13, s10, s8
	s_add_i32 s21, s19, 0
	v_add_lshl_u32 v132, v3, v1, 1
	s_add_i32 m0, s21, 0x10000
	s_mul_i32 s6, s42, 0x2c0000
	global_load_lds_dwordx4 v132, s[12:13]
	s_add_i32 m0, s21, 0x12000
	v_readlane_b32 s9, v239, 9
	s_mul_hi_i32 s5, s42, 0x2c0000
	s_add_u32 s6, s9, s6
	v_readlane_b32 s9, v239, 10
	s_addc_u32 s5, s9, s5
	v_mul_lo_u32 v0, v0, s4
	s_add_u32 s10, s6, s7
	v_add_lshl_u32 v134, v1, v0, 1
	global_load_lds_dwordx4 v128, s[12:13]
	s_addc_u32 s11, s5, s8
	s_mov_b32 m0, s21
	s_add_i32 s22, s21, 0x2000
	global_load_lds_dwordx4 v134, s[10:11]
	s_mov_b32 m0, s22
	s_add_u32 s6, s12, 0x160000
	global_load_lds_dwordx4 v130, s[10:11]
	s_addc_u32 s7, s13, 0
	s_add_i32 m0, s21, 0x14000
	v_mov_b32_e32 v133, 0
	global_load_lds_dwordx4 v132, s[6:7]
	s_add_i32 m0, s21, 0x16000
	v_mov_b32_e32 v129, v133
	global_load_lds_dwordx4 v128, s[6:7]
	s_add_u32 s6, s10, 0x160000
	s_addc_u32 s7, s11, 0
	s_add_i32 s23, s21, 0x4000
	s_mov_b32 m0, s23
	s_add_i32 s24, s21, 0x6000
	global_load_lds_dwordx4 v134, s[6:7]
	s_mov_b32 m0, s24
	v_mov_b32_e32 v135, v133
	global_load_lds_dwordx4 v130, s[6:7]
	v_mov_b32_e32 v131, v133
	s_movk_i32 s25, 0x2000
	s_mov_b32 s26, 0
	v_lshl_add_u64 v[6:7], s[12:13], 0, v[132:133]
	v_lshl_add_u64 v[4:5], s[12:13], 0, v[128:129]
	v_lshl_add_u64 v[2:3], s[10:11], 0, v[134:135]
	v_lshl_add_u64 v[0:1], s[10:11], 0, v[130:131]
	s_cmp_lg_u32 s0, 1
	s_mov_b32 s5, 0x16000
	s_cbranch_scc1 .LBB0_1072
	s_setprio 1
	s_barrier

.LBB0_1081:
	ds_read_b128 v[144:147], v159
	ds_read_b128 v[148:151], v159 offset:1024
	ds_read_b128 v[152:155], v159 offset:2048
	ds_read_b128 v[162:165], v159 offset:3072
	s_add_u32 s12, s10, 0x100
	s_addc_u32 s13, s11, 0
	s_cmp_eq_u32 s47, s98
	s_cselect_b32 s17, s7, s13
	s_cselect_b32 s16, s6, s12
	s_cselect_b32 s15, s9, s46
	s_cselect_b32 s14, s8, s45
	v_lshl_add_u64 v[174:175], s[10:11], 0, v[136:137]
	s_add_i32 m0, s21, 0xc000
	ds_read_b128 v[166:169], v160
	ds_read_b128 v[170:173], v160 offset:1024
	ds_read_b128 v[182:185], v160 offset:2048
	ds_read_b128 v[186:189], v160 offset:3072
	ds_read_b128 v[190:193], v160 offset:4096
	ds_read_b128 v[194:197], v160 offset:5120
	ds_read_b128 v[198:201], v160 offset:6144
	ds_read_b128 v[202:205], v160 offset:7168
	global_load_lds_dwordx4 v[174:175], off
	v_lshl_add_u64 v[174:175], s[10:11], 0, v[138:139]
	s_add_i32 m0, s21, 0xe000
	s_nop 0
	global_load_lds_dwordx4 v[174:175], off
	s_waitcnt lgkmcnt(8)
	s_barrier
	s_waitcnt lgkmcnt(0)
	s_waitcnt lgkmcnt(0)
	v_mfma_f32_16x16x32_bf16 v[124:127], v[144:147], v[166:169], v[124:127]
	v_mfma_f32_16x16x32_bf16 v[120:123], v[152:155], v[166:169], v[120:123]
	v_mfma_f32_16x16x32_bf16 v[112:115], v[144:147], v[182:185], v[112:115]
	v_mfma_f32_16x16x32_bf16 v[104:107], v[152:155], v[182:185], v[104:107]
	v_mfma_f32_16x16x32_bf16 v[96:99], v[144:147], v[190:193], v[96:99]
	v_mfma_f32_16x16x32_bf16 v[88:91], v[152:155], v[190:193], v[88:91]
	v_mfma_f32_16x16x32_bf16 v[80:83], v[144:147], v[198:201], v[80:83]
	v_mfma_f32_16x16x32_bf16 v[72:75], v[152:155], v[198:201], v[72:75]
	v_mfma_f32_16x16x32_bf16 v[124:127], v[148:151], v[170:173], v[124:127]
	v_mfma_f32_16x16x32_bf16 v[120:123], v[162:165], v[170:173], v[120:123]
	v_mfma_f32_16x16x32_bf16 v[112:115], v[148:151], v[186:189], v[112:115]
	v_mfma_f32_16x16x32_bf16 v[104:107], v[162:165], v[186:189], v[104:107]
	v_mfma_f32_16x16x32_bf16 v[96:99], v[148:151], v[194:197], v[96:99]
	v_mfma_f32_16x16x32_bf16 v[88:91], v[162:165], v[194:197], v[88:91]
	v_mfma_f32_16x16x32_bf16 v[80:83], v[148:151], v[202:205], v[80:83]
	v_mfma_f32_16x16x32_bf16 v[72:75], v[162:165], v[202:205], v[72:75]
	s_barrier
	s_add_i32 s10, s37, s19
	v_lshl_add_u64 v[174:175], s[14:15], 0, v[132:133]
	s_mov_b32 m0, s10
	ds_read_b128 v[206:209], v161
	ds_read_b128 v[210:213], v161 offset:1024
	ds_read_b128 v[214:217], v161 offset:2048
	ds_read_b128 v[218:221], v161 offset:3072
	global_load_lds_dwordx4 v[174:175], off
	v_lshl_add_u64 v[222:223], s[14:15], 0, v[128:129]
	s_add_i32 m0, s10, 0x2000
	s_nop 0
	global_load_lds_dwordx4 v[222:223], off
	s_barrier
	s_waitcnt lgkmcnt(0)
	s_waitcnt lgkmcnt(0)
	v_mfma_f32_16x16x32_bf16 v[116:119], v[206:209], v[166:169], v[116:119]
	v_mfma_f32_16x16x32_bf16 v[108:111], v[214:217], v[166:169], v[108:111]
	v_mfma_f32_16x16x32_bf16 v[100:103], v[206:209], v[182:185], v[100:103]
	v_mfma_f32_16x16x32_bf16 v[92:95], v[214:217], v[182:185], v[92:95]
	v_mfma_f32_16x16x32_bf16 v[84:87], v[206:209], v[190:193], v[84:87]
	v_mfma_f32_16x16x32_bf16 v[76:79], v[214:217], v[190:193], v[76:79]
	v_mfma_f32_16x16x32_bf16 v[68:71], v[206:209], v[198:201], v[68:71]
	v_mfma_f32_16x16x32_bf16 v[64:67], v[214:217], v[198:201], v[64:67]
	v_mfma_f32_16x16x32_bf16 v[116:119], v[210:213], v[170:173], v[116:119]
	v_mfma_f32_16x16x32_bf16 v[108:111], v[218:221], v[170:173], v[108:111]
	v_mfma_f32_16x16x32_bf16 v[100:103], v[210:213], v[186:189], v[100:103]
	v_mfma_f32_16x16x32_bf16 v[92:95], v[218:221], v[186:189], v[92:95]
	v_mfma_f32_16x16x32_bf16 v[84:87], v[210:213], v[194:197], v[84:87]
	v_mfma_f32_16x16x32_bf16 v[76:79], v[218:221], v[194:197], v[76:79]
	v_mfma_f32_16x16x32_bf16 v[68:71], v[210:213], v[202:205], v[68:71]
	v_mfma_f32_16x16x32_bf16 v[64:67], v[218:221], v[202:205], v[64:67]
	s_mov_b32 m0, s21
	v_lshl_add_u64 v[224:225], s[16:17], 0, v[134:135]
	s_barrier
	ds_read_b128 v[166:169], v160 offset:16384
	ds_read_b128 v[170:173], v160 offset:17408
	ds_read_b128 v[182:185], v160 offset:18432
	ds_read_b128 v[186:189], v160 offset:19456
	ds_read_b128 v[190:193], v160 offset:20480
	ds_read_b128 v[194:197], v160 offset:21504
	ds_read_b128 v[198:201], v160 offset:22528
	ds_read_b128 v[202:205], v160 offset:23552
	global_load_lds_dwordx4 v[224:225], off
	v_lshl_add_u64 v[226:227], s[16:17], 0, v[130:131]
	s_mov_b32 m0, s22
	s_nop 0
	global_load_lds_dwordx4 v[226:227], off
	s_barrier
	s_waitcnt lgkmcnt(0)
	s_waitcnt lgkmcnt(0)
	v_mfma_f32_16x16x32_bf16 v[60:63], v[144:147], v[166:169], v[60:63]
	v_mfma_f32_16x16x32_bf16 v[56:59], v[152:155], v[166:169], v[56:59]
	v_mfma_f32_16x16x32_bf16 v[48:51], v[144:147], v[182:185], v[48:51]
	v_mfma_f32_16x16x32_bf16 v[40:43], v[152:155], v[182:185], v[40:43]
	v_mfma_f32_16x16x32_bf16 v[32:35], v[144:147], v[190:193], v[32:35]
	v_mfma_f32_16x16x32_bf16 v[24:27], v[152:155], v[190:193], v[24:27]
	v_mfma_f32_16x16x32_bf16 v[16:19], v[144:147], v[198:201], v[16:19]
	v_mfma_f32_16x16x32_bf16 v[8:11], v[152:155], v[198:201], v[8:11]
	v_mfma_f32_16x16x32_bf16 v[60:63], v[148:151], v[170:173], v[60:63]
	v_mfma_f32_16x16x32_bf16 v[56:59], v[162:165], v[170:173], v[56:59]
	v_mfma_f32_16x16x32_bf16 v[48:51], v[148:151], v[186:189], v[48:51]
	v_mfma_f32_16x16x32_bf16 v[40:43], v[162:165], v[186:189], v[40:43]
	v_mfma_f32_16x16x32_bf16 v[32:35], v[148:151], v[194:197], v[32:35]
	v_mfma_f32_16x16x32_bf16 v[24:27], v[162:165], v[194:197], v[24:27]
	v_mfma_f32_16x16x32_bf16 v[16:19], v[148:151], v[202:205], v[16:19]
	v_mfma_f32_16x16x32_bf16 v[8:11], v[162:165], v[202:205], v[8:11]
	s_barrier
	s_add_u32 s10, s14, 0x160000
	s_addc_u32 s11, s15, 0
	s_add_i32 s34, s38, s19
	v_lshl_add_u64 v[144:145], s[10:11], 0, v[132:133]
	s_mov_b32 m0, s34
	s_nop 0
	global_load_lds_dwordx4 v[144:145], off
	v_lshl_add_u64 v[144:145], s[10:11], 0, v[128:129]
	s_add_i32 m0, s34, 0x2000
	s_nop 0
	global_load_lds_dwordx4 v[144:145], off
	s_waitcnt vmcnt(6)
	s_barrier
	v_mfma_f32_16x16x32_bf16 v[52:55], v[206:209], v[166:169], v[52:55]
	v_mfma_f32_16x16x32_bf16 v[44:47], v[214:217], v[166:169], v[44:47]
	v_mfma_f32_16x16x32_bf16 v[36:39], v[206:209], v[182:185], v[36:39]
	v_mfma_f32_16x16x32_bf16 v[28:31], v[214:217], v[182:185], v[28:31]
	v_mfma_f32_16x16x32_bf16 v[20:23], v[206:209], v[190:193], v[20:23]
	v_mfma_f32_16x16x32_bf16 v[12:15], v[214:217], v[190:193], v[12:15]
	v_mfma_f32_16x16x32_bf16 v[4:7], v[206:209], v[198:201], v[4:7]
	v_mfma_f32_16x16x32_bf16 v[0:3], v[214:217], v[198:201], v[0:3]
	v_mfma_f32_16x16x32_bf16 v[52:55], v[210:213], v[170:173], v[52:55]
	v_mfma_f32_16x16x32_bf16 v[44:47], v[218:221], v[170:173], v[44:47]
	v_mfma_f32_16x16x32_bf16 v[36:39], v[210:213], v[186:189], v[36:39]
	v_mfma_f32_16x16x32_bf16 v[28:31], v[218:221], v[186:189], v[28:31]
	v_mfma_f32_16x16x32_bf16 v[20:23], v[210:213], v[194:197], v[20:23]
	v_mfma_f32_16x16x32_bf16 v[12:15], v[218:221], v[194:197], v[12:15]
	v_mfma_f32_16x16x32_bf16 v[4:7], v[210:213], v[202:205], v[4:7]
	v_mfma_f32_16x16x32_bf16 v[0:3], v[218:221], v[202:205], v[0:3]
	s_add_i32 s34, 0, 0x18000
	v_add_u32_e32 v162, s34, v157
	s_barrier
	ds_read_b128 v[144:147], v162
	ds_read_b128 v[148:151], v162 offset:1024
	ds_read_b128 v[152:155], v162 offset:2048
	ds_read_b128 v[162:165], v162 offset:3072
	s_add_u32 s10, s16, 0x160000
	s_addc_u32 s11, s17, 0
	s_mov_b32 m0, s23
	v_lshl_add_u64 v[206:207], s[10:11], 0, v[134:135]
	ds_read_b128 v[166:169], v160 offset:32768
	ds_read_b128 v[170:173], v160 offset:33792
	ds_read_b128 v[182:185], v160 offset:34816
	ds_read_b128 v[186:189], v160 offset:35840
	ds_read_b128 v[190:193], v160 offset:36864
	ds_read_b128 v[194:197], v160 offset:37888
	ds_read_b128 v[198:201], v160 offset:38912
	ds_read_b128 v[202:205], v160 offset:39936
	global_load_lds_dwordx4 v[206:207], off
	v_lshl_add_u64 v[206:207], s[10:11], 0, v[130:131]
	s_mov_b32 m0, s24
	s_nop 0
	global_load_lds_dwordx4 v[206:207], off
	s_waitcnt lgkmcnt(8)
	s_barrier
	s_waitcnt lgkmcnt(0)
	s_waitcnt lgkmcnt(0)
	v_mfma_f32_16x16x32_bf16 v[124:127], v[144:147], v[166:169], v[124:127]
	v_mfma_f32_16x16x32_bf16 v[120:123], v[152:155], v[166:169], v[120:123]
	v_mfma_f32_16x16x32_bf16 v[112:115], v[144:147], v[182:185], v[112:115]
	v_mfma_f32_16x16x32_bf16 v[104:107], v[152:155], v[182:185], v[104:107]
	v_mfma_f32_16x16x32_bf16 v[96:99], v[144:147], v[190:193], v[96:99]
	v_mfma_f32_16x16x32_bf16 v[88:91], v[152:155], v[190:193], v[88:91]
	v_mfma_f32_16x16x32_bf16 v[80:83], v[144:147], v[198:201], v[80:83]
	v_mfma_f32_16x16x32_bf16 v[72:75], v[152:155], v[198:201], v[72:75]
	v_mfma_f32_16x16x32_bf16 v[124:127], v[148:151], v[170:173], v[124:127]
	v_mfma_f32_16x16x32_bf16 v[120:123], v[162:165], v[170:173], v[120:123]
	v_mfma_f32_16x16x32_bf16 v[112:115], v[148:151], v[186:189], v[112:115]
	v_mfma_f32_16x16x32_bf16 v[104:107], v[162:165], v[186:189], v[104:107]
	v_mfma_f32_16x16x32_bf16 v[96:99], v[148:151], v[194:197], v[96:99]
	v_mfma_f32_16x16x32_bf16 v[88:91], v[162:165], v[194:197], v[88:91]
	v_mfma_f32_16x16x32_bf16 v[80:83], v[148:151], v[202:205], v[80:83]
	v_mfma_f32_16x16x32_bf16 v[72:75], v[162:165], v[202:205], v[72:75]
	s_barrier
	s_add_i32 s16, 0, 0x1c000
	s_add_i32 s10, s34, s19
	v_add_u32_e32 v177, s16, v157
	v_lshl_add_u64 v[174:175], v[174:175], 0, s[0:1]
	s_mov_b32 m0, s10
	ds_read_b128 v[206:209], v177
	ds_read_b128 v[210:213], v177 offset:1024
	ds_read_b128 v[214:217], v177 offset:2048
	ds_read_b128 v[218:221], v177 offset:3072
	global_load_lds_dwordx4 v[174:175], off
	v_lshl_add_u64 v[174:175], v[222:223], 0, s[0:1]
	s_add_i32 m0, s10, 0x2000
	s_nop 0
	global_load_lds_dwordx4 v[174:175], off
	s_barrier
	s_waitcnt lgkmcnt(0)
	s_waitcnt lgkmcnt(0)
	v_mfma_f32_16x16x32_bf16 v[116:119], v[206:209], v[166:169], v[116:119]
	v_mfma_f32_16x16x32_bf16 v[108:111], v[214:217], v[166:169], v[108:111]
	v_mfma_f32_16x16x32_bf16 v[100:103], v[206:209], v[182:185], v[100:103]
	v_mfma_f32_16x16x32_bf16 v[92:95], v[214:217], v[182:185], v[92:95]
	v_mfma_f32_16x16x32_bf16 v[84:87], v[206:209], v[190:193], v[84:87]
	v_mfma_f32_16x16x32_bf16 v[76:79], v[214:217], v[190:193], v[76:79]
	v_mfma_f32_16x16x32_bf16 v[68:71], v[206:209], v[198:201], v[68:71]
	v_mfma_f32_16x16x32_bf16 v[64:67], v[214:217], v[198:201], v[64:67]
	v_mfma_f32_16x16x32_bf16 v[116:119], v[210:213], v[170:173], v[116:119]
	v_mfma_f32_16x16x32_bf16 v[108:111], v[218:221], v[170:173], v[108:111]
	v_mfma_f32_16x16x32_bf16 v[100:103], v[210:213], v[186:189], v[100:103]
	v_mfma_f32_16x16x32_bf16 v[92:95], v[218:221], v[186:189], v[92:95]
	v_mfma_f32_16x16x32_bf16 v[84:87], v[210:213], v[194:197], v[84:87]
	v_mfma_f32_16x16x32_bf16 v[76:79], v[218:221], v[194:197], v[76:79]
	v_mfma_f32_16x16x32_bf16 v[68:71], v[210:213], v[202:205], v[68:71]
	v_mfma_f32_16x16x32_bf16 v[64:67], v[218:221], v[202:205], v[64:67]
	s_mov_b32 m0, s35
	v_lshl_add_u64 v[174:175], v[224:225], 0, s[0:1]
	s_barrier
	ds_read_b128 v[166:169], v160 offset:49152
	ds_read_b128 v[170:173], v160 offset:50176
	ds_read_b128 v[182:185], v160 offset:51200
	ds_read_b128 v[186:189], v160 offset:52224
	ds_read_b128 v[190:193], v160 offset:53248
	ds_read_b128 v[194:197], v160 offset:54272
	ds_read_b128 v[198:201], v160 offset:55296
	ds_read_b128 v[202:205], v160 offset:56320
	global_load_lds_dwordx4 v[174:175], off
	v_lshl_add_u64 v[174:175], v[226:227], 0, s[0:1]
	s_mov_b32 m0, s36
	s_nop 0
	global_load_lds_dwordx4 v[174:175], off
	s_barrier
	s_waitcnt lgkmcnt(0)
	s_waitcnt lgkmcnt(0)
	v_mfma_f32_16x16x32_bf16 v[60:63], v[144:147], v[166:169], v[60:63]
	v_mfma_f32_16x16x32_bf16 v[56:59], v[152:155], v[166:169], v[56:59]
	v_mfma_f32_16x16x32_bf16 v[48:51], v[144:147], v[182:185], v[48:51]
	v_mfma_f32_16x16x32_bf16 v[40:43], v[152:155], v[182:185], v[40:43]
	v_mfma_f32_16x16x32_bf16 v[32:35], v[144:147], v[190:193], v[32:35]
	v_mfma_f32_16x16x32_bf16 v[24:27], v[152:155], v[190:193], v[24:27]
	v_mfma_f32_16x16x32_bf16 v[16:19], v[144:147], v[198:201], v[16:19]
	v_mfma_f32_16x16x32_bf16 v[8:11], v[152:155], v[198:201], v[8:11]
	v_mfma_f32_16x16x32_bf16 v[60:63], v[148:151], v[170:173], v[60:63]
	v_mfma_f32_16x16x32_bf16 v[56:59], v[162:165], v[170:173], v[56:59]
	v_mfma_f32_16x16x32_bf16 v[48:51], v[148:151], v[186:189], v[48:51]
	v_mfma_f32_16x16x32_bf16 v[40:43], v[162:165], v[186:189], v[40:43]
	v_mfma_f32_16x16x32_bf16 v[32:35], v[148:151], v[194:197], v[32:35]
	v_mfma_f32_16x16x32_bf16 v[24:27], v[162:165], v[194:197], v[24:27]
	v_mfma_f32_16x16x32_bf16 v[16:19], v[148:151], v[202:205], v[16:19]
	v_mfma_f32_16x16x32_bf16 v[8:11], v[162:165], v[202:205], v[8:11]
	s_barrier
	s_add_u32 s10, s14, 0x160080
	s_addc_u32 s11, s15, 0
	s_add_i32 s14, s16, s19
	v_lshl_add_u64 v[144:145], s[10:11], 0, v[132:133]
	s_mov_b32 m0, s14
	s_nop 0
	global_load_lds_dwordx4 v[144:145], off
	v_lshl_add_u64 v[144:145], s[10:11], 0, v[128:129]
	s_add_i32 m0, s14, 0x2000
	s_nop 0
	global_load_lds_dwordx4 v[144:145], off
	s_waitcnt vmcnt(6)
	s_barrier
	v_mfma_f32_16x16x32_bf16 v[52:55], v[206:209], v[166:169], v[52:55]
	v_mfma_f32_16x16x32_bf16 v[44:47], v[214:217], v[166:169], v[44:47]
	v_mfma_f32_16x16x32_bf16 v[36:39], v[206:209], v[182:185], v[36:39]
	v_mfma_f32_16x16x32_bf16 v[28:31], v[214:217], v[182:185], v[28:31]
	v_mfma_f32_16x16x32_bf16 v[20:23], v[206:209], v[190:193], v[20:23]
	v_mfma_f32_16x16x32_bf16 v[12:15], v[214:217], v[190:193], v[12:15]
	v_mfma_f32_16x16x32_bf16 v[4:7], v[206:209], v[198:201], v[4:7]
	v_mfma_f32_16x16x32_bf16 v[0:3], v[214:217], v[198:201], v[0:3]
	v_mfma_f32_16x16x32_bf16 v[52:55], v[210:213], v[170:173], v[52:55]
	v_mfma_f32_16x16x32_bf16 v[44:47], v[218:221], v[170:173], v[44:47]
	v_mfma_f32_16x16x32_bf16 v[36:39], v[210:213], v[186:189], v[36:39]
	v_mfma_f32_16x16x32_bf16 v[28:31], v[218:221], v[186:189], v[28:31]
	v_mfma_f32_16x16x32_bf16 v[20:23], v[210:213], v[194:197], v[20:23]
	v_mfma_f32_16x16x32_bf16 v[12:15], v[218:221], v[194:197], v[12:15]
	v_mfma_f32_16x16x32_bf16 v[4:7], v[210:213], v[202:205], v[4:7]
	v_mfma_f32_16x16x32_bf16 v[0:3], v[218:221], v[202:205], v[0:3]
	s_add_i32 s47, s47, 2
	s_add_u32 s45, s45, 0x100
	s_addc_u32 s46, s46, 0
	s_cmp_gt_i32 s47, s98
	s_mov_b64 s[10:11], s[12:13]
	s_barrier
	s_cbranch_scc0 .LBB0_1081
	v_lshl_add_u32 v146, s42, 8, v156
	v_lshl_or_b32 v144, s44, 8, v158
	v_ashrrev_i32_e32 v145, 31, v144
	v_or_b32_e32 v152, 16, v146
	v_or_b32_e32 v150, 32, v146
	v_or_b32_e32 v148, 48, v146
	s_cmp_eq_u32 s43, 0
	v_ashrrev_i32_e32 v147, 31, v146
	v_lshlrev_b64 v[144:145], 2, v[144:145]
	v_ashrrev_i32_e32 v153, 31, v152
	v_ashrrev_i32_e32 v151, 31, v150
	v_ashrrev_i32_e32 v149, 31, v148
	s_cbranch_scc1 .LBB0_1084
	v_lshlrev_b64 v[154:155], 13, v[146:147]
	v_lshl_add_u64 v[154:155], s[30:31], 0, v[154:155]
	v_lshl_add_u64 v[162:163], v[154:155], 0, v[144:145]
	v_lshlrev_b64 v[154:155], 13, v[152:153]
	v_lshl_add_u64 v[154:155], s[30:31], 0, v[154:155]
	v_lshl_add_u64 v[154:155], v[154:155], 0, v[144:145]
	global_store_dwordx4 v[162:163], v[124:127], off
	global_store_dwordx4 v[162:163], v[120:123], off offset:16
	global_store_dwordx4 v[162:163], v[116:119], off offset:512
	global_store_dwordx4 v[162:163], v[108:111], off offset:528
	global_store_dwordx4 v[154:155], v[112:115], off
	global_store_dwordx4 v[154:155], v[104:107], off offset:16
	global_store_dwordx4 v[154:155], v[100:103], off offset:512
	global_store_dwordx4 v[154:155], v[92:95], off offset:528
	v_lshlrev_b64 v[154:155], 13, v[150:151]
	v_lshl_add_u64 v[154:155], s[30:31], 0, v[154:155]
	v_lshl_add_u64 v[154:155], v[154:155], 0, v[144:145]
	global_store_dwordx4 v[154:155], v[96:99], off
	global_store_dwordx4 v[154:155], v[88:91], off offset:16
	global_store_dwordx4 v[154:155], v[84:87], off offset:512
	global_store_dwordx4 v[154:155], v[76:79], off offset:528
	v_lshlrev_b64 v[154:155], 13, v[148:149]
	v_lshl_add_u64 v[154:155], s[30:31], 0, v[154:155]
	v_lshl_add_u64 v[154:155], v[154:155], 0, v[144:145]
	s_mov_b64 s[10:11], 0x100000
	global_store_dwordx4 v[154:155], v[80:83], off
	global_store_dwordx4 v[154:155], v[72:75], off offset:16
	global_store_dwordx4 v[154:155], v[68:71], off offset:512
	global_store_dwordx4 v[154:155], v[64:67], off offset:528
	v_lshl_add_u64 v[154:155], v[162:163], 0, s[10:11]
	s_mov_b32 s10, 0x100000
	v_add_co_u32_e32 v164, vcc, s10, v162
	s_mov_b64 s[10:11], 0x120000
	s_nop 0
	v_addc_co_u32_e32 v165, vcc, 0, v163, vcc
	global_store_dwordx4 v[164:165], v[60:63], off
	global_store_dwordx4 v[154:155], v[56:59], off offset:16
	global_store_dwordx4 v[154:155], v[52:55], off offset:512
	global_store_dwordx4 v[154:155], v[44:47], off offset:528
	v_lshl_add_u64 v[154:155], v[162:163], 0, s[10:11]
	s_mov_b32 s10, 0x120000
	v_add_co_u32_e32 v164, vcc, s10, v162
	s_mov_b64 s[10:11], 0x140000
	s_nop 0
	v_addc_co_u32_e32 v165, vcc, 0, v163, vcc
	global_store_dwordx4 v[164:165], v[48:51], off
	global_store_dwordx4 v[154:155], v[40:43], off offset:16
	global_store_dwordx4 v[154:155], v[36:39], off offset:512
	global_store_dwordx4 v[154:155], v[28:31], off offset:528
	v_add_co_u32_e32 v164, vcc, 0x140000, v162
	v_lshl_add_u64 v[154:155], v[162:163], 0, s[10:11]
	s_nop 0
	v_addc_co_u32_e32 v165, vcc, 0, v163, vcc
	s_mov_b64 s[10:11], 0x160000
	global_store_dwordx4 v[164:165], v[32:35], off
	global_store_dwordx4 v[154:155], v[24:27], off offset:16
	global_store_dwordx4 v[154:155], v[20:23], off offset:512
	global_store_dwordx4 v[154:155], v[12:15], off offset:528
	v_lshl_add_u64 v[154:155], v[162:163], 0, s[10:11]
	v_add_co_u32_e32 v162, vcc, 0x160000, v162
	s_nop 1
	v_addc_co_u32_e32 v163, vcc, 0, v163, vcc
	global_store_dwordx4 v[162:163], v[16:19], off
	global_store_dwordx4 v[154:155], v[8:11], off offset:16
	s_cbranch_execnz .LBB0_1073
	s_branch .LBB0_1085

.LBB0_1086:
	s_waitcnt vmcnt(0)
	s_setprio 0
	s_cmpk_gt_u32 s18, 0xff
	s_cbranch_scc1 .LBB0_1088
	s_barrier
